# EpiRes epilogues P6 P10: 8 loads per row group hoisted, one wait per group; plus transposes and attention rewrite
# speedup vs baseline: 1.0386x; 1.0185x over previous
; template <int MAPID> __device__ __forceinline__ void transpose_item(const float* __restrict__ W, int K, int Nsrc, bf16_t* __restrict__ WT, int nblk, float* scr, int item, int lane) {
;     const int kb = item / nblk, nb = item % nblk, k0 = 64 * kb, n0 = 32 * nb;
;     const int srcc = colmap<MAPID>(n0 + (lane & 31));
; #pragma unroll 8
;     for (int i = 0; i < 32; ++i) { const int kk = 2 * i + (lane >> 5); scr[kk * 33 + (lane & 31)] = srcc >= 0 ? __builtin_nontemporal_load(W + (size_t)(k0 + kk) * Nsrc + srcc) : 0.f; }
.LBB0_239:
	s_ashr_i32 s0, s5, 31
	s_lshr_b32 s0, s0, 26
	s_add_i32 s0, s5, s0
	s_and_b32 s2, s0, 0xffffffc0
	s_sub_i32 s0, s5, s2
	s_lshl_b32 s7, s0, 5
	s_cmp_gt_i32 s0, -1
	s_cselect_b64 s[0:1], -1, 0
	v_or_b32_e32 v0, s7, v6
	v_cndmask_b32_e64 v14, 0, 1, s[0:1]
	s_waitcnt lgkmcnt(0)
	v_lshl_add_u64 v[4:5], v[0:1], 2, s[82:83]
	v_or_b32_e32 v0, s2, v7
	v_cmp_ne_u32_e64 s[0:1], 1, v14
	v_mov_b32_e32 v14, v13
	s_mov_b32 s3, 0
	v_mov_b32_e32 v16, v0
	v_mov_b32_e32 v17, 0
	v_lshlrev_b64 v[16:17], 13, v[16:17]
	v_lshl_add_u64 v[36:37], v[4:5], 0, v[16:17]
	s_mov_b64 s[100:101], 0
	v_mov_b32_e32 v44, 0
	v_mov_b32_e32 v45, 0
	v_mov_b32_e32 v46, 0
	v_mov_b32_e32 v47, 0
	v_mov_b32_e32 v48, 0
	v_mov_b32_e32 v49, 0
	v_mov_b32_e32 v50, 0
	v_mov_b32_e32 v51, 0
	v_mov_b32_e32 v52, 0
	v_mov_b32_e32 v53, 0
	v_mov_b32_e32 v54, 0
	v_mov_b32_e32 v55, 0
	v_mov_b32_e32 v56, 0
	v_mov_b32_e32 v57, 0
	v_mov_b32_e32 v58, 0
	v_mov_b32_e32 v59, 0
	v_mov_b32_e32 v60, 0
	v_mov_b32_e32 v61, 0
	v_mov_b32_e32 v62, 0
	v_mov_b32_e32 v63, 0
	v_mov_b32_e32 v64, 0
	v_mov_b32_e32 v65, 0
	v_mov_b32_e32 v66, 0
	v_mov_b32_e32 v67, 0
	v_mov_b32_e32 v68, 0
	v_mov_b32_e32 v69, 0
	v_mov_b32_e32 v70, 0
	v_mov_b32_e32 v71, 0
	v_mov_b32_e32 v72, 0
	v_mov_b32_e32 v73, 0
	v_mov_b32_e32 v74, 0
	v_mov_b32_e32 v75, 0
	s_and_b64 vcc, exec, s[0:1]
	s_cbranch_vccnz .Ltr_b_skip
	v_lshl_add_u64 v[38:39], v[36:37], 0, s[100:101]
	global_load_dword v44, v[38:39], off nt
	s_add_u32 s100, s100, 0x4000
	s_addc_u32 s101, s101, 0
	v_lshl_add_u64 v[38:39], v[36:37], 0, s[100:101]
	global_load_dword v45, v[38:39], off nt
	s_add_u32 s100, s100, 0x4000
	s_addc_u32 s101, s101, 0
	v_lshl_add_u64 v[38:39], v[36:37], 0, s[100:101]
	global_load_dword v46, v[38:39], off nt
	s_add_u32 s100, s100, 0x4000
	s_addc_u32 s101, s101, 0
	v_lshl_add_u64 v[38:39], v[36:37], 0, s[100:101]
	global_load_dword v47, v[38:39], off nt
	s_add_u32 s100, s100, 0x4000
	s_addc_u32 s101, s101, 0
	v_lshl_add_u64 v[38:39], v[36:37], 0, s[100:101]
	global_load_dword v48, v[38:39], off nt
	s_add_u32 s100, s100, 0x4000
	s_addc_u32 s101, s101, 0
	v_lshl_add_u64 v[38:39], v[36:37], 0, s[100:101]
	global_load_dword v49, v[38:39], off nt
	s_add_u32 s100, s100, 0x4000
	s_addc_u32 s101, s101, 0
	v_lshl_add_u64 v[38:39], v[36:37], 0, s[100:101]
	global_load_dword v50, v[38:39], off nt
	s_add_u32 s100, s100, 0x4000
	s_addc_u32 s101, s101, 0
	v_lshl_add_u64 v[38:39], v[36:37], 0, s[100:101]
	global_load_dword v51, v[38:39], off nt
	s_add_u32 s100, s100, 0x4000
	s_addc_u32 s101, s101, 0
	v_lshl_add_u64 v[38:39], v[36:37], 0, s[100:101]
	global_load_dword v52, v[38:39], off nt
	s_add_u32 s100, s100, 0x4000
	s_addc_u32 s101, s101, 0
	v_lshl_add_u64 v[38:39], v[36:37], 0, s[100:101]
	global_load_dword v53, v[38:39], off nt
	s_add_u32 s100, s100, 0x4000
	s_addc_u32 s101, s101, 0
	v_lshl_add_u64 v[38:39], v[36:37], 0, s[100:101]
	global_load_dword v54, v[38:39], off nt
	s_add_u32 s100, s100, 0x4000
	s_addc_u32 s101, s101, 0
	v_lshl_add_u64 v[38:39], v[36:37], 0, s[100:101]
	global_load_dword v55, v[38:39], off nt
	s_add_u32 s100, s100, 0x4000
	s_addc_u32 s101, s101, 0
	v_lshl_add_u64 v[38:39], v[36:37], 0, s[100:101]
	global_load_dword v56, v[38:39], off nt
	s_add_u32 s100, s100, 0x4000
	s_addc_u32 s101, s101, 0
	v_lshl_add_u64 v[38:39], v[36:37], 0, s[100:101]
	global_load_dword v57, v[38:39], off nt
	s_add_u32 s100, s100, 0x4000
	s_addc_u32 s101, s101, 0
	v_lshl_add_u64 v[38:39], v[36:37], 0, s[100:101]
	global_load_dword v58, v[38:39], off nt
	s_add_u32 s100, s100, 0x4000
	s_addc_u32 s101, s101, 0
	v_lshl_add_u64 v[38:39], v[36:37], 0, s[100:101]
	global_load_dword v59, v[38:39], off nt
	s_add_u32 s100, s100, 0x4000
	s_addc_u32 s101, s101, 0
	v_lshl_add_u64 v[38:39], v[36:37], 0, s[100:101]
	global_load_dword v60, v[38:39], off nt
	s_add_u32 s100, s100, 0x4000
	s_addc_u32 s101, s101, 0
	v_lshl_add_u64 v[38:39], v[36:37], 0, s[100:101]
	global_load_dword v61, v[38:39], off nt
	s_add_u32 s100, s100, 0x4000
	s_addc_u32 s101, s101, 0
	v_lshl_add_u64 v[38:39], v[36:37], 0, s[100:101]
	global_load_dword v62, v[38:39], off nt
	s_add_u32 s100, s100, 0x4000
	s_addc_u32 s101, s101, 0
	v_lshl_add_u64 v[38:39], v[36:37], 0, s[100:101]
	global_load_dword v63, v[38:39], off nt
	s_add_u32 s100, s100, 0x4000
	s_addc_u32 s101, s101, 0
	v_lshl_add_u64 v[38:39], v[36:37], 0, s[100:101]
	global_load_dword v64, v[38:39], off nt
	s_add_u32 s100, s100, 0x4000
	s_addc_u32 s101, s101, 0
	v_lshl_add_u64 v[38:39], v[36:37], 0, s[100:101]
	global_load_dword v65, v[38:39], off nt
	s_add_u32 s100, s100, 0x4000
	s_addc_u32 s101, s101, 0
	v_lshl_add_u64 v[38:39], v[36:37], 0, s[100:101]
	global_load_dword v66, v[38:39], off nt
	s_add_u32 s100, s100, 0x4000
	s_addc_u32 s101, s101, 0
	v_lshl_add_u64 v[38:39], v[36:37], 0, s[100:101]
	global_load_dword v67, v[38:39], off nt
	s_add_u32 s100, s100, 0x4000
	s_addc_u32 s101, s101, 0
	v_lshl_add_u64 v[38:39], v[36:37], 0, s[100:101]
	global_load_dword v68, v[38:39], off nt
	s_add_u32 s100, s100, 0x4000
	s_addc_u32 s101, s101, 0
	v_lshl_add_u64 v[38:39], v[36:37], 0, s[100:101]
	global_load_dword v69, v[38:39], off nt
	s_add_u32 s100, s100, 0x4000
	s_addc_u32 s101, s101, 0
	v_lshl_add_u64 v[38:39], v[36:37], 0, s[100:101]
	global_load_dword v70, v[38:39], off nt
	s_add_u32 s100, s100, 0x4000
	s_addc_u32 s101, s101, 0
	v_lshl_add_u64 v[38:39], v[36:37], 0, s[100:101]
	global_load_dword v71, v[38:39], off nt
	s_add_u32 s100, s100, 0x4000
	s_addc_u32 s101, s101, 0
	v_lshl_add_u64 v[38:39], v[36:37], 0, s[100:101]
	global_load_dword v72, v[38:39], off nt
	s_add_u32 s100, s100, 0x4000
	s_addc_u32 s101, s101, 0
	v_lshl_add_u64 v[38:39], v[36:37], 0, s[100:101]
	global_load_dword v73, v[38:39], off nt
	s_add_u32 s100, s100, 0x4000
	s_addc_u32 s101, s101, 0
	v_lshl_add_u64 v[38:39], v[36:37], 0, s[100:101]
	global_load_dword v74, v[38:39], off nt
	s_add_u32 s100, s100, 0x4000
	s_addc_u32 s101, s101, 0
	v_lshl_add_u64 v[38:39], v[36:37], 0, s[100:101]
	global_load_dword v75, v[38:39], off nt
	s_add_u32 s100, s100, 0x4000
	s_addc_u32 s101, s101, 0

; __device__ __forceinline__ void unpack8(u32x4 w, float* v) { v[0] = bflo(w.x); v[1] = bfhi(w.x); v[2] = bflo(w.y); v[3] = bfhi(w.y); v[4] = bflo(w.z); v[5] = bfhi(w.z); v[6] = bflo(w.w); v[7] = bfhi(w.w); }
; __device__ __forceinline__ void attn_phase(const Args& a, unsigned char* lds, int lane, int wave) {
;     ...
;         const bool sample = t >= TP; const int bb = sample ? (t - TP) >> 6 : 0;
;         const int c = t >> 6; const int L = sample ? 1088 : 64 * (c + 1);
;         const int nsel = min(256, L);
;         const unsigned* cand = CAND + (size_t)t * 256;
; #pragma unroll
;         for (int j = 0; j < 4; ++j) { const int i = j * 64 + lane; if (i < nsel) sel[i] = cand[i] & 0x3FFFu; }
;         bf16_t* qp = P + (size_t)t * NP + lane * 16;
;         float q[16]; unpack8(*(const u32x4*)qp, q); unpack8(*(const u32x4*)(qp + 8), q + 8);
;         float mx = -INFINITY, l = 0.f, o[16];
; #pragma unroll
;         for (int d = 0; d < 16; ++d) o[d] = 0.f;
;         for (int j = 0; j < nsel; j += 8) {
;             const u32x4 ida = *(const u32x4*)(sel + j), idb = *(const u32x4*)(sel + j + 4);
;             u32x4 kk[8], vv[8];
; #pragma unroll
;             for (int i = 0; i < 8; ++i) { const int idx = (int)(i < 4 ? ida[i & 3] : idb[i & 3]); const unsigned char* kp;
;                 if (!sample) kp = KV8 + (size_t)idx * 2048;
;                 else if (idx < 1024) kp = CKV8 + (size_t)(bb * 1024 + idx) * 2048;
;                 else kp = KV8 + (size_t)(TP + bb * 64 + idx - 1024) * 2048;
;                 kk[i] = *(const u32x4*)(kp + lane * 16); vv[i] = *(const u32x4*)(kp + 1024 + lane * 16); }
.Lat_q:
	s_and_b32 s0, s2, 0xffffffc0
	s_add_i32 s0, s0, 64
	s_min_i32 s30, s0, 0x100
	s_lshl_b32 s8, s2, 10
	s_add_u32 s8, s26, s8
	s_addc_u32 s9, s27, 0
	global_load_dword v0, v99, s[8:9]
	global_load_dword v1, v99, s[8:9] offset:256
	global_load_dword v2, v99, s[8:9] offset:512
	global_load_dword v3, v99, s[8:9] offset:768
	v_mad_i64_i32 v[60:61], s[10:11], s2, v98, v[58:59]
	s_add_u32 s4, s62, 0x1be00000
	s_addc_u32 s5, s63, 0
	s_mov_b64 s[6:7], s[4:5]
	s_cmpk_gt_i32 s2, 0x3fff
	s_cbranch_scc0 .Lat_ns
	s_movk_i32 s30, 0x100
	s_add_i32 s8, s2, 0xffffc000
	s_and_b32 s9, s8, 0xffffffc0
	s_addk_i32 s9, 0x3c00
	s_lshl_b32 s9, s9, 11
	s_add_u32 s4, s4, s9
	s_addc_u32 s5, s5, 0
	s_lshl_b32 s8, s8, 4
	s_and_b32 s8, s8, 0xfffffc00
	s_lshl_b32 s8, s8, 11
	s_add_u32 s6, s62, 0x1df00000
	s_addc_u32 s7, s63, 0
	s_add_u32 s6, s6, s8
	s_addc_u32 s7, s7, 0
.Lat_ns:
	global_load_dwordx4 v[4:7], v[60:61], off
	global_load_dwordx4 v[8:11], v[60:61], off offset:16
	s_add_i32 s31, s29, -16
	s_lshr_b32 s3, s30, 4
	s_waitcnt vmcnt(2)
	v_and_b32_e32 v0, 0x3fff, v0
	v_and_b32_e32 v1, 0x3fff, v1
	v_and_b32_e32 v2, 0x3fff, v2
	v_and_b32_e32 v3, 0x3fff, v3
	ds_write_b32 v94, v0
	ds_write_b32 v94, v1 offset:256
	ds_write_b32 v94, v2 offset:512
	ds_write_b32 v94, v3 offset:768
	v_mov_b32_e32 v246, s31
	ds_read_b128 v[204:207], v246
	ds_read_b128 v[208:211], v246 offset:16
	ds_read_b128 v[212:215], v246 offset:32
	ds_read_b128 v[216:219], v246 offset:48
	v_mov_b32_e32 v62, 0
	v_mov_b32_e32 v63, 0
	v_mov_b32_e32 v64, 0
	v_mov_b32_e32 v65, 0
	v_mov_b32_e32 v66, 0
	v_mov_b32_e32 v67, 0
	v_mov_b32_e32 v68, 0
	v_mov_b32_e32 v69, 0
	v_mov_b32_e32 v70, 0
	v_mov_b32_e32 v71, 0
	v_mov_b32_e32 v72, 0
	v_mov_b32_e32 v73, 0
	v_mov_b32_e32 v74, 0
	v_mov_b32_e32 v75, 0
	v_mov_b32_e32 v76, 0
	v_mov_b32_e32 v77, 0
	v_mov_b32_e32 v108, 0
	v_mov_b32_e32 v109, 0xff800000
	s_waitcnt vmcnt(0)
	v_lshlrev_b32_e32 v78, 16, v4
	v_and_b32_e32 v79, 0xffff0000, v4
	v_lshlrev_b32_e32 v80, 16, v5
	v_and_b32_e32 v81, 0xffff0000, v5
	v_lshlrev_b32_e32 v82, 16, v6
	v_and_b32_e32 v83, 0xffff0000, v6
	v_lshlrev_b32_e32 v84, 16, v7
	v_and_b32_e32 v85, 0xffff0000, v7
	v_lshlrev_b32_e32 v86, 16, v8
	v_and_b32_e32 v87, 0xffff0000, v8
	v_lshlrev_b32_e32 v88, 16, v9
	v_and_b32_e32 v89, 0xffff0000, v9
	v_lshlrev_b32_e32 v90, 16, v10
	v_and_b32_e32 v91, 0xffff0000, v10
	v_lshlrev_b32_e32 v92, 16, v11
	v_and_b32_e32 v93, 0xffff0000, v11
	s_waitcnt lgkmcnt(0)
	v_readfirstlane_b32 s8, v204
	v_readfirstlane_b32 s9, v205
	v_readfirstlane_b32 s10, v206
	v_readfirstlane_b32 s11, v207
	v_readfirstlane_b32 s12, v208
	v_readfirstlane_b32 s13, v209
	v_readfirstlane_b32 s14, v210
	v_readfirstlane_b32 s15, v211
	v_readfirstlane_b32 s16, v212
	v_readfirstlane_b32 s17, v213
	v_readfirstlane_b32 s18, v214
	v_readfirstlane_b32 s19, v215
	v_readfirstlane_b32 s20, v216
	v_readfirstlane_b32 s21, v217
	v_readfirstlane_b32 s22, v218
	v_readfirstlane_b32 s23, v219
	s_cmp_lt_u32 s8, 0x400
	s_cselect_b32 s24, s6, s4
	s_cselect_b32 s25, s7, s5
	s_lshl_b32 s8, s8, 11
	s_add_u32 s24, s24, s8
	s_addc_u32 s25, s25, 0
	global_load_dwordx4 v[132:135], v56, s[24:25]
	s_cmp_lt_u32 s9, 0x400
	s_cselect_b32 s24, s6, s4
	s_cselect_b32 s25, s7, s5
	s_lshl_b32 s9, s9, 11
	s_add_u32 s24, s24, s9
	s_addc_u32 s25, s25, 0
	global_load_dwordx4 v[136:139], v56, s[24:25]
	s_cmp_lt_u32 s10, 0x400
	s_cselect_b32 s24, s6, s4
	s_cselect_b32 s25, s7, s5
	s_lshl_b32 s10, s10, 11
	s_add_u32 s24, s24, s10
	s_addc_u32 s25, s25, 0
	global_load_dwordx4 v[140:143], v56, s[24:25]
	s_cmp_lt_u32 s11, 0x400
	s_cselect_b32 s24, s6, s4
	s_cselect_b32 s25, s7, s5
	s_lshl_b32 s11, s11, 11
	s_add_u32 s24, s24, s11
	s_addc_u32 s25, s25, 0
	global_load_dwordx4 v[144:147], v56, s[24:25]
	s_cmp_lt_u32 s12, 0x400
	s_cselect_b32 s24, s6, s4
	s_cselect_b32 s25, s7, s5
	s_lshl_b32 s12, s12, 11
	s_add_u32 s24, s24, s12
	s_addc_u32 s25, s25, 0
	global_load_dwordx4 v[148:151], v56, s[24:25]
	s_cmp_lt_u32 s13, 0x400
	s_cselect_b32 s24, s6, s4
	s_cselect_b32 s25, s7, s5
	s_lshl_b32 s13, s13, 11
	s_add_u32 s24, s24, s13
	s_addc_u32 s25, s25, 0
	global_load_dwordx4 v[152:155], v56, s[24:25]
	s_cmp_lt_u32 s14, 0x400
	s_cselect_b32 s24, s6, s4
	s_cselect_b32 s25, s7, s5
	s_lshl_b32 s14, s14, 11
	s_add_u32 s24, s24, s14
	s_addc_u32 s25, s25, 0
	global_load_dwordx4 v[156:159], v56, s[24:25]
	s_cmp_lt_u32 s15, 0x400
	s_cselect_b32 s24, s6, s4
	s_cselect_b32 s25, s7, s5
	s_lshl_b32 s15, s15, 11
	s_add_u32 s24, s24, s15
	s_addc_u32 s25, s25, 0
	global_load_dwordx4 v[160:163], v56, s[24:25]
	s_cmp_lt_u32 s16, 0x400
	s_cselect_b32 s24, s6, s4
	s_cselect_b32 s25, s7, s5
	s_lshl_b32 s16, s16, 11
	s_add_u32 s24, s24, s16
	s_addc_u32 s25, s25, 0
	global_load_dwordx4 v[164:167], v56, s[24:25]
	s_cmp_lt_u32 s17, 0x400
	s_cselect_b32 s24, s6, s4
	s_cselect_b32 s25, s7, s5
	s_lshl_b32 s17, s17, 11
	s_add_u32 s24, s24, s17
	s_addc_u32 s25, s25, 0
	global_load_dwordx4 v[168:171], v56, s[24:25]
	s_cmp_lt_u32 s18, 0x400
	s_cselect_b32 s24, s6, s4
	s_cselect_b32 s25, s7, s5
	s_lshl_b32 s18, s18, 11
	s_add_u32 s24, s24, s18
	s_addc_u32 s25, s25, 0
	global_load_dwordx4 v[172:175], v56, s[24:25]
	s_cmp_lt_u32 s19, 0x400
	s_cselect_b32 s24, s6, s4
	s_cselect_b32 s25, s7, s5
	s_lshl_b32 s19, s19, 11
	s_add_u32 s24, s24, s19
	s_addc_u32 s25, s25, 0
	global_load_dwordx4 v[176:179], v56, s[24:25]
	s_cmp_lt_u32 s20, 0x400
	s_cselect_b32 s24, s6, s4
	s_cselect_b32 s25, s7, s5
	s_lshl_b32 s20, s20, 11
	s_add_u32 s24, s24, s20
	s_addc_u32 s25, s25, 0
	global_load_dwordx4 v[180:183], v56, s[24:25]
	s_cmp_lt_u32 s21, 0x400
	s_cselect_b32 s24, s6, s4
	s_cselect_b32 s25, s7, s5
	s_lshl_b32 s21, s21, 11
	s_add_u32 s24, s24, s21
; __device__ __forceinline__ void attn_phase(const Args& a, unsigned char* lds, int lane, int wave) {
;     ...
;             for (int i = 0; i < 8; ++i) { const int idx = (int)(i < 4 ? ida[i & 3] : idb[i & 3]); const unsigned char* kp;
;                 if (!sample) kp = KV8 + (size_t)idx * 2048;
;                 else if (idx < 1024) kp = CKV8 + (size_t)(bb * 1024 + idx) * 2048;
;                 else kp = KV8 + (size_t)(TP + bb * 64 + idx - 1024) * 2048;
;                 kk[i] = *(const u32x4*)(kp + lane * 16); vv[i] = *(const u32x4*)(kp + 1024 + lane * 16); }
;             float s[8];
; #pragma unroll
;             for (int i = 0; i < 8; ++i) { float kf[16]; unpack16_fp8(kk[i], kf); float d0 = 0.f, d1 = 0.f;
; #pragma unroll
;                 for (int x = 0; x < 16; x += 2) { d0 += q[x] * kf[x]; d1 += q[x + 1] * kf[x + 1]; }
	s_addc_u32 s25, s25, 0
	global_load_dwordx4 v[184:187], v56, s[24:25]
	s_cmp_lt_u32 s22, 0x400
	s_cselect_b32 s24, s6, s4
	s_cselect_b32 s25, s7, s5
	s_lshl_b32 s22, s22, 11
	s_add_u32 s24, s24, s22
	s_addc_u32 s25, s25, 0
	global_load_dwordx4 v[188:191], v56, s[24:25]
	s_cmp_lt_u32 s23, 0x400
	s_cselect_b32 s24, s6, s4
	s_cselect_b32 s25, s7, s5
	s_lshl_b32 s23, s23, 11
	s_add_u32 s24, s24, s23
	s_addc_u32 s25, s25, 0
	global_load_dwordx4 v[192:195], v56, s[24:25]
	s_cmp_lt_u32 s8, 0x200000
	s_cselect_b32 s24, s6, s4
	s_cselect_b32 s25, s7, s5
	s_add_u32 s24, s24, s8
	s_addc_u32 s25, s25, 0
	global_load_dwordx4 v[0:3], v56, s[24:25] offset:1024
	s_cmp_lt_u32 s9, 0x200000
	s_cselect_b32 s24, s6, s4
	s_cselect_b32 s25, s7, s5
	s_add_u32 s24, s24, s9
	s_addc_u32 s25, s25, 0
	global_load_dwordx4 v[4:7], v56, s[24:25] offset:1024
	s_cmp_lt_u32 s10, 0x200000
	s_cselect_b32 s24, s6, s4
	s_cselect_b32 s25, s7, s5
	s_add_u32 s24, s24, s10
	s_addc_u32 s25, s25, 0
	global_load_dwordx4 v[8:11], v56, s[24:25] offset:1024
	s_cmp_lt_u32 s11, 0x200000
	s_cselect_b32 s24, s6, s4
	s_cselect_b32 s25, s7, s5
	s_add_u32 s24, s24, s11
	s_addc_u32 s25, s25, 0
	global_load_dwordx4 v[12:15], v56, s[24:25] offset:1024
	s_cmp_lt_u32 s12, 0x200000
	s_cselect_b32 s24, s6, s4
	s_cselect_b32 s25, s7, s5
	s_add_u32 s24, s24, s12
	s_addc_u32 s25, s25, 0
	global_load_dwordx4 v[16:19], v56, s[24:25] offset:1024
	s_cmp_lt_u32 s13, 0x200000
	s_cselect_b32 s24, s6, s4
	s_cselect_b32 s25, s7, s5
	s_add_u32 s24, s24, s13
	s_addc_u32 s25, s25, 0
	global_load_dwordx4 v[20:23], v56, s[24:25] offset:1024
	s_cmp_lt_u32 s14, 0x200000
	s_cselect_b32 s24, s6, s4
	s_cselect_b32 s25, s7, s5
	s_add_u32 s24, s24, s14
	s_addc_u32 s25, s25, 0
	global_load_dwordx4 v[24:27], v56, s[24:25] offset:1024
	s_cmp_lt_u32 s15, 0x200000
	s_cselect_b32 s24, s6, s4
	s_cselect_b32 s25, s7, s5
	s_add_u32 s24, s24, s15
	s_addc_u32 s25, s25, 0
	global_load_dwordx4 v[28:31], v56, s[24:25] offset:1024
	s_cmp_lt_u32 s16, 0x200000
	s_cselect_b32 s24, s6, s4
	s_cselect_b32 s25, s7, s5
	s_add_u32 s24, s24, s16
	s_addc_u32 s25, s25, 0
	global_load_dwordx4 v[32:35], v56, s[24:25] offset:1024
	s_cmp_lt_u32 s17, 0x200000
	s_cselect_b32 s24, s6, s4
	s_cselect_b32 s25, s7, s5
	s_add_u32 s24, s24, s17
	s_addc_u32 s25, s25, 0
	global_load_dwordx4 v[36:39], v56, s[24:25] offset:1024
	s_cmp_lt_u32 s18, 0x200000
	s_cselect_b32 s24, s6, s4
	s_cselect_b32 s25, s7, s5
	s_add_u32 s24, s24, s18
	s_addc_u32 s25, s25, 0
	global_load_dwordx4 v[40:43], v56, s[24:25] offset:1024
	s_cmp_lt_u32 s19, 0x200000
	s_cselect_b32 s24, s6, s4
	s_cselect_b32 s25, s7, s5
	s_add_u32 s24, s24, s19
	s_addc_u32 s25, s25, 0
	global_load_dwordx4 v[44:47], v56, s[24:25] offset:1024
	s_cmp_lt_u32 s20, 0x200000
	s_cselect_b32 s24, s6, s4
	s_cselect_b32 s25, s7, s5
	s_add_u32 s24, s24, s20
	s_addc_u32 s25, s25, 0
	global_load_dwordx4 v[48:51], v56, s[24:25] offset:1024
	s_cmp_lt_u32 s21, 0x200000
	s_cselect_b32 s24, s6, s4
	s_cselect_b32 s25, s7, s5
	s_add_u32 s24, s24, s21
	s_addc_u32 s25, s25, 0
	global_load_dwordx4 v[52:55], v56, s[24:25] offset:1024
	s_cmp_lt_u32 s22, 0x200000
	s_cselect_b32 s24, s6, s4
	s_cselect_b32 s25, s7, s5
	s_add_u32 s24, s24, s22
	s_addc_u32 s25, s25, 0
	global_load_dwordx4 v[196:199], v56, s[24:25] offset:1024
	s_cmp_lt_u32 s23, 0x200000
	s_cselect_b32 s24, s6, s4
	s_cselect_b32 s25, s7, s5
	s_add_u32 s24, s24, s23
	s_addc_u32 s25, s25, 0
	global_load_dwordx4 v[200:203], v56, s[24:25] offset:1024
	s_add_i32 s3, s3, -1
.Lat_blk:
	s_waitcnt vmcnt(30)
	v_cvt_pk_f32_fp8_e32 v[204:205], v132
	v_cvt_pk_f32_fp8_e32 v[206:207], v136
	v_pk_mul_f32 v[220:221], v[204:205], v[78:79]
	v_pk_mul_f32 v[222:223], v[206:207], v[78:79]
	v_cvt_pk_f32_fp8_sdwa v[208:209], v132 src0_sel:WORD_1
	v_cvt_pk_f32_fp8_sdwa v[210:211], v136 src0_sel:WORD_1
	v_pk_fma_f32 v[220:221], v[208:209], v[80:81], v[220:221]
	v_pk_fma_f32 v[222:223], v[210:211], v[80:81], v[222:223]
	v_cvt_pk_f32_fp8_e32 v[212:213], v133
	v_cvt_pk_f32_fp8_e32 v[214:215], v137
	v_pk_fma_f32 v[220:221], v[212:213], v[82:83], v[220:221]
	v_pk_fma_f32 v[222:223], v[214:215], v[82:83], v[222:223]
	v_cvt_pk_f32_fp8_sdwa v[216:217], v133 src0_sel:WORD_1
	v_cvt_pk_f32_fp8_sdwa v[218:219], v137 src0_sel:WORD_1
	v_pk_fma_f32 v[220:221], v[216:217], v[84:85], v[220:221]
	v_pk_fma_f32 v[222:223], v[218:219], v[84:85], v[222:223]
	v_cvt_pk_f32_fp8_e32 v[204:205], v134
	v_cvt_pk_f32_fp8_e32 v[206:207], v138
	v_pk_fma_f32 v[220:221], v[204:205], v[86:87], v[220:221]
	v_pk_fma_f32 v[222:223], v[206:207], v[86:87], v[222:223]
	v_cvt_pk_f32_fp8_sdwa v[208:209], v134 src0_sel:WORD_1
	v_cvt_pk_f32_fp8_sdwa v[210:211], v138 src0_sel:WORD_1
	v_pk_fma_f32 v[220:221], v[208:209], v[88:89], v[220:221]
	v_pk_fma_f32 v[222:223], v[210:211], v[88:89], v[222:223]
	v_cvt_pk_f32_fp8_e32 v[212:213], v135
	v_cvt_pk_f32_fp8_e32 v[214:215], v139
	v_pk_fma_f32 v[220:221], v[212:213], v[90:91], v[220:221]
	v_pk_fma_f32 v[222:223], v[214:215], v[90:91], v[222:223]
	v_cvt_pk_f32_fp8_sdwa v[216:217], v135 src0_sel:WORD_1
	v_cvt_pk_f32_fp8_sdwa v[218:219], v139 src0_sel:WORD_1
	v_pk_fma_f32 v[220:221], v[216:217], v[92:93], v[220:221]
	v_pk_fma_f32 v[222:223], v[218:219], v[92:93], v[222:223]
	s_waitcnt vmcnt(28)
; __device__ __forceinline__ void attn_phase(const Args& a, unsigned char* lds, int lane, int wave) {
;     ...
;             float s[8];
; #pragma unroll
;             for (int i = 0; i < 8; ++i) { float kf[16]; unpack16_fp8(kk[i], kf); float d0 = 0.f, d1 = 0.f;
; #pragma unroll
;                 for (int x = 0; x < 16; x += 2) { d0 += q[x] * kf[x]; d1 += q[x + 1] * kf[x + 1]; }
;                 float d = d0 + d1;
;                 d += __shfl_xor(d, 1); d += __shfl_xor(d, 2); d += __shfl_xor(d, 4); s[i] = d; }
	v_cvt_pk_f32_fp8_e32 v[204:205], v140
	v_cvt_pk_f32_fp8_e32 v[206:207], v144
	v_pk_mul_f32 v[224:225], v[204:205], v[78:79]
	v_pk_mul_f32 v[226:227], v[206:207], v[78:79]
	v_cvt_pk_f32_fp8_sdwa v[208:209], v140 src0_sel:WORD_1
	v_cvt_pk_f32_fp8_sdwa v[210:211], v144 src0_sel:WORD_1
	v_pk_fma_f32 v[224:225], v[208:209], v[80:81], v[224:225]
	v_pk_fma_f32 v[226:227], v[210:211], v[80:81], v[226:227]
	v_cvt_pk_f32_fp8_e32 v[212:213], v141
	v_cvt_pk_f32_fp8_e32 v[214:215], v145
	v_pk_fma_f32 v[224:225], v[212:213], v[82:83], v[224:225]
	v_pk_fma_f32 v[226:227], v[214:215], v[82:83], v[226:227]
	v_cvt_pk_f32_fp8_sdwa v[216:217], v141 src0_sel:WORD_1
	v_cvt_pk_f32_fp8_sdwa v[218:219], v145 src0_sel:WORD_1
	v_pk_fma_f32 v[224:225], v[216:217], v[84:85], v[224:225]
	v_pk_fma_f32 v[226:227], v[218:219], v[84:85], v[226:227]
	v_cvt_pk_f32_fp8_e32 v[204:205], v142
	v_cvt_pk_f32_fp8_e32 v[206:207], v146
	v_pk_fma_f32 v[224:225], v[204:205], v[86:87], v[224:225]
	v_pk_fma_f32 v[226:227], v[206:207], v[86:87], v[226:227]
	v_cvt_pk_f32_fp8_sdwa v[208:209], v142 src0_sel:WORD_1
	v_cvt_pk_f32_fp8_sdwa v[210:211], v146 src0_sel:WORD_1
	v_pk_fma_f32 v[224:225], v[208:209], v[88:89], v[224:225]
	v_pk_fma_f32 v[226:227], v[210:211], v[88:89], v[226:227]
	v_cvt_pk_f32_fp8_e32 v[212:213], v143
	v_cvt_pk_f32_fp8_e32 v[214:215], v147
	v_pk_fma_f32 v[224:225], v[212:213], v[90:91], v[224:225]
	v_pk_fma_f32 v[226:227], v[214:215], v[90:91], v[226:227]
	v_cvt_pk_f32_fp8_sdwa v[216:217], v143 src0_sel:WORD_1
	v_cvt_pk_f32_fp8_sdwa v[218:219], v147 src0_sel:WORD_1
	v_pk_fma_f32 v[224:225], v[216:217], v[92:93], v[224:225]
	v_pk_fma_f32 v[226:227], v[218:219], v[92:93], v[226:227]
	v_add_f32_e32 v110, v220, v221
	v_add_f32_e32 v111, v222, v223
	v_add_f32_e32 v112, v224, v225
	v_add_f32_e32 v113, v226, v227
	v_add_f32_dpp v110, v110, v110 quad_perm:[1,0,3,2] row_mask:0xf bank_mask:0xf
	v_add_f32_dpp v111, v111, v111 quad_perm:[1,0,3,2] row_mask:0xf bank_mask:0xf
	v_add_f32_dpp v112, v112, v112 quad_perm:[1,0,3,2] row_mask:0xf bank_mask:0xf
	v_add_f32_dpp v113, v113, v113 quad_perm:[1,0,3,2] row_mask:0xf bank_mask:0xf
	v_add_f32_dpp v110, v110, v110 quad_perm:[2,3,0,1] row_mask:0xf bank_mask:0xf
	v_add_f32_dpp v111, v111, v111 quad_perm:[2,3,0,1] row_mask:0xf bank_mask:0xf
	v_add_f32_dpp v112, v112, v112 quad_perm:[2,3,0,1] row_mask:0xf bank_mask:0xf
	v_add_f32_dpp v113, v113, v113 quad_perm:[2,3,0,1] row_mask:0xf bank_mask:0xf
	v_add_f32_dpp v110, v110, v110 row_half_mirror row_mask:0xf bank_mask:0xf
	v_add_f32_dpp v111, v111, v111 row_half_mirror row_mask:0xf bank_mask:0xf
	v_add_f32_dpp v112, v112, v112 row_half_mirror row_mask:0xf bank_mask:0xf
	v_add_f32_dpp v113, v113, v113 row_half_mirror row_mask:0xf bank_mask:0xf
	s_waitcnt vmcnt(26)
	v_cvt_pk_f32_fp8_e32 v[204:205], v148
	v_cvt_pk_f32_fp8_e32 v[206:207], v152
	v_pk_mul_f32 v[220:221], v[204:205], v[78:79]
	v_pk_mul_f32 v[222:223], v[206:207], v[78:79]
	v_cvt_pk_f32_fp8_sdwa v[208:209], v148 src0_sel:WORD_1
	v_cvt_pk_f32_fp8_sdwa v[210:211], v152 src0_sel:WORD_1
	v_pk_fma_f32 v[220:221], v[208:209], v[80:81], v[220:221]
	v_pk_fma_f32 v[222:223], v[210:211], v[80:81], v[222:223]
	v_cvt_pk_f32_fp8_e32 v[212:213], v149
	v_cvt_pk_f32_fp8_e32 v[214:215], v153
	v_pk_fma_f32 v[220:221], v[212:213], v[82:83], v[220:221]
	v_pk_fma_f32 v[222:223], v[214:215], v[82:83], v[222:223]
	v_cvt_pk_f32_fp8_sdwa v[216:217], v149 src0_sel:WORD_1
	v_cvt_pk_f32_fp8_sdwa v[218:219], v153 src0_sel:WORD_1
	v_pk_fma_f32 v[220:221], v[216:217], v[84:85], v[220:221]
	v_pk_fma_f32 v[222:223], v[218:219], v[84:85], v[222:223]
	v_cvt_pk_f32_fp8_e32 v[204:205], v150
	v_cvt_pk_f32_fp8_e32 v[206:207], v154
	v_pk_fma_f32 v[220:221], v[204:205], v[86:87], v[220:221]
	v_pk_fma_f32 v[222:223], v[206:207], v[86:87], v[222:223]
	v_cvt_pk_f32_fp8_sdwa v[208:209], v150 src0_sel:WORD_1
	v_cvt_pk_f32_fp8_sdwa v[210:211], v154 src0_sel:WORD_1
	v_pk_fma_f32 v[220:221], v[208:209], v[88:89], v[220:221]
	v_pk_fma_f32 v[222:223], v[210:211], v[88:89], v[222:223]
	v_cvt_pk_f32_fp8_e32 v[212:213], v151
	v_cvt_pk_f32_fp8_e32 v[214:215], v155
	v_pk_fma_f32 v[220:221], v[212:213], v[90:91], v[220:221]
	v_pk_fma_f32 v[222:223], v[214:215], v[90:91], v[222:223]
	v_cvt_pk_f32_fp8_sdwa v[216:217], v151 src0_sel:WORD_1
	v_cvt_pk_f32_fp8_sdwa v[218:219], v155 src0_sel:WORD_1
	v_pk_fma_f32 v[220:221], v[216:217], v[92:93], v[220:221]
	v_pk_fma_f32 v[222:223], v[218:219], v[92:93], v[222:223]
	s_waitcnt vmcnt(24)
; __device__ __forceinline__ void attn_phase(const Args& a, unsigned char* lds, int lane, int wave) {
;     ...
;             float s[8];
; #pragma unroll
;             for (int i = 0; i < 8; ++i) { float kf[16]; unpack16_fp8(kk[i], kf); float d0 = 0.f, d1 = 0.f;
; #pragma unroll
;                 for (int x = 0; x < 16; x += 2) { d0 += q[x] * kf[x]; d1 += q[x + 1] * kf[x + 1]; }
;                 float d = d0 + d1;
;                 d += __shfl_xor(d, 1); d += __shfl_xor(d, 2); d += __shfl_xor(d, 4); s[i] = d; }
	v_cvt_pk_f32_fp8_e32 v[204:205], v156
	v_cvt_pk_f32_fp8_e32 v[206:207], v160
	v_pk_mul_f32 v[224:225], v[204:205], v[78:79]
	v_pk_mul_f32 v[226:227], v[206:207], v[78:79]
	v_cvt_pk_f32_fp8_sdwa v[208:209], v156 src0_sel:WORD_1
	v_cvt_pk_f32_fp8_sdwa v[210:211], v160 src0_sel:WORD_1
	v_pk_fma_f32 v[224:225], v[208:209], v[80:81], v[224:225]
	v_pk_fma_f32 v[226:227], v[210:211], v[80:81], v[226:227]
	v_cvt_pk_f32_fp8_e32 v[212:213], v157
	v_cvt_pk_f32_fp8_e32 v[214:215], v161
	v_pk_fma_f32 v[224:225], v[212:213], v[82:83], v[224:225]
	v_pk_fma_f32 v[226:227], v[214:215], v[82:83], v[226:227]
	v_cvt_pk_f32_fp8_sdwa v[216:217], v157 src0_sel:WORD_1
	v_cvt_pk_f32_fp8_sdwa v[218:219], v161 src0_sel:WORD_1
	v_pk_fma_f32 v[224:225], v[216:217], v[84:85], v[224:225]
	v_pk_fma_f32 v[226:227], v[218:219], v[84:85], v[226:227]
	v_cvt_pk_f32_fp8_e32 v[204:205], v158
	v_cvt_pk_f32_fp8_e32 v[206:207], v162
	v_pk_fma_f32 v[224:225], v[204:205], v[86:87], v[224:225]
	v_pk_fma_f32 v[226:227], v[206:207], v[86:87], v[226:227]
	v_cvt_pk_f32_fp8_sdwa v[208:209], v158 src0_sel:WORD_1
	v_cvt_pk_f32_fp8_sdwa v[210:211], v162 src0_sel:WORD_1
	v_pk_fma_f32 v[224:225], v[208:209], v[88:89], v[224:225]
	v_pk_fma_f32 v[226:227], v[210:211], v[88:89], v[226:227]
	v_cvt_pk_f32_fp8_e32 v[212:213], v159
	v_cvt_pk_f32_fp8_e32 v[214:215], v163
	v_pk_fma_f32 v[224:225], v[212:213], v[90:91], v[224:225]
	v_pk_fma_f32 v[226:227], v[214:215], v[90:91], v[226:227]
	v_cvt_pk_f32_fp8_sdwa v[216:217], v159 src0_sel:WORD_1
	v_cvt_pk_f32_fp8_sdwa v[218:219], v163 src0_sel:WORD_1
	v_pk_fma_f32 v[224:225], v[216:217], v[92:93], v[224:225]
	v_pk_fma_f32 v[226:227], v[218:219], v[92:93], v[226:227]
	v_add_f32_e32 v114, v220, v221
	v_add_f32_e32 v115, v222, v223
	v_add_f32_e32 v116, v224, v225
	v_add_f32_e32 v117, v226, v227
	v_add_f32_dpp v114, v114, v114 quad_perm:[1,0,3,2] row_mask:0xf bank_mask:0xf
	v_add_f32_dpp v115, v115, v115 quad_perm:[1,0,3,2] row_mask:0xf bank_mask:0xf
	v_add_f32_dpp v116, v116, v116 quad_perm:[1,0,3,2] row_mask:0xf bank_mask:0xf
	v_add_f32_dpp v117, v117, v117 quad_perm:[1,0,3,2] row_mask:0xf bank_mask:0xf
	v_add_f32_dpp v114, v114, v114 quad_perm:[2,3,0,1] row_mask:0xf bank_mask:0xf
	v_add_f32_dpp v115, v115, v115 quad_perm:[2,3,0,1] row_mask:0xf bank_mask:0xf
	v_add_f32_dpp v116, v116, v116 quad_perm:[2,3,0,1] row_mask:0xf bank_mask:0xf
	v_add_f32_dpp v117, v117, v117 quad_perm:[2,3,0,1] row_mask:0xf bank_mask:0xf
	v_add_f32_dpp v114, v114, v114 row_half_mirror row_mask:0xf bank_mask:0xf
	v_add_f32_dpp v115, v115, v115 row_half_mirror row_mask:0xf bank_mask:0xf
	v_add_f32_dpp v116, v116, v116 row_half_mirror row_mask:0xf bank_mask:0xf
	v_add_f32_dpp v117, v117, v117 row_half_mirror row_mask:0xf bank_mask:0xf
	s_waitcnt vmcnt(22)
	v_cvt_pk_f32_fp8_e32 v[204:205], v164
	v_cvt_pk_f32_fp8_e32 v[206:207], v168
	v_pk_mul_f32 v[220:221], v[204:205], v[78:79]
	v_pk_mul_f32 v[222:223], v[206:207], v[78:79]
	v_cvt_pk_f32_fp8_sdwa v[208:209], v164 src0_sel:WORD_1
	v_cvt_pk_f32_fp8_sdwa v[210:211], v168 src0_sel:WORD_1
	v_pk_fma_f32 v[220:221], v[208:209], v[80:81], v[220:221]
	v_pk_fma_f32 v[222:223], v[210:211], v[80:81], v[222:223]
	v_cvt_pk_f32_fp8_e32 v[212:213], v165
	v_cvt_pk_f32_fp8_e32 v[214:215], v169
	v_pk_fma_f32 v[220:221], v[212:213], v[82:83], v[220:221]
	v_pk_fma_f32 v[222:223], v[214:215], v[82:83], v[222:223]
	v_cvt_pk_f32_fp8_sdwa v[216:217], v165 src0_sel:WORD_1
	v_cvt_pk_f32_fp8_sdwa v[218:219], v169 src0_sel:WORD_1
	v_pk_fma_f32 v[220:221], v[216:217], v[84:85], v[220:221]
	v_pk_fma_f32 v[222:223], v[218:219], v[84:85], v[222:223]
	v_cvt_pk_f32_fp8_e32 v[204:205], v166
	v_cvt_pk_f32_fp8_e32 v[206:207], v170
	v_pk_fma_f32 v[220:221], v[204:205], v[86:87], v[220:221]
	v_pk_fma_f32 v[222:223], v[206:207], v[86:87], v[222:223]
	v_cvt_pk_f32_fp8_sdwa v[208:209], v166 src0_sel:WORD_1
	v_cvt_pk_f32_fp8_sdwa v[210:211], v170 src0_sel:WORD_1
	v_pk_fma_f32 v[220:221], v[208:209], v[88:89], v[220:221]
	v_pk_fma_f32 v[222:223], v[210:211], v[88:89], v[222:223]
	v_cvt_pk_f32_fp8_e32 v[212:213], v167
	v_cvt_pk_f32_fp8_e32 v[214:215], v171
	v_pk_fma_f32 v[220:221], v[212:213], v[90:91], v[220:221]
	v_pk_fma_f32 v[222:223], v[214:215], v[90:91], v[222:223]
	v_cvt_pk_f32_fp8_sdwa v[216:217], v167 src0_sel:WORD_1
	v_cvt_pk_f32_fp8_sdwa v[218:219], v171 src0_sel:WORD_1
	v_pk_fma_f32 v[220:221], v[216:217], v[92:93], v[220:221]
	v_pk_fma_f32 v[222:223], v[218:219], v[92:93], v[222:223]
	s_waitcnt vmcnt(20)
; __device__ __forceinline__ void attn_phase(const Args& a, unsigned char* lds, int lane, int wave) {
;     ...
;             float s[8];
; #pragma unroll
;             for (int i = 0; i < 8; ++i) { float kf[16]; unpack16_fp8(kk[i], kf); float d0 = 0.f, d1 = 0.f;
; #pragma unroll
;                 for (int x = 0; x < 16; x += 2) { d0 += q[x] * kf[x]; d1 += q[x + 1] * kf[x + 1]; }
;                 float d = d0 + d1;
;                 d += __shfl_xor(d, 1); d += __shfl_xor(d, 2); d += __shfl_xor(d, 4); s[i] = d; }
	v_cvt_pk_f32_fp8_e32 v[204:205], v172
	v_cvt_pk_f32_fp8_e32 v[206:207], v176
	v_pk_mul_f32 v[224:225], v[204:205], v[78:79]
	v_pk_mul_f32 v[226:227], v[206:207], v[78:79]
	v_cvt_pk_f32_fp8_sdwa v[208:209], v172 src0_sel:WORD_1
	v_cvt_pk_f32_fp8_sdwa v[210:211], v176 src0_sel:WORD_1
	v_pk_fma_f32 v[224:225], v[208:209], v[80:81], v[224:225]
	v_pk_fma_f32 v[226:227], v[210:211], v[80:81], v[226:227]
	v_cvt_pk_f32_fp8_e32 v[212:213], v173
	v_cvt_pk_f32_fp8_e32 v[214:215], v177
	v_pk_fma_f32 v[224:225], v[212:213], v[82:83], v[224:225]
	v_pk_fma_f32 v[226:227], v[214:215], v[82:83], v[226:227]
	v_cvt_pk_f32_fp8_sdwa v[216:217], v173 src0_sel:WORD_1
	v_cvt_pk_f32_fp8_sdwa v[218:219], v177 src0_sel:WORD_1
	v_pk_fma_f32 v[224:225], v[216:217], v[84:85], v[224:225]
	v_pk_fma_f32 v[226:227], v[218:219], v[84:85], v[226:227]
	v_cvt_pk_f32_fp8_e32 v[204:205], v174
	v_cvt_pk_f32_fp8_e32 v[206:207], v178
	v_pk_fma_f32 v[224:225], v[204:205], v[86:87], v[224:225]
	v_pk_fma_f32 v[226:227], v[206:207], v[86:87], v[226:227]
	v_cvt_pk_f32_fp8_sdwa v[208:209], v174 src0_sel:WORD_1
	v_cvt_pk_f32_fp8_sdwa v[210:211], v178 src0_sel:WORD_1
	v_pk_fma_f32 v[224:225], v[208:209], v[88:89], v[224:225]
	v_pk_fma_f32 v[226:227], v[210:211], v[88:89], v[226:227]
	v_cvt_pk_f32_fp8_e32 v[212:213], v175
	v_cvt_pk_f32_fp8_e32 v[214:215], v179
	v_pk_fma_f32 v[224:225], v[212:213], v[90:91], v[224:225]
	v_pk_fma_f32 v[226:227], v[214:215], v[90:91], v[226:227]
	v_cvt_pk_f32_fp8_sdwa v[216:217], v175 src0_sel:WORD_1
	v_cvt_pk_f32_fp8_sdwa v[218:219], v179 src0_sel:WORD_1
	v_pk_fma_f32 v[224:225], v[216:217], v[92:93], v[224:225]
	v_pk_fma_f32 v[226:227], v[218:219], v[92:93], v[226:227]
	v_add_f32_e32 v118, v220, v221
	v_add_f32_e32 v119, v222, v223
	v_add_f32_e32 v120, v224, v225
	v_add_f32_e32 v121, v226, v227
	v_add_f32_dpp v118, v118, v118 quad_perm:[1,0,3,2] row_mask:0xf bank_mask:0xf
	v_add_f32_dpp v119, v119, v119 quad_perm:[1,0,3,2] row_mask:0xf bank_mask:0xf
	v_add_f32_dpp v120, v120, v120 quad_perm:[1,0,3,2] row_mask:0xf bank_mask:0xf
	v_add_f32_dpp v121, v121, v121 quad_perm:[1,0,3,2] row_mask:0xf bank_mask:0xf
	v_add_f32_dpp v118, v118, v118 quad_perm:[2,3,0,1] row_mask:0xf bank_mask:0xf
	v_add_f32_dpp v119, v119, v119 quad_perm:[2,3,0,1] row_mask:0xf bank_mask:0xf
	v_add_f32_dpp v120, v120, v120 quad_perm:[2,3,0,1] row_mask:0xf bank_mask:0xf
	v_add_f32_dpp v121, v121, v121 quad_perm:[2,3,0,1] row_mask:0xf bank_mask:0xf
	v_add_f32_dpp v118, v118, v118 row_half_mirror row_mask:0xf bank_mask:0xf
	v_add_f32_dpp v119, v119, v119 row_half_mirror row_mask:0xf bank_mask:0xf
	v_add_f32_dpp v120, v120, v120 row_half_mirror row_mask:0xf bank_mask:0xf
	v_add_f32_dpp v121, v121, v121 row_half_mirror row_mask:0xf bank_mask:0xf
	s_waitcnt vmcnt(18)
	v_cvt_pk_f32_fp8_e32 v[204:205], v180
	v_cvt_pk_f32_fp8_e32 v[206:207], v184
	v_pk_mul_f32 v[220:221], v[204:205], v[78:79]
	v_pk_mul_f32 v[222:223], v[206:207], v[78:79]
	v_cvt_pk_f32_fp8_sdwa v[208:209], v180 src0_sel:WORD_1
	v_cvt_pk_f32_fp8_sdwa v[210:211], v184 src0_sel:WORD_1
	v_pk_fma_f32 v[220:221], v[208:209], v[80:81], v[220:221]
	v_pk_fma_f32 v[222:223], v[210:211], v[80:81], v[222:223]
	v_cvt_pk_f32_fp8_e32 v[212:213], v181
	v_cvt_pk_f32_fp8_e32 v[214:215], v185
	v_pk_fma_f32 v[220:221], v[212:213], v[82:83], v[220:221]
	v_pk_fma_f32 v[222:223], v[214:215], v[82:83], v[222:223]
	v_cvt_pk_f32_fp8_sdwa v[216:217], v181 src0_sel:WORD_1
	v_cvt_pk_f32_fp8_sdwa v[218:219], v185 src0_sel:WORD_1
	v_pk_fma_f32 v[220:221], v[216:217], v[84:85], v[220:221]
	v_pk_fma_f32 v[222:223], v[218:219], v[84:85], v[222:223]
	v_cvt_pk_f32_fp8_e32 v[204:205], v182
	v_cvt_pk_f32_fp8_e32 v[206:207], v186
	v_pk_fma_f32 v[220:221], v[204:205], v[86:87], v[220:221]
	v_pk_fma_f32 v[222:223], v[206:207], v[86:87], v[222:223]
	v_cvt_pk_f32_fp8_sdwa v[208:209], v182 src0_sel:WORD_1
	v_cvt_pk_f32_fp8_sdwa v[210:211], v186 src0_sel:WORD_1
	v_pk_fma_f32 v[220:221], v[208:209], v[88:89], v[220:221]
	v_pk_fma_f32 v[222:223], v[210:211], v[88:89], v[222:223]
	v_cvt_pk_f32_fp8_e32 v[212:213], v183
	v_cvt_pk_f32_fp8_e32 v[214:215], v187
	v_pk_fma_f32 v[220:221], v[212:213], v[90:91], v[220:221]
	v_pk_fma_f32 v[222:223], v[214:215], v[90:91], v[222:223]
	v_cvt_pk_f32_fp8_sdwa v[216:217], v183 src0_sel:WORD_1
	v_cvt_pk_f32_fp8_sdwa v[218:219], v187 src0_sel:WORD_1
	v_pk_fma_f32 v[220:221], v[216:217], v[92:93], v[220:221]
	v_pk_fma_f32 v[222:223], v[218:219], v[92:93], v[222:223]
	s_waitcnt vmcnt(16)
; __device__ __forceinline__ void attn_phase(const Args& a, unsigned char* lds, int lane, int wave) {
;     ...
;             float s[8];
; #pragma unroll
;             for (int i = 0; i < 8; ++i) { float kf[16]; unpack16_fp8(kk[i], kf); float d0 = 0.f, d1 = 0.f;
; #pragma unroll
;                 for (int x = 0; x < 16; x += 2) { d0 += q[x] * kf[x]; d1 += q[x + 1] * kf[x + 1]; }
;                 float d = d0 + d1;
;                 d += __shfl_xor(d, 1); d += __shfl_xor(d, 2); d += __shfl_xor(d, 4); s[i] = d; }
;             const float mn = fmaxf(fmaxf(fmaxf(mx, fmaxf(s[0], s[1])), fmaxf(s[2], s[3])), fmaxf(fmaxf(s[4], s[5]), fmaxf(s[6], s[7])));
;             const float al = __builtin_amdgcn_exp2f(mx - mn);
;             float p[8];
; #pragma unroll
;             for (int i = 0; i < 8; ++i) p[i] = __builtin_amdgcn_exp2f(s[i] - mn);
;             l = l * al + ((p[0] + p[1]) + (p[2] + p[3])) + ((p[4] + p[5]) + (p[6] + p[7]));
; #pragma unroll
;             for (int d = 0; d < 16; ++d) o[d] *= al;
	v_cvt_pk_f32_fp8_e32 v[204:205], v188
	v_cvt_pk_f32_fp8_e32 v[206:207], v192
	v_pk_mul_f32 v[224:225], v[204:205], v[78:79]
	v_pk_mul_f32 v[226:227], v[206:207], v[78:79]
	v_cvt_pk_f32_fp8_sdwa v[208:209], v188 src0_sel:WORD_1
	v_cvt_pk_f32_fp8_sdwa v[210:211], v192 src0_sel:WORD_1
	v_pk_fma_f32 v[224:225], v[208:209], v[80:81], v[224:225]
	v_pk_fma_f32 v[226:227], v[210:211], v[80:81], v[226:227]
	v_cvt_pk_f32_fp8_e32 v[212:213], v189
	v_cvt_pk_f32_fp8_e32 v[214:215], v193
	v_pk_fma_f32 v[224:225], v[212:213], v[82:83], v[224:225]
	v_pk_fma_f32 v[226:227], v[214:215], v[82:83], v[226:227]
	v_cvt_pk_f32_fp8_sdwa v[216:217], v189 src0_sel:WORD_1
	v_cvt_pk_f32_fp8_sdwa v[218:219], v193 src0_sel:WORD_1
	v_pk_fma_f32 v[224:225], v[216:217], v[84:85], v[224:225]
	v_pk_fma_f32 v[226:227], v[218:219], v[84:85], v[226:227]
	v_cvt_pk_f32_fp8_e32 v[204:205], v190
	v_cvt_pk_f32_fp8_e32 v[206:207], v194
	v_pk_fma_f32 v[224:225], v[204:205], v[86:87], v[224:225]
	v_pk_fma_f32 v[226:227], v[206:207], v[86:87], v[226:227]
	v_cvt_pk_f32_fp8_sdwa v[208:209], v190 src0_sel:WORD_1
	v_cvt_pk_f32_fp8_sdwa v[210:211], v194 src0_sel:WORD_1
	v_pk_fma_f32 v[224:225], v[208:209], v[88:89], v[224:225]
	v_pk_fma_f32 v[226:227], v[210:211], v[88:89], v[226:227]
	v_cvt_pk_f32_fp8_e32 v[212:213], v191
	v_cvt_pk_f32_fp8_e32 v[214:215], v195
	v_pk_fma_f32 v[224:225], v[212:213], v[90:91], v[224:225]
	v_pk_fma_f32 v[226:227], v[214:215], v[90:91], v[226:227]
	v_cvt_pk_f32_fp8_sdwa v[216:217], v191 src0_sel:WORD_1
	v_cvt_pk_f32_fp8_sdwa v[218:219], v195 src0_sel:WORD_1
	v_pk_fma_f32 v[224:225], v[216:217], v[92:93], v[224:225]
	v_pk_fma_f32 v[226:227], v[218:219], v[92:93], v[226:227]
	v_add_f32_e32 v122, v220, v221
	v_add_f32_e32 v123, v222, v223
	v_add_f32_e32 v124, v224, v225
	v_add_f32_e32 v125, v226, v227
	v_add_f32_dpp v122, v122, v122 quad_perm:[1,0,3,2] row_mask:0xf bank_mask:0xf
	v_add_f32_dpp v123, v123, v123 quad_perm:[1,0,3,2] row_mask:0xf bank_mask:0xf
	v_add_f32_dpp v124, v124, v124 quad_perm:[1,0,3,2] row_mask:0xf bank_mask:0xf
	v_add_f32_dpp v125, v125, v125 quad_perm:[1,0,3,2] row_mask:0xf bank_mask:0xf
	v_add_f32_dpp v122, v122, v122 quad_perm:[2,3,0,1] row_mask:0xf bank_mask:0xf
	v_add_f32_dpp v123, v123, v123 quad_perm:[2,3,0,1] row_mask:0xf bank_mask:0xf
	v_add_f32_dpp v124, v124, v124 quad_perm:[2,3,0,1] row_mask:0xf bank_mask:0xf
	v_add_f32_dpp v125, v125, v125 quad_perm:[2,3,0,1] row_mask:0xf bank_mask:0xf
	v_add_f32_dpp v122, v122, v122 row_half_mirror row_mask:0xf bank_mask:0xf
	v_add_f32_dpp v123, v123, v123 row_half_mirror row_mask:0xf bank_mask:0xf
	v_add_f32_dpp v124, v124, v124 row_half_mirror row_mask:0xf bank_mask:0xf
	v_add_f32_dpp v125, v125, v125 row_half_mirror row_mask:0xf bank_mask:0xf
	v_max3_f32 v228, v110, v111, v112
	v_max3_f32 v229, v113, v114, v115
	v_max3_f32 v230, v116, v117, v118
	v_max3_f32 v231, v119, v120, v121
	v_max3_f32 v232, v122, v123, v124
	v_max3_f32 v233, v125, v109, v228
	v_max3_f32 v234, v229, v230, v231
	v_max3_f32 v235, v232, v233, v234
	v_sub_f32_e32 v236, v109, v235
	v_sub_f32_e32 v110, v110, v235
	v_sub_f32_e32 v111, v111, v235
	v_sub_f32_e32 v112, v112, v235
	v_sub_f32_e32 v113, v113, v235
	v_sub_f32_e32 v114, v114, v235
	v_sub_f32_e32 v115, v115, v235
	v_sub_f32_e32 v116, v116, v235
	v_sub_f32_e32 v117, v117, v235
	v_sub_f32_e32 v118, v118, v235
	v_sub_f32_e32 v119, v119, v235
	v_sub_f32_e32 v120, v120, v235
	v_sub_f32_e32 v121, v121, v235
	v_sub_f32_e32 v122, v122, v235
	v_sub_f32_e32 v123, v123, v235
	v_sub_f32_e32 v124, v124, v235
	v_sub_f32_e32 v125, v125, v235
	v_exp_f32_e32 v244, v236
	v_exp_f32_e32 v110, v110
	v_exp_f32_e32 v111, v111
	v_exp_f32_e32 v112, v112
	v_exp_f32_e32 v113, v113
	v_exp_f32_e32 v114, v114
	v_exp_f32_e32 v115, v115
	v_exp_f32_e32 v116, v116
	v_exp_f32_e32 v117, v117
	v_exp_f32_e32 v118, v118
	v_exp_f32_e32 v119, v119
	v_exp_f32_e32 v120, v120
	v_exp_f32_e32 v121, v121
	v_exp_f32_e32 v122, v122
	v_exp_f32_e32 v123, v123
	v_exp_f32_e32 v124, v124
	v_exp_f32_e32 v125, v125
	v_mov_b32_e32 v109, v235
	v_pk_mul_f32 v[62:63], v[62:63], v[244:245] op_sel_hi:[1,0]
	v_pk_mul_f32 v[64:65], v[64:65], v[244:245] op_sel_hi:[1,0]
	v_pk_mul_f32 v[66:67], v[66:67], v[244:245] op_sel_hi:[1,0]
	v_pk_mul_f32 v[68:69], v[68:69], v[244:245] op_sel_hi:[1,0]
	v_pk_mul_f32 v[70:71], v[70:71], v[244:245] op_sel_hi:[1,0]
	v_pk_mul_f32 v[72:73], v[72:73], v[244:245] op_sel_hi:[1,0]
	v_pk_mul_f32 v[74:75], v[74:75], v[244:245] op_sel_hi:[1,0]
	v_pk_mul_f32 v[76:77], v[76:77], v[244:245] op_sel_hi:[1,0]
	v_add_f32_e32 v228, v110, v111
	v_add_f32_e32 v229, v112, v113
	v_add_f32_e32 v230, v114, v115
	v_add_f32_e32 v231, v116, v117
	v_add_f32_e32 v232, v118, v119
	v_add_f32_e32 v233, v120, v121
	v_add_f32_e32 v234, v122, v123
	v_add_f32_e32 v235, v124, v125
	v_add_f32_e32 v228, v228, v229
	v_add_f32_e32 v230, v230, v231
	v_add_f32_e32 v232, v232, v233
	v_add_f32_e32 v234, v234, v235
	v_add_f32_e32 v228, v228, v230
	v_add_f32_e32 v232, v232, v234
	v_add_f32_e32 v228, v228, v232
	v_fma_f32 v108, v108, v244, v228
	s_add_i32 s31, s31, 64
	v_mov_b32_e32 v246, s31
	ds_read_b128 v[204:207], v246
	ds_read_b128 v[208:211], v246 offset:16
	ds_read_b128 v[212:215], v246 offset:32
	ds_read_b128 v[216:219], v246 offset:48
	s_waitcnt lgkmcnt(0)
; __device__ __forceinline__ void attn_phase(const Args& a, unsigned char* lds, int lane, int wave) {
;     ...
;             for (int i = 0; i < 8; ++i) { const int idx = (int)(i < 4 ? ida[i & 3] : idb[i & 3]); const unsigned char* kp;
;                 if (!sample) kp = KV8 + (size_t)idx * 2048;
;                 else if (idx < 1024) kp = CKV8 + (size_t)(bb * 1024 + idx) * 2048;
;                 else kp = KV8 + (size_t)(TP + bb * 64 + idx - 1024) * 2048;
;                 kk[i] = *(const u32x4*)(kp + lane * 16); vv[i] = *(const u32x4*)(kp + 1024 + lane * 16); }
;     ...
; #pragma unroll
;             for (int i = 0; i < 8; ++i) { float vf[16]; unpack16_fp8(vv[i], vf);
; #pragma unroll
;                 for (int d = 0; d < 16; ++d) o[d] += p[i] * vf[d]; }
	v_readfirstlane_b32 s8, v204
	v_readfirstlane_b32 s9, v205
	v_readfirstlane_b32 s10, v206
	v_readfirstlane_b32 s11, v207
	v_readfirstlane_b32 s12, v208
	v_readfirstlane_b32 s13, v209
	v_readfirstlane_b32 s14, v210
	v_readfirstlane_b32 s15, v211
	v_readfirstlane_b32 s16, v212
	v_readfirstlane_b32 s17, v213
	v_readfirstlane_b32 s18, v214
	v_readfirstlane_b32 s19, v215
	v_readfirstlane_b32 s20, v216
	v_readfirstlane_b32 s21, v217
	v_readfirstlane_b32 s22, v218
	v_readfirstlane_b32 s23, v219
	s_cmp_lt_u32 s8, 0x400
	s_cselect_b32 s24, s6, s4
	s_cselect_b32 s25, s7, s5
	s_lshl_b32 s8, s8, 11
	s_add_u32 s24, s24, s8
	s_addc_u32 s25, s25, 0
	global_load_dwordx4 v[132:135], v56, s[24:25]
	s_cmp_lt_u32 s9, 0x400
	s_cselect_b32 s24, s6, s4
	s_cselect_b32 s25, s7, s5
	s_lshl_b32 s9, s9, 11
	s_add_u32 s24, s24, s9
	s_addc_u32 s25, s25, 0
	global_load_dwordx4 v[136:139], v56, s[24:25]
	s_cmp_lt_u32 s10, 0x400
	s_cselect_b32 s24, s6, s4
	s_cselect_b32 s25, s7, s5
	s_lshl_b32 s10, s10, 11
	s_add_u32 s24, s24, s10
	s_addc_u32 s25, s25, 0
	global_load_dwordx4 v[140:143], v56, s[24:25]
	s_cmp_lt_u32 s11, 0x400
	s_cselect_b32 s24, s6, s4
	s_cselect_b32 s25, s7, s5
	s_lshl_b32 s11, s11, 11
	s_add_u32 s24, s24, s11
	s_addc_u32 s25, s25, 0
	global_load_dwordx4 v[144:147], v56, s[24:25]
	s_cmp_lt_u32 s12, 0x400
	s_cselect_b32 s24, s6, s4
	s_cselect_b32 s25, s7, s5
	s_lshl_b32 s12, s12, 11
	s_add_u32 s24, s24, s12
	s_addc_u32 s25, s25, 0
	global_load_dwordx4 v[148:151], v56, s[24:25]
	s_cmp_lt_u32 s13, 0x400
	s_cselect_b32 s24, s6, s4
	s_cselect_b32 s25, s7, s5
	s_lshl_b32 s13, s13, 11
	s_add_u32 s24, s24, s13
	s_addc_u32 s25, s25, 0
	global_load_dwordx4 v[152:155], v56, s[24:25]
	s_cmp_lt_u32 s14, 0x400
	s_cselect_b32 s24, s6, s4
	s_cselect_b32 s25, s7, s5
	s_lshl_b32 s14, s14, 11
	s_add_u32 s24, s24, s14
	s_addc_u32 s25, s25, 0
	global_load_dwordx4 v[156:159], v56, s[24:25]
	s_cmp_lt_u32 s15, 0x400
	s_cselect_b32 s24, s6, s4
	s_cselect_b32 s25, s7, s5
	s_lshl_b32 s15, s15, 11
	s_add_u32 s24, s24, s15
	s_addc_u32 s25, s25, 0
	global_load_dwordx4 v[160:163], v56, s[24:25]
	s_cmp_lt_u32 s16, 0x400
	s_cselect_b32 s24, s6, s4
	s_cselect_b32 s25, s7, s5
	s_lshl_b32 s16, s16, 11
	s_add_u32 s24, s24, s16
	s_addc_u32 s25, s25, 0
	global_load_dwordx4 v[164:167], v56, s[24:25]
	s_cmp_lt_u32 s17, 0x400
	s_cselect_b32 s24, s6, s4
	s_cselect_b32 s25, s7, s5
	s_lshl_b32 s17, s17, 11
	s_add_u32 s24, s24, s17
	s_addc_u32 s25, s25, 0
	global_load_dwordx4 v[168:171], v56, s[24:25]
	s_cmp_lt_u32 s18, 0x400
	s_cselect_b32 s24, s6, s4
	s_cselect_b32 s25, s7, s5
	s_lshl_b32 s18, s18, 11
	s_add_u32 s24, s24, s18
	s_addc_u32 s25, s25, 0
	global_load_dwordx4 v[172:175], v56, s[24:25]
	s_cmp_lt_u32 s19, 0x400
	s_cselect_b32 s24, s6, s4
	s_cselect_b32 s25, s7, s5
	s_lshl_b32 s19, s19, 11
	s_add_u32 s24, s24, s19
	s_addc_u32 s25, s25, 0
	global_load_dwordx4 v[176:179], v56, s[24:25]
	s_cmp_lt_u32 s20, 0x400
	s_cselect_b32 s24, s6, s4
	s_cselect_b32 s25, s7, s5
	s_lshl_b32 s20, s20, 11
	s_add_u32 s24, s24, s20
	s_addc_u32 s25, s25, 0
	global_load_dwordx4 v[180:183], v56, s[24:25]
	s_cmp_lt_u32 s21, 0x400
	s_cselect_b32 s24, s6, s4
	s_cselect_b32 s25, s7, s5
	s_lshl_b32 s21, s21, 11
	s_add_u32 s24, s24, s21
	s_addc_u32 s25, s25, 0
	global_load_dwordx4 v[184:187], v56, s[24:25]
	s_cmp_lt_u32 s22, 0x400
	s_cselect_b32 s24, s6, s4
	s_cselect_b32 s25, s7, s5
	s_lshl_b32 s22, s22, 11
	s_add_u32 s24, s24, s22
	s_addc_u32 s25, s25, 0
	global_load_dwordx4 v[188:191], v56, s[24:25]
	s_cmp_lt_u32 s23, 0x400
	s_cselect_b32 s24, s6, s4
	s_cselect_b32 s25, s7, s5
	s_lshl_b32 s23, s23, 11
	s_add_u32 s24, s24, s23
	s_addc_u32 s25, s25, 0
	global_load_dwordx4 v[192:195], v56, s[24:25]
	s_waitcnt vmcnt(31)
	v_cvt_pk_f32_fp8_e32 v[204:205], v0
	v_cvt_pk_f32_fp8_sdwa v[206:207], v0 src0_sel:WORD_1
	v_pk_fma_f32 v[62:63], v[204:205], v[110:111], v[62:63] op_sel_hi:[1,0,1]
	v_pk_fma_f32 v[64:65], v[206:207], v[110:111], v[64:65] op_sel_hi:[1,0,1]
	v_cvt_pk_f32_fp8_e32 v[208:209], v1
	v_cvt_pk_f32_fp8_sdwa v[210:211], v1 src0_sel:WORD_1
	v_pk_fma_f32 v[66:67], v[208:209], v[110:111], v[66:67] op_sel_hi:[1,0,1]
	v_pk_fma_f32 v[68:69], v[210:211], v[110:111], v[68:69] op_sel_hi:[1,0,1]
	v_cvt_pk_f32_fp8_e32 v[212:213], v2
	v_cvt_pk_f32_fp8_sdwa v[214:215], v2 src0_sel:WORD_1
	v_pk_fma_f32 v[70:71], v[212:213], v[110:111], v[70:71] op_sel_hi:[1,0,1]
	v_pk_fma_f32 v[72:73], v[214:215], v[110:111], v[72:73] op_sel_hi:[1,0,1]
	v_cvt_pk_f32_fp8_e32 v[216:217], v3
	v_cvt_pk_f32_fp8_sdwa v[218:219], v3 src0_sel:WORD_1
	v_pk_fma_f32 v[74:75], v[216:217], v[110:111], v[74:75] op_sel_hi:[1,0,1]
	v_pk_fma_f32 v[76:77], v[218:219], v[110:111], v[76:77] op_sel_hi:[1,0,1]
	s_waitcnt vmcnt(30)
	v_cvt_pk_f32_fp8_e32 v[204:205], v4
	v_cvt_pk_f32_fp8_sdwa v[206:207], v4 src0_sel:WORD_1
	v_pk_fma_f32 v[62:63], v[204:205], v[110:111], v[62:63] op_sel:[0,1,0] op_sel_hi:[1,1,1]
	v_pk_fma_f32 v[64:65], v[206:207], v[110:111], v[64:65] op_sel:[0,1,0] op_sel_hi:[1,1,1]
	v_cvt_pk_f32_fp8_e32 v[208:209], v5
	v_cvt_pk_f32_fp8_sdwa v[210:211], v5 src0_sel:WORD_1
	v_pk_fma_f32 v[66:67], v[208:209], v[110:111], v[66:67] op_sel:[0,1,0] op_sel_hi:[1,1,1]
	v_pk_fma_f32 v[68:69], v[210:211], v[110:111], v[68:69] op_sel:[0,1,0] op_sel_hi:[1,1,1]
	v_cvt_pk_f32_fp8_e32 v[212:213], v6
	v_cvt_pk_f32_fp8_sdwa v[214:215], v6 src0_sel:WORD_1
	v_pk_fma_f32 v[70:71], v[212:213], v[110:111], v[70:71] op_sel:[0,1,0] op_sel_hi:[1,1,1]
	v_pk_fma_f32 v[72:73], v[214:215], v[110:111], v[72:73] op_sel:[0,1,0] op_sel_hi:[1,1,1]
	v_cvt_pk_f32_fp8_e32 v[216:217], v7
	v_cvt_pk_f32_fp8_sdwa v[218:219], v7 src0_sel:WORD_1
	v_pk_fma_f32 v[74:75], v[216:217], v[110:111], v[74:75] op_sel:[0,1,0] op_sel_hi:[1,1,1]
	v_pk_fma_f32 v[76:77], v[218:219], v[110:111], v[76:77] op_sel:[0,1,0] op_sel_hi:[1,1,1]
	s_waitcnt vmcnt(29)
; __device__ __forceinline__ void attn_phase(const Args& a, unsigned char* lds, int lane, int wave) {
;     ...
; #pragma unroll
;             for (int i = 0; i < 8; ++i) { float vf[16]; unpack16_fp8(vv[i], vf);
; #pragma unroll
;                 for (int d = 0; d < 16; ++d) o[d] += p[i] * vf[d]; }
	v_cvt_pk_f32_fp8_e32 v[204:205], v8
	v_cvt_pk_f32_fp8_sdwa v[206:207], v8 src0_sel:WORD_1
	v_pk_fma_f32 v[62:63], v[204:205], v[112:113], v[62:63] op_sel_hi:[1,0,1]
	v_pk_fma_f32 v[64:65], v[206:207], v[112:113], v[64:65] op_sel_hi:[1,0,1]
	v_cvt_pk_f32_fp8_e32 v[208:209], v9
	v_cvt_pk_f32_fp8_sdwa v[210:211], v9 src0_sel:WORD_1
	v_pk_fma_f32 v[66:67], v[208:209], v[112:113], v[66:67] op_sel_hi:[1,0,1]
	v_pk_fma_f32 v[68:69], v[210:211], v[112:113], v[68:69] op_sel_hi:[1,0,1]
	v_cvt_pk_f32_fp8_e32 v[212:213], v10
	v_cvt_pk_f32_fp8_sdwa v[214:215], v10 src0_sel:WORD_1
	v_pk_fma_f32 v[70:71], v[212:213], v[112:113], v[70:71] op_sel_hi:[1,0,1]
	v_pk_fma_f32 v[72:73], v[214:215], v[112:113], v[72:73] op_sel_hi:[1,0,1]
	v_cvt_pk_f32_fp8_e32 v[216:217], v11
	v_cvt_pk_f32_fp8_sdwa v[218:219], v11 src0_sel:WORD_1
	v_pk_fma_f32 v[74:75], v[216:217], v[112:113], v[74:75] op_sel_hi:[1,0,1]
	v_pk_fma_f32 v[76:77], v[218:219], v[112:113], v[76:77] op_sel_hi:[1,0,1]
	s_waitcnt vmcnt(28)
	v_cvt_pk_f32_fp8_e32 v[204:205], v12
	v_cvt_pk_f32_fp8_sdwa v[206:207], v12 src0_sel:WORD_1
	v_pk_fma_f32 v[62:63], v[204:205], v[112:113], v[62:63] op_sel:[0,1,0] op_sel_hi:[1,1,1]
	v_pk_fma_f32 v[64:65], v[206:207], v[112:113], v[64:65] op_sel:[0,1,0] op_sel_hi:[1,1,1]
	v_cvt_pk_f32_fp8_e32 v[208:209], v13
	v_cvt_pk_f32_fp8_sdwa v[210:211], v13 src0_sel:WORD_1
	v_pk_fma_f32 v[66:67], v[208:209], v[112:113], v[66:67] op_sel:[0,1,0] op_sel_hi:[1,1,1]
	v_pk_fma_f32 v[68:69], v[210:211], v[112:113], v[68:69] op_sel:[0,1,0] op_sel_hi:[1,1,1]
	v_cvt_pk_f32_fp8_e32 v[212:213], v14
	v_cvt_pk_f32_fp8_sdwa v[214:215], v14 src0_sel:WORD_1
	v_pk_fma_f32 v[70:71], v[212:213], v[112:113], v[70:71] op_sel:[0,1,0] op_sel_hi:[1,1,1]
	v_pk_fma_f32 v[72:73], v[214:215], v[112:113], v[72:73] op_sel:[0,1,0] op_sel_hi:[1,1,1]
	v_cvt_pk_f32_fp8_e32 v[216:217], v15
	v_cvt_pk_f32_fp8_sdwa v[218:219], v15 src0_sel:WORD_1
	v_pk_fma_f32 v[74:75], v[216:217], v[112:113], v[74:75] op_sel:[0,1,0] op_sel_hi:[1,1,1]
	v_pk_fma_f32 v[76:77], v[218:219], v[112:113], v[76:77] op_sel:[0,1,0] op_sel_hi:[1,1,1]
	s_waitcnt vmcnt(27)
	v_cvt_pk_f32_fp8_e32 v[204:205], v16
	v_cvt_pk_f32_fp8_sdwa v[206:207], v16 src0_sel:WORD_1
	v_pk_fma_f32 v[62:63], v[204:205], v[114:115], v[62:63] op_sel_hi:[1,0,1]
	v_pk_fma_f32 v[64:65], v[206:207], v[114:115], v[64:65] op_sel_hi:[1,0,1]
	v_cvt_pk_f32_fp8_e32 v[208:209], v17
	v_cvt_pk_f32_fp8_sdwa v[210:211], v17 src0_sel:WORD_1
	v_pk_fma_f32 v[66:67], v[208:209], v[114:115], v[66:67] op_sel_hi:[1,0,1]
	v_pk_fma_f32 v[68:69], v[210:211], v[114:115], v[68:69] op_sel_hi:[1,0,1]
	v_cvt_pk_f32_fp8_e32 v[212:213], v18
	v_cvt_pk_f32_fp8_sdwa v[214:215], v18 src0_sel:WORD_1
	v_pk_fma_f32 v[70:71], v[212:213], v[114:115], v[70:71] op_sel_hi:[1,0,1]
	v_pk_fma_f32 v[72:73], v[214:215], v[114:115], v[72:73] op_sel_hi:[1,0,1]
	v_cvt_pk_f32_fp8_e32 v[216:217], v19
	v_cvt_pk_f32_fp8_sdwa v[218:219], v19 src0_sel:WORD_1
	v_pk_fma_f32 v[74:75], v[216:217], v[114:115], v[74:75] op_sel_hi:[1,0,1]
	v_pk_fma_f32 v[76:77], v[218:219], v[114:115], v[76:77] op_sel_hi:[1,0,1]
	s_waitcnt vmcnt(26)
	v_cvt_pk_f32_fp8_e32 v[204:205], v20
	v_cvt_pk_f32_fp8_sdwa v[206:207], v20 src0_sel:WORD_1
	v_pk_fma_f32 v[62:63], v[204:205], v[114:115], v[62:63] op_sel:[0,1,0] op_sel_hi:[1,1,1]
	v_pk_fma_f32 v[64:65], v[206:207], v[114:115], v[64:65] op_sel:[0,1,0] op_sel_hi:[1,1,1]
	v_cvt_pk_f32_fp8_e32 v[208:209], v21
	v_cvt_pk_f32_fp8_sdwa v[210:211], v21 src0_sel:WORD_1
	v_pk_fma_f32 v[66:67], v[208:209], v[114:115], v[66:67] op_sel:[0,1,0] op_sel_hi:[1,1,1]
	v_pk_fma_f32 v[68:69], v[210:211], v[114:115], v[68:69] op_sel:[0,1,0] op_sel_hi:[1,1,1]
	v_cvt_pk_f32_fp8_e32 v[212:213], v22
	v_cvt_pk_f32_fp8_sdwa v[214:215], v22 src0_sel:WORD_1
	v_pk_fma_f32 v[70:71], v[212:213], v[114:115], v[70:71] op_sel:[0,1,0] op_sel_hi:[1,1,1]
	v_pk_fma_f32 v[72:73], v[214:215], v[114:115], v[72:73] op_sel:[0,1,0] op_sel_hi:[1,1,1]
	v_cvt_pk_f32_fp8_e32 v[216:217], v23
	v_cvt_pk_f32_fp8_sdwa v[218:219], v23 src0_sel:WORD_1
	v_pk_fma_f32 v[74:75], v[216:217], v[114:115], v[74:75] op_sel:[0,1,0] op_sel_hi:[1,1,1]
	v_pk_fma_f32 v[76:77], v[218:219], v[114:115], v[76:77] op_sel:[0,1,0] op_sel_hi:[1,1,1]
	s_waitcnt vmcnt(25)
	v_cvt_pk_f32_fp8_e32 v[204:205], v24
	v_cvt_pk_f32_fp8_sdwa v[206:207], v24 src0_sel:WORD_1
	v_pk_fma_f32 v[62:63], v[204:205], v[116:117], v[62:63] op_sel_hi:[1,0,1]
	v_pk_fma_f32 v[64:65], v[206:207], v[116:117], v[64:65] op_sel_hi:[1,0,1]
	v_cvt_pk_f32_fp8_e32 v[208:209], v25
	v_cvt_pk_f32_fp8_sdwa v[210:211], v25 src0_sel:WORD_1
	v_pk_fma_f32 v[66:67], v[208:209], v[116:117], v[66:67] op_sel_hi:[1,0,1]
	v_pk_fma_f32 v[68:69], v[210:211], v[116:117], v[68:69] op_sel_hi:[1,0,1]
	v_cvt_pk_f32_fp8_e32 v[212:213], v26
	v_cvt_pk_f32_fp8_sdwa v[214:215], v26 src0_sel:WORD_1
	v_pk_fma_f32 v[70:71], v[212:213], v[116:117], v[70:71] op_sel_hi:[1,0,1]
	v_pk_fma_f32 v[72:73], v[214:215], v[116:117], v[72:73] op_sel_hi:[1,0,1]
	v_cvt_pk_f32_fp8_e32 v[216:217], v27
	v_cvt_pk_f32_fp8_sdwa v[218:219], v27 src0_sel:WORD_1
	v_pk_fma_f32 v[74:75], v[216:217], v[116:117], v[74:75] op_sel_hi:[1,0,1]
	v_pk_fma_f32 v[76:77], v[218:219], v[116:117], v[76:77] op_sel_hi:[1,0,1]
	s_waitcnt vmcnt(24)
; __device__ __forceinline__ void attn_phase(const Args& a, unsigned char* lds, int lane, int wave) {
;     ...
; #pragma unroll
;             for (int i = 0; i < 8; ++i) { float vf[16]; unpack16_fp8(vv[i], vf);
; #pragma unroll
;                 for (int d = 0; d < 16; ++d) o[d] += p[i] * vf[d]; }
	v_cvt_pk_f32_fp8_e32 v[204:205], v28
	v_cvt_pk_f32_fp8_sdwa v[206:207], v28 src0_sel:WORD_1
	v_pk_fma_f32 v[62:63], v[204:205], v[116:117], v[62:63] op_sel:[0,1,0] op_sel_hi:[1,1,1]
	v_pk_fma_f32 v[64:65], v[206:207], v[116:117], v[64:65] op_sel:[0,1,0] op_sel_hi:[1,1,1]
	v_cvt_pk_f32_fp8_e32 v[208:209], v29
	v_cvt_pk_f32_fp8_sdwa v[210:211], v29 src0_sel:WORD_1
	v_pk_fma_f32 v[66:67], v[208:209], v[116:117], v[66:67] op_sel:[0,1,0] op_sel_hi:[1,1,1]
	v_pk_fma_f32 v[68:69], v[210:211], v[116:117], v[68:69] op_sel:[0,1,0] op_sel_hi:[1,1,1]
	v_cvt_pk_f32_fp8_e32 v[212:213], v30
	v_cvt_pk_f32_fp8_sdwa v[214:215], v30 src0_sel:WORD_1
	v_pk_fma_f32 v[70:71], v[212:213], v[116:117], v[70:71] op_sel:[0,1,0] op_sel_hi:[1,1,1]
	v_pk_fma_f32 v[72:73], v[214:215], v[116:117], v[72:73] op_sel:[0,1,0] op_sel_hi:[1,1,1]
	v_cvt_pk_f32_fp8_e32 v[216:217], v31
	v_cvt_pk_f32_fp8_sdwa v[218:219], v31 src0_sel:WORD_1
	v_pk_fma_f32 v[74:75], v[216:217], v[116:117], v[74:75] op_sel:[0,1,0] op_sel_hi:[1,1,1]
	v_pk_fma_f32 v[76:77], v[218:219], v[116:117], v[76:77] op_sel:[0,1,0] op_sel_hi:[1,1,1]
	s_waitcnt vmcnt(23)
	v_cvt_pk_f32_fp8_e32 v[204:205], v32
	v_cvt_pk_f32_fp8_sdwa v[206:207], v32 src0_sel:WORD_1
	v_pk_fma_f32 v[62:63], v[204:205], v[118:119], v[62:63] op_sel_hi:[1,0,1]
	v_pk_fma_f32 v[64:65], v[206:207], v[118:119], v[64:65] op_sel_hi:[1,0,1]
	v_cvt_pk_f32_fp8_e32 v[208:209], v33
	v_cvt_pk_f32_fp8_sdwa v[210:211], v33 src0_sel:WORD_1
	v_pk_fma_f32 v[66:67], v[208:209], v[118:119], v[66:67] op_sel_hi:[1,0,1]
	v_pk_fma_f32 v[68:69], v[210:211], v[118:119], v[68:69] op_sel_hi:[1,0,1]
	v_cvt_pk_f32_fp8_e32 v[212:213], v34
	v_cvt_pk_f32_fp8_sdwa v[214:215], v34 src0_sel:WORD_1
	v_pk_fma_f32 v[70:71], v[212:213], v[118:119], v[70:71] op_sel_hi:[1,0,1]
	v_pk_fma_f32 v[72:73], v[214:215], v[118:119], v[72:73] op_sel_hi:[1,0,1]
	v_cvt_pk_f32_fp8_e32 v[216:217], v35
	v_cvt_pk_f32_fp8_sdwa v[218:219], v35 src0_sel:WORD_1
	v_pk_fma_f32 v[74:75], v[216:217], v[118:119], v[74:75] op_sel_hi:[1,0,1]
	v_pk_fma_f32 v[76:77], v[218:219], v[118:119], v[76:77] op_sel_hi:[1,0,1]
	s_waitcnt vmcnt(22)
	v_cvt_pk_f32_fp8_e32 v[204:205], v36
	v_cvt_pk_f32_fp8_sdwa v[206:207], v36 src0_sel:WORD_1
	v_pk_fma_f32 v[62:63], v[204:205], v[118:119], v[62:63] op_sel:[0,1,0] op_sel_hi:[1,1,1]
	v_pk_fma_f32 v[64:65], v[206:207], v[118:119], v[64:65] op_sel:[0,1,0] op_sel_hi:[1,1,1]
	v_cvt_pk_f32_fp8_e32 v[208:209], v37
	v_cvt_pk_f32_fp8_sdwa v[210:211], v37 src0_sel:WORD_1
	v_pk_fma_f32 v[66:67], v[208:209], v[118:119], v[66:67] op_sel:[0,1,0] op_sel_hi:[1,1,1]
	v_pk_fma_f32 v[68:69], v[210:211], v[118:119], v[68:69] op_sel:[0,1,0] op_sel_hi:[1,1,1]
	v_cvt_pk_f32_fp8_e32 v[212:213], v38
	v_cvt_pk_f32_fp8_sdwa v[214:215], v38 src0_sel:WORD_1
	v_pk_fma_f32 v[70:71], v[212:213], v[118:119], v[70:71] op_sel:[0,1,0] op_sel_hi:[1,1,1]
	v_pk_fma_f32 v[72:73], v[214:215], v[118:119], v[72:73] op_sel:[0,1,0] op_sel_hi:[1,1,1]
	v_cvt_pk_f32_fp8_e32 v[216:217], v39
	v_cvt_pk_f32_fp8_sdwa v[218:219], v39 src0_sel:WORD_1
	v_pk_fma_f32 v[74:75], v[216:217], v[118:119], v[74:75] op_sel:[0,1,0] op_sel_hi:[1,1,1]
	v_pk_fma_f32 v[76:77], v[218:219], v[118:119], v[76:77] op_sel:[0,1,0] op_sel_hi:[1,1,1]
	s_waitcnt vmcnt(21)
	v_cvt_pk_f32_fp8_e32 v[204:205], v40
	v_cvt_pk_f32_fp8_sdwa v[206:207], v40 src0_sel:WORD_1
	v_pk_fma_f32 v[62:63], v[204:205], v[120:121], v[62:63] op_sel_hi:[1,0,1]
	v_pk_fma_f32 v[64:65], v[206:207], v[120:121], v[64:65] op_sel_hi:[1,0,1]
	v_cvt_pk_f32_fp8_e32 v[208:209], v41
	v_cvt_pk_f32_fp8_sdwa v[210:211], v41 src0_sel:WORD_1
	v_pk_fma_f32 v[66:67], v[208:209], v[120:121], v[66:67] op_sel_hi:[1,0,1]
	v_pk_fma_f32 v[68:69], v[210:211], v[120:121], v[68:69] op_sel_hi:[1,0,1]
	v_cvt_pk_f32_fp8_e32 v[212:213], v42
	v_cvt_pk_f32_fp8_sdwa v[214:215], v42 src0_sel:WORD_1
	v_pk_fma_f32 v[70:71], v[212:213], v[120:121], v[70:71] op_sel_hi:[1,0,1]
	v_pk_fma_f32 v[72:73], v[214:215], v[120:121], v[72:73] op_sel_hi:[1,0,1]
	v_cvt_pk_f32_fp8_e32 v[216:217], v43
	v_cvt_pk_f32_fp8_sdwa v[218:219], v43 src0_sel:WORD_1
	v_pk_fma_f32 v[74:75], v[216:217], v[120:121], v[74:75] op_sel_hi:[1,0,1]
	v_pk_fma_f32 v[76:77], v[218:219], v[120:121], v[76:77] op_sel_hi:[1,0,1]
	s_waitcnt vmcnt(20)
	v_cvt_pk_f32_fp8_e32 v[204:205], v44
	v_cvt_pk_f32_fp8_sdwa v[206:207], v44 src0_sel:WORD_1
	v_pk_fma_f32 v[62:63], v[204:205], v[120:121], v[62:63] op_sel:[0,1,0] op_sel_hi:[1,1,1]
	v_pk_fma_f32 v[64:65], v[206:207], v[120:121], v[64:65] op_sel:[0,1,0] op_sel_hi:[1,1,1]
	v_cvt_pk_f32_fp8_e32 v[208:209], v45
	v_cvt_pk_f32_fp8_sdwa v[210:211], v45 src0_sel:WORD_1
	v_pk_fma_f32 v[66:67], v[208:209], v[120:121], v[66:67] op_sel:[0,1,0] op_sel_hi:[1,1,1]
	v_pk_fma_f32 v[68:69], v[210:211], v[120:121], v[68:69] op_sel:[0,1,0] op_sel_hi:[1,1,1]
	v_cvt_pk_f32_fp8_e32 v[212:213], v46
	v_cvt_pk_f32_fp8_sdwa v[214:215], v46 src0_sel:WORD_1
	v_pk_fma_f32 v[70:71], v[212:213], v[120:121], v[70:71] op_sel:[0,1,0] op_sel_hi:[1,1,1]
	v_pk_fma_f32 v[72:73], v[214:215], v[120:121], v[72:73] op_sel:[0,1,0] op_sel_hi:[1,1,1]
	v_cvt_pk_f32_fp8_e32 v[216:217], v47
	v_cvt_pk_f32_fp8_sdwa v[218:219], v47 src0_sel:WORD_1
	v_pk_fma_f32 v[74:75], v[216:217], v[120:121], v[74:75] op_sel:[0,1,0] op_sel_hi:[1,1,1]
	v_pk_fma_f32 v[76:77], v[218:219], v[120:121], v[76:77] op_sel:[0,1,0] op_sel_hi:[1,1,1]
	s_waitcnt vmcnt(19)
; __device__ __forceinline__ void attn_phase(const Args& a, unsigned char* lds, int lane, int wave) {
;     ...
;             for (int i = 0; i < 8; ++i) { const int idx = (int)(i < 4 ? ida[i & 3] : idb[i & 3]); const unsigned char* kp;
;                 if (!sample) kp = KV8 + (size_t)idx * 2048;
;                 else if (idx < 1024) kp = CKV8 + (size_t)(bb * 1024 + idx) * 2048;
;                 else kp = KV8 + (size_t)(TP + bb * 64 + idx - 1024) * 2048;
;                 kk[i] = *(const u32x4*)(kp + lane * 16); vv[i] = *(const u32x4*)(kp + 1024 + lane * 16); }
;     ...
; #pragma unroll
;             for (int i = 0; i < 8; ++i) { float vf[16]; unpack16_fp8(vv[i], vf);
; #pragma unroll
;                 for (int d = 0; d < 16; ++d) o[d] += p[i] * vf[d]; }
	v_cvt_pk_f32_fp8_e32 v[204:205], v48
	v_cvt_pk_f32_fp8_sdwa v[206:207], v48 src0_sel:WORD_1
	v_pk_fma_f32 v[62:63], v[204:205], v[122:123], v[62:63] op_sel_hi:[1,0,1]
	v_pk_fma_f32 v[64:65], v[206:207], v[122:123], v[64:65] op_sel_hi:[1,0,1]
	v_cvt_pk_f32_fp8_e32 v[208:209], v49
	v_cvt_pk_f32_fp8_sdwa v[210:211], v49 src0_sel:WORD_1
	v_pk_fma_f32 v[66:67], v[208:209], v[122:123], v[66:67] op_sel_hi:[1,0,1]
	v_pk_fma_f32 v[68:69], v[210:211], v[122:123], v[68:69] op_sel_hi:[1,0,1]
	v_cvt_pk_f32_fp8_e32 v[212:213], v50
	v_cvt_pk_f32_fp8_sdwa v[214:215], v50 src0_sel:WORD_1
	v_pk_fma_f32 v[70:71], v[212:213], v[122:123], v[70:71] op_sel_hi:[1,0,1]
	v_pk_fma_f32 v[72:73], v[214:215], v[122:123], v[72:73] op_sel_hi:[1,0,1]
	v_cvt_pk_f32_fp8_e32 v[216:217], v51
	v_cvt_pk_f32_fp8_sdwa v[218:219], v51 src0_sel:WORD_1
	v_pk_fma_f32 v[74:75], v[216:217], v[122:123], v[74:75] op_sel_hi:[1,0,1]
	v_pk_fma_f32 v[76:77], v[218:219], v[122:123], v[76:77] op_sel_hi:[1,0,1]
	s_waitcnt vmcnt(18)
	v_cvt_pk_f32_fp8_e32 v[204:205], v52
	v_cvt_pk_f32_fp8_sdwa v[206:207], v52 src0_sel:WORD_1
	v_pk_fma_f32 v[62:63], v[204:205], v[122:123], v[62:63] op_sel:[0,1,0] op_sel_hi:[1,1,1]
	v_pk_fma_f32 v[64:65], v[206:207], v[122:123], v[64:65] op_sel:[0,1,0] op_sel_hi:[1,1,1]
	v_cvt_pk_f32_fp8_e32 v[208:209], v53
	v_cvt_pk_f32_fp8_sdwa v[210:211], v53 src0_sel:WORD_1
	v_pk_fma_f32 v[66:67], v[208:209], v[122:123], v[66:67] op_sel:[0,1,0] op_sel_hi:[1,1,1]
	v_pk_fma_f32 v[68:69], v[210:211], v[122:123], v[68:69] op_sel:[0,1,0] op_sel_hi:[1,1,1]
	v_cvt_pk_f32_fp8_e32 v[212:213], v54
	v_cvt_pk_f32_fp8_sdwa v[214:215], v54 src0_sel:WORD_1
	v_pk_fma_f32 v[70:71], v[212:213], v[122:123], v[70:71] op_sel:[0,1,0] op_sel_hi:[1,1,1]
	v_pk_fma_f32 v[72:73], v[214:215], v[122:123], v[72:73] op_sel:[0,1,0] op_sel_hi:[1,1,1]
	v_cvt_pk_f32_fp8_e32 v[216:217], v55
	v_cvt_pk_f32_fp8_sdwa v[218:219], v55 src0_sel:WORD_1
	v_pk_fma_f32 v[74:75], v[216:217], v[122:123], v[74:75] op_sel:[0,1,0] op_sel_hi:[1,1,1]
	v_pk_fma_f32 v[76:77], v[218:219], v[122:123], v[76:77] op_sel:[0,1,0] op_sel_hi:[1,1,1]
	s_waitcnt vmcnt(17)
	v_cvt_pk_f32_fp8_e32 v[204:205], v196
	v_cvt_pk_f32_fp8_sdwa v[206:207], v196 src0_sel:WORD_1
	v_pk_fma_f32 v[62:63], v[204:205], v[124:125], v[62:63] op_sel_hi:[1,0,1]
	v_pk_fma_f32 v[64:65], v[206:207], v[124:125], v[64:65] op_sel_hi:[1,0,1]
	v_cvt_pk_f32_fp8_e32 v[208:209], v197
	v_cvt_pk_f32_fp8_sdwa v[210:211], v197 src0_sel:WORD_1
	v_pk_fma_f32 v[66:67], v[208:209], v[124:125], v[66:67] op_sel_hi:[1,0,1]
	v_pk_fma_f32 v[68:69], v[210:211], v[124:125], v[68:69] op_sel_hi:[1,0,1]
	v_cvt_pk_f32_fp8_e32 v[212:213], v198
	v_cvt_pk_f32_fp8_sdwa v[214:215], v198 src0_sel:WORD_1
	v_pk_fma_f32 v[70:71], v[212:213], v[124:125], v[70:71] op_sel_hi:[1,0,1]
	v_pk_fma_f32 v[72:73], v[214:215], v[124:125], v[72:73] op_sel_hi:[1,0,1]
	v_cvt_pk_f32_fp8_e32 v[216:217], v199
	v_cvt_pk_f32_fp8_sdwa v[218:219], v199 src0_sel:WORD_1
	v_pk_fma_f32 v[74:75], v[216:217], v[124:125], v[74:75] op_sel_hi:[1,0,1]
	v_pk_fma_f32 v[76:77], v[218:219], v[124:125], v[76:77] op_sel_hi:[1,0,1]
	s_waitcnt vmcnt(16)
	v_cvt_pk_f32_fp8_e32 v[204:205], v200
	v_cvt_pk_f32_fp8_sdwa v[206:207], v200 src0_sel:WORD_1
	v_pk_fma_f32 v[62:63], v[204:205], v[124:125], v[62:63] op_sel:[0,1,0] op_sel_hi:[1,1,1]
	v_pk_fma_f32 v[64:65], v[206:207], v[124:125], v[64:65] op_sel:[0,1,0] op_sel_hi:[1,1,1]
	v_cvt_pk_f32_fp8_e32 v[208:209], v201
	v_cvt_pk_f32_fp8_sdwa v[210:211], v201 src0_sel:WORD_1
	v_pk_fma_f32 v[66:67], v[208:209], v[124:125], v[66:67] op_sel:[0,1,0] op_sel_hi:[1,1,1]
	v_pk_fma_f32 v[68:69], v[210:211], v[124:125], v[68:69] op_sel:[0,1,0] op_sel_hi:[1,1,1]
	v_cvt_pk_f32_fp8_e32 v[212:213], v202
	v_cvt_pk_f32_fp8_sdwa v[214:215], v202 src0_sel:WORD_1
	v_pk_fma_f32 v[70:71], v[212:213], v[124:125], v[70:71] op_sel:[0,1,0] op_sel_hi:[1,1,1]
	v_pk_fma_f32 v[72:73], v[214:215], v[124:125], v[72:73] op_sel:[0,1,0] op_sel_hi:[1,1,1]
	v_cvt_pk_f32_fp8_e32 v[216:217], v203
	v_cvt_pk_f32_fp8_sdwa v[218:219], v203 src0_sel:WORD_1
	v_pk_fma_f32 v[74:75], v[216:217], v[124:125], v[74:75] op_sel:[0,1,0] op_sel_hi:[1,1,1]
	v_pk_fma_f32 v[76:77], v[218:219], v[124:125], v[76:77] op_sel:[0,1,0] op_sel_hi:[1,1,1]
	s_cmp_lt_u32 s8, 0x200000
	s_cselect_b32 s24, s6, s4
	s_cselect_b32 s25, s7, s5
	s_add_u32 s24, s24, s8
	s_addc_u32 s25, s25, 0
	global_load_dwordx4 v[0:3], v56, s[24:25] offset:1024
	s_cmp_lt_u32 s9, 0x200000
	s_cselect_b32 s24, s6, s4
	s_cselect_b32 s25, s7, s5
	s_add_u32 s24, s24, s9
	s_addc_u32 s25, s25, 0
	global_load_dwordx4 v[4:7], v56, s[24:25] offset:1024
	s_cmp_lt_u32 s10, 0x200000
	s_cselect_b32 s24, s6, s4
	s_cselect_b32 s25, s7, s5
	s_add_u32 s24, s24, s10
	s_addc_u32 s25, s25, 0
	global_load_dwordx4 v[8:11], v56, s[24:25] offset:1024
	s_cmp_lt_u32 s11, 0x200000
	s_cselect_b32 s24, s6, s4
	s_cselect_b32 s25, s7, s5
	s_add_u32 s24, s24, s11
	s_addc_u32 s25, s25, 0
	global_load_dwordx4 v[12:15], v56, s[24:25] offset:1024
	s_cmp_lt_u32 s12, 0x200000
	s_cselect_b32 s24, s6, s4
	s_cselect_b32 s25, s7, s5
	s_add_u32 s24, s24, s12
	s_addc_u32 s25, s25, 0
	global_load_dwordx4 v[16:19], v56, s[24:25] offset:1024
	s_cmp_lt_u32 s13, 0x200000
	s_cselect_b32 s24, s6, s4
	s_cselect_b32 s25, s7, s5
	s_add_u32 s24, s24, s13
	s_addc_u32 s25, s25, 0
	global_load_dwordx4 v[20:23], v56, s[24:25] offset:1024
	s_cmp_lt_u32 s14, 0x200000
	s_cselect_b32 s24, s6, s4
	s_cselect_b32 s25, s7, s5
	s_add_u32 s24, s24, s14
	s_addc_u32 s25, s25, 0
	global_load_dwordx4 v[24:27], v56, s[24:25] offset:1024
	s_cmp_lt_u32 s15, 0x200000
	s_cselect_b32 s24, s6, s4
	s_cselect_b32 s25, s7, s5
	s_add_u32 s24, s24, s15
	s_addc_u32 s25, s25, 0
; __device__ __forceinline__ void attn_phase(const Args& a, unsigned char* lds, int lane, int wave) {
;     ...
;             for (int i = 0; i < 8; ++i) { const int idx = (int)(i < 4 ? ida[i & 3] : idb[i & 3]); const unsigned char* kp;
;                 if (!sample) kp = KV8 + (size_t)idx * 2048;
;                 else if (idx < 1024) kp = CKV8 + (size_t)(bb * 1024 + idx) * 2048;
;                 else kp = KV8 + (size_t)(TP + bb * 64 + idx - 1024) * 2048;
;                 kk[i] = *(const u32x4*)(kp + lane * 16); vv[i] = *(const u32x4*)(kp + 1024 + lane * 16); }
;             float s[8];
; #pragma unroll
;             for (int i = 0; i < 8; ++i) { float kf[16]; unpack16_fp8(kk[i], kf); float d0 = 0.f, d1 = 0.f;
; #pragma unroll
;                 for (int x = 0; x < 16; x += 2) { d0 += q[x] * kf[x]; d1 += q[x + 1] * kf[x + 1]; }
;                 float d = d0 + d1;
;                 d += __shfl_xor(d, 1); d += __shfl_xor(d, 2); d += __shfl_xor(d, 4); s[i] = d; }
	global_load_dwordx4 v[28:31], v56, s[24:25] offset:1024
	s_cmp_lt_u32 s16, 0x200000
	s_cselect_b32 s24, s6, s4
	s_cselect_b32 s25, s7, s5
	s_add_u32 s24, s24, s16
	s_addc_u32 s25, s25, 0
	global_load_dwordx4 v[32:35], v56, s[24:25] offset:1024
	s_cmp_lt_u32 s17, 0x200000
	s_cselect_b32 s24, s6, s4
	s_cselect_b32 s25, s7, s5
	s_add_u32 s24, s24, s17
	s_addc_u32 s25, s25, 0
	global_load_dwordx4 v[36:39], v56, s[24:25] offset:1024
	s_cmp_lt_u32 s18, 0x200000
	s_cselect_b32 s24, s6, s4
	s_cselect_b32 s25, s7, s5
	s_add_u32 s24, s24, s18
	s_addc_u32 s25, s25, 0
	global_load_dwordx4 v[40:43], v56, s[24:25] offset:1024
	s_cmp_lt_u32 s19, 0x200000
	s_cselect_b32 s24, s6, s4
	s_cselect_b32 s25, s7, s5
	s_add_u32 s24, s24, s19
	s_addc_u32 s25, s25, 0
	global_load_dwordx4 v[44:47], v56, s[24:25] offset:1024
	s_cmp_lt_u32 s20, 0x200000
	s_cselect_b32 s24, s6, s4
	s_cselect_b32 s25, s7, s5
	s_add_u32 s24, s24, s20
	s_addc_u32 s25, s25, 0
	global_load_dwordx4 v[48:51], v56, s[24:25] offset:1024
	s_cmp_lt_u32 s21, 0x200000
	s_cselect_b32 s24, s6, s4
	s_cselect_b32 s25, s7, s5
	s_add_u32 s24, s24, s21
	s_addc_u32 s25, s25, 0
	global_load_dwordx4 v[52:55], v56, s[24:25] offset:1024
	s_cmp_lt_u32 s22, 0x200000
	s_cselect_b32 s24, s6, s4
	s_cselect_b32 s25, s7, s5
	s_add_u32 s24, s24, s22
	s_addc_u32 s25, s25, 0
	global_load_dwordx4 v[196:199], v56, s[24:25] offset:1024
	s_cmp_lt_u32 s23, 0x200000
	s_cselect_b32 s24, s6, s4
	s_cselect_b32 s25, s7, s5
	s_add_u32 s24, s24, s23
	s_addc_u32 s25, s25, 0
	global_load_dwordx4 v[200:203], v56, s[24:25] offset:1024
	s_add_i32 s3, s3, -1
	s_cmp_lg_u32 s3, 0
	s_cbranch_scc1 .Lat_blk
	s_waitcnt vmcnt(30)
	v_cvt_pk_f32_fp8_e32 v[204:205], v132
	v_cvt_pk_f32_fp8_e32 v[206:207], v136
	v_pk_mul_f32 v[220:221], v[204:205], v[78:79]
	v_pk_mul_f32 v[222:223], v[206:207], v[78:79]
	v_cvt_pk_f32_fp8_sdwa v[208:209], v132 src0_sel:WORD_1
	v_cvt_pk_f32_fp8_sdwa v[210:211], v136 src0_sel:WORD_1
	v_pk_fma_f32 v[220:221], v[208:209], v[80:81], v[220:221]
	v_pk_fma_f32 v[222:223], v[210:211], v[80:81], v[222:223]
	v_cvt_pk_f32_fp8_e32 v[212:213], v133
	v_cvt_pk_f32_fp8_e32 v[214:215], v137
	v_pk_fma_f32 v[220:221], v[212:213], v[82:83], v[220:221]
	v_pk_fma_f32 v[222:223], v[214:215], v[82:83], v[222:223]
	v_cvt_pk_f32_fp8_sdwa v[216:217], v133 src0_sel:WORD_1
	v_cvt_pk_f32_fp8_sdwa v[218:219], v137 src0_sel:WORD_1
	v_pk_fma_f32 v[220:221], v[216:217], v[84:85], v[220:221]
	v_pk_fma_f32 v[222:223], v[218:219], v[84:85], v[222:223]
	v_cvt_pk_f32_fp8_e32 v[204:205], v134
	v_cvt_pk_f32_fp8_e32 v[206:207], v138
	v_pk_fma_f32 v[220:221], v[204:205], v[86:87], v[220:221]
	v_pk_fma_f32 v[222:223], v[206:207], v[86:87], v[222:223]
	v_cvt_pk_f32_fp8_sdwa v[208:209], v134 src0_sel:WORD_1
	v_cvt_pk_f32_fp8_sdwa v[210:211], v138 src0_sel:WORD_1
	v_pk_fma_f32 v[220:221], v[208:209], v[88:89], v[220:221]
	v_pk_fma_f32 v[222:223], v[210:211], v[88:89], v[222:223]
	v_cvt_pk_f32_fp8_e32 v[212:213], v135
	v_cvt_pk_f32_fp8_e32 v[214:215], v139
	v_pk_fma_f32 v[220:221], v[212:213], v[90:91], v[220:221]
	v_pk_fma_f32 v[222:223], v[214:215], v[90:91], v[222:223]
	v_cvt_pk_f32_fp8_sdwa v[216:217], v135 src0_sel:WORD_1
	v_cvt_pk_f32_fp8_sdwa v[218:219], v139 src0_sel:WORD_1
	v_pk_fma_f32 v[220:221], v[216:217], v[92:93], v[220:221]
	v_pk_fma_f32 v[222:223], v[218:219], v[92:93], v[222:223]
	s_waitcnt vmcnt(28)
	v_cvt_pk_f32_fp8_e32 v[204:205], v140
	v_cvt_pk_f32_fp8_e32 v[206:207], v144
	v_pk_mul_f32 v[224:225], v[204:205], v[78:79]
	v_pk_mul_f32 v[226:227], v[206:207], v[78:79]
	v_cvt_pk_f32_fp8_sdwa v[208:209], v140 src0_sel:WORD_1
	v_cvt_pk_f32_fp8_sdwa v[210:211], v144 src0_sel:WORD_1
	v_pk_fma_f32 v[224:225], v[208:209], v[80:81], v[224:225]
	v_pk_fma_f32 v[226:227], v[210:211], v[80:81], v[226:227]
	v_cvt_pk_f32_fp8_e32 v[212:213], v141
	v_cvt_pk_f32_fp8_e32 v[214:215], v145
	v_pk_fma_f32 v[224:225], v[212:213], v[82:83], v[224:225]
	v_pk_fma_f32 v[226:227], v[214:215], v[82:83], v[226:227]
	v_cvt_pk_f32_fp8_sdwa v[216:217], v141 src0_sel:WORD_1
	v_cvt_pk_f32_fp8_sdwa v[218:219], v145 src0_sel:WORD_1
	v_pk_fma_f32 v[224:225], v[216:217], v[84:85], v[224:225]
	v_pk_fma_f32 v[226:227], v[218:219], v[84:85], v[226:227]
	v_cvt_pk_f32_fp8_e32 v[204:205], v142
	v_cvt_pk_f32_fp8_e32 v[206:207], v146
	v_pk_fma_f32 v[224:225], v[204:205], v[86:87], v[224:225]
	v_pk_fma_f32 v[226:227], v[206:207], v[86:87], v[226:227]
	v_cvt_pk_f32_fp8_sdwa v[208:209], v142 src0_sel:WORD_1
	v_cvt_pk_f32_fp8_sdwa v[210:211], v146 src0_sel:WORD_1
	v_pk_fma_f32 v[224:225], v[208:209], v[88:89], v[224:225]
	v_pk_fma_f32 v[226:227], v[210:211], v[88:89], v[226:227]
	v_cvt_pk_f32_fp8_e32 v[212:213], v143
	v_cvt_pk_f32_fp8_e32 v[214:215], v147
	v_pk_fma_f32 v[224:225], v[212:213], v[90:91], v[224:225]
	v_pk_fma_f32 v[226:227], v[214:215], v[90:91], v[226:227]
	v_cvt_pk_f32_fp8_sdwa v[216:217], v143 src0_sel:WORD_1
	v_cvt_pk_f32_fp8_sdwa v[218:219], v147 src0_sel:WORD_1
	v_pk_fma_f32 v[224:225], v[216:217], v[92:93], v[224:225]
	v_pk_fma_f32 v[226:227], v[218:219], v[92:93], v[226:227]
	v_add_f32_e32 v110, v220, v221
	v_add_f32_e32 v111, v222, v223
	v_add_f32_e32 v112, v224, v225
	v_add_f32_e32 v113, v226, v227
	v_add_f32_dpp v110, v110, v110 quad_perm:[1,0,3,2] row_mask:0xf bank_mask:0xf
	v_add_f32_dpp v111, v111, v111 quad_perm:[1,0,3,2] row_mask:0xf bank_mask:0xf
	v_add_f32_dpp v112, v112, v112 quad_perm:[1,0,3,2] row_mask:0xf bank_mask:0xf
	v_add_f32_dpp v113, v113, v113 quad_perm:[1,0,3,2] row_mask:0xf bank_mask:0xf
	v_add_f32_dpp v110, v110, v110 quad_perm:[2,3,0,1] row_mask:0xf bank_mask:0xf
	v_add_f32_dpp v111, v111, v111 quad_perm:[2,3,0,1] row_mask:0xf bank_mask:0xf
	v_add_f32_dpp v112, v112, v112 quad_perm:[2,3,0,1] row_mask:0xf bank_mask:0xf
	v_add_f32_dpp v113, v113, v113 quad_perm:[2,3,0,1] row_mask:0xf bank_mask:0xf
	v_add_f32_dpp v110, v110, v110 row_half_mirror row_mask:0xf bank_mask:0xf
	v_add_f32_dpp v111, v111, v111 row_half_mirror row_mask:0xf bank_mask:0xf
	v_add_f32_dpp v112, v112, v112 row_half_mirror row_mask:0xf bank_mask:0xf
	v_add_f32_dpp v113, v113, v113 row_half_mirror row_mask:0xf bank_mask:0xf
	s_waitcnt vmcnt(26)
; __device__ __forceinline__ void attn_phase(const Args& a, unsigned char* lds, int lane, int wave) {
;     ...
;             float s[8];
; #pragma unroll
;             for (int i = 0; i < 8; ++i) { float kf[16]; unpack16_fp8(kk[i], kf); float d0 = 0.f, d1 = 0.f;
; #pragma unroll
;                 for (int x = 0; x < 16; x += 2) { d0 += q[x] * kf[x]; d1 += q[x + 1] * kf[x + 1]; }
;                 float d = d0 + d1;
;                 d += __shfl_xor(d, 1); d += __shfl_xor(d, 2); d += __shfl_xor(d, 4); s[i] = d; }
	v_cvt_pk_f32_fp8_e32 v[204:205], v148
	v_cvt_pk_f32_fp8_e32 v[206:207], v152
	v_pk_mul_f32 v[220:221], v[204:205], v[78:79]
	v_pk_mul_f32 v[222:223], v[206:207], v[78:79]
	v_cvt_pk_f32_fp8_sdwa v[208:209], v148 src0_sel:WORD_1
	v_cvt_pk_f32_fp8_sdwa v[210:211], v152 src0_sel:WORD_1
	v_pk_fma_f32 v[220:221], v[208:209], v[80:81], v[220:221]
	v_pk_fma_f32 v[222:223], v[210:211], v[80:81], v[222:223]
	v_cvt_pk_f32_fp8_e32 v[212:213], v149
	v_cvt_pk_f32_fp8_e32 v[214:215], v153
	v_pk_fma_f32 v[220:221], v[212:213], v[82:83], v[220:221]
	v_pk_fma_f32 v[222:223], v[214:215], v[82:83], v[222:223]
	v_cvt_pk_f32_fp8_sdwa v[216:217], v149 src0_sel:WORD_1
	v_cvt_pk_f32_fp8_sdwa v[218:219], v153 src0_sel:WORD_1
	v_pk_fma_f32 v[220:221], v[216:217], v[84:85], v[220:221]
	v_pk_fma_f32 v[222:223], v[218:219], v[84:85], v[222:223]
	v_cvt_pk_f32_fp8_e32 v[204:205], v150
	v_cvt_pk_f32_fp8_e32 v[206:207], v154
	v_pk_fma_f32 v[220:221], v[204:205], v[86:87], v[220:221]
	v_pk_fma_f32 v[222:223], v[206:207], v[86:87], v[222:223]
	v_cvt_pk_f32_fp8_sdwa v[208:209], v150 src0_sel:WORD_1
	v_cvt_pk_f32_fp8_sdwa v[210:211], v154 src0_sel:WORD_1
	v_pk_fma_f32 v[220:221], v[208:209], v[88:89], v[220:221]
	v_pk_fma_f32 v[222:223], v[210:211], v[88:89], v[222:223]
	v_cvt_pk_f32_fp8_e32 v[212:213], v151
	v_cvt_pk_f32_fp8_e32 v[214:215], v155
	v_pk_fma_f32 v[220:221], v[212:213], v[90:91], v[220:221]
	v_pk_fma_f32 v[222:223], v[214:215], v[90:91], v[222:223]
	v_cvt_pk_f32_fp8_sdwa v[216:217], v151 src0_sel:WORD_1
	v_cvt_pk_f32_fp8_sdwa v[218:219], v155 src0_sel:WORD_1
	v_pk_fma_f32 v[220:221], v[216:217], v[92:93], v[220:221]
	v_pk_fma_f32 v[222:223], v[218:219], v[92:93], v[222:223]
	s_waitcnt vmcnt(24)
	v_cvt_pk_f32_fp8_e32 v[204:205], v156
	v_cvt_pk_f32_fp8_e32 v[206:207], v160
	v_pk_mul_f32 v[224:225], v[204:205], v[78:79]
	v_pk_mul_f32 v[226:227], v[206:207], v[78:79]
	v_cvt_pk_f32_fp8_sdwa v[208:209], v156 src0_sel:WORD_1
	v_cvt_pk_f32_fp8_sdwa v[210:211], v160 src0_sel:WORD_1
	v_pk_fma_f32 v[224:225], v[208:209], v[80:81], v[224:225]
	v_pk_fma_f32 v[226:227], v[210:211], v[80:81], v[226:227]
	v_cvt_pk_f32_fp8_e32 v[212:213], v157
	v_cvt_pk_f32_fp8_e32 v[214:215], v161
	v_pk_fma_f32 v[224:225], v[212:213], v[82:83], v[224:225]
	v_pk_fma_f32 v[226:227], v[214:215], v[82:83], v[226:227]
	v_cvt_pk_f32_fp8_sdwa v[216:217], v157 src0_sel:WORD_1
	v_cvt_pk_f32_fp8_sdwa v[218:219], v161 src0_sel:WORD_1
	v_pk_fma_f32 v[224:225], v[216:217], v[84:85], v[224:225]
	v_pk_fma_f32 v[226:227], v[218:219], v[84:85], v[226:227]
	v_cvt_pk_f32_fp8_e32 v[204:205], v158
	v_cvt_pk_f32_fp8_e32 v[206:207], v162
	v_pk_fma_f32 v[224:225], v[204:205], v[86:87], v[224:225]
	v_pk_fma_f32 v[226:227], v[206:207], v[86:87], v[226:227]
	v_cvt_pk_f32_fp8_sdwa v[208:209], v158 src0_sel:WORD_1
	v_cvt_pk_f32_fp8_sdwa v[210:211], v162 src0_sel:WORD_1
	v_pk_fma_f32 v[224:225], v[208:209], v[88:89], v[224:225]
	v_pk_fma_f32 v[226:227], v[210:211], v[88:89], v[226:227]
	v_cvt_pk_f32_fp8_e32 v[212:213], v159
	v_cvt_pk_f32_fp8_e32 v[214:215], v163
	v_pk_fma_f32 v[224:225], v[212:213], v[90:91], v[224:225]
	v_pk_fma_f32 v[226:227], v[214:215], v[90:91], v[226:227]
	v_cvt_pk_f32_fp8_sdwa v[216:217], v159 src0_sel:WORD_1
	v_cvt_pk_f32_fp8_sdwa v[218:219], v163 src0_sel:WORD_1
	v_pk_fma_f32 v[224:225], v[216:217], v[92:93], v[224:225]
	v_pk_fma_f32 v[226:227], v[218:219], v[92:93], v[226:227]
	v_add_f32_e32 v114, v220, v221
	v_add_f32_e32 v115, v222, v223
	v_add_f32_e32 v116, v224, v225
	v_add_f32_e32 v117, v226, v227
	v_add_f32_dpp v114, v114, v114 quad_perm:[1,0,3,2] row_mask:0xf bank_mask:0xf
	v_add_f32_dpp v115, v115, v115 quad_perm:[1,0,3,2] row_mask:0xf bank_mask:0xf
	v_add_f32_dpp v116, v116, v116 quad_perm:[1,0,3,2] row_mask:0xf bank_mask:0xf
	v_add_f32_dpp v117, v117, v117 quad_perm:[1,0,3,2] row_mask:0xf bank_mask:0xf
	v_add_f32_dpp v114, v114, v114 quad_perm:[2,3,0,1] row_mask:0xf bank_mask:0xf
	v_add_f32_dpp v115, v115, v115 quad_perm:[2,3,0,1] row_mask:0xf bank_mask:0xf
	v_add_f32_dpp v116, v116, v116 quad_perm:[2,3,0,1] row_mask:0xf bank_mask:0xf
	v_add_f32_dpp v117, v117, v117 quad_perm:[2,3,0,1] row_mask:0xf bank_mask:0xf
	v_add_f32_dpp v114, v114, v114 row_half_mirror row_mask:0xf bank_mask:0xf
	v_add_f32_dpp v115, v115, v115 row_half_mirror row_mask:0xf bank_mask:0xf
	v_add_f32_dpp v116, v116, v116 row_half_mirror row_mask:0xf bank_mask:0xf
	v_add_f32_dpp v117, v117, v117 row_half_mirror row_mask:0xf bank_mask:0xf
	s_waitcnt vmcnt(22)
	v_cvt_pk_f32_fp8_e32 v[204:205], v164
	v_cvt_pk_f32_fp8_e32 v[206:207], v168
	v_pk_mul_f32 v[220:221], v[204:205], v[78:79]
	v_pk_mul_f32 v[222:223], v[206:207], v[78:79]
	v_cvt_pk_f32_fp8_sdwa v[208:209], v164 src0_sel:WORD_1
	v_cvt_pk_f32_fp8_sdwa v[210:211], v168 src0_sel:WORD_1
	v_pk_fma_f32 v[220:221], v[208:209], v[80:81], v[220:221]
	v_pk_fma_f32 v[222:223], v[210:211], v[80:81], v[222:223]
	v_cvt_pk_f32_fp8_e32 v[212:213], v165
	v_cvt_pk_f32_fp8_e32 v[214:215], v169
	v_pk_fma_f32 v[220:221], v[212:213], v[82:83], v[220:221]
	v_pk_fma_f32 v[222:223], v[214:215], v[82:83], v[222:223]
	v_cvt_pk_f32_fp8_sdwa v[216:217], v165 src0_sel:WORD_1
	v_cvt_pk_f32_fp8_sdwa v[218:219], v169 src0_sel:WORD_1
	v_pk_fma_f32 v[220:221], v[216:217], v[84:85], v[220:221]
	v_pk_fma_f32 v[222:223], v[218:219], v[84:85], v[222:223]
	v_cvt_pk_f32_fp8_e32 v[204:205], v166
	v_cvt_pk_f32_fp8_e32 v[206:207], v170
	v_pk_fma_f32 v[220:221], v[204:205], v[86:87], v[220:221]
	v_pk_fma_f32 v[222:223], v[206:207], v[86:87], v[222:223]
	v_cvt_pk_f32_fp8_sdwa v[208:209], v166 src0_sel:WORD_1
	v_cvt_pk_f32_fp8_sdwa v[210:211], v170 src0_sel:WORD_1
	v_pk_fma_f32 v[220:221], v[208:209], v[88:89], v[220:221]
	v_pk_fma_f32 v[222:223], v[210:211], v[88:89], v[222:223]
	v_cvt_pk_f32_fp8_e32 v[212:213], v167
	v_cvt_pk_f32_fp8_e32 v[214:215], v171
	v_pk_fma_f32 v[220:221], v[212:213], v[90:91], v[220:221]
	v_pk_fma_f32 v[222:223], v[214:215], v[90:91], v[222:223]
	v_cvt_pk_f32_fp8_sdwa v[216:217], v167 src0_sel:WORD_1
	v_cvt_pk_f32_fp8_sdwa v[218:219], v171 src0_sel:WORD_1
	v_pk_fma_f32 v[220:221], v[216:217], v[92:93], v[220:221]
	v_pk_fma_f32 v[222:223], v[218:219], v[92:93], v[222:223]
	s_waitcnt vmcnt(20)
; __device__ __forceinline__ void attn_phase(const Args& a, unsigned char* lds, int lane, int wave) {
;     ...
;             float s[8];
; #pragma unroll
;             for (int i = 0; i < 8; ++i) { float kf[16]; unpack16_fp8(kk[i], kf); float d0 = 0.f, d1 = 0.f;
; #pragma unroll
;                 for (int x = 0; x < 16; x += 2) { d0 += q[x] * kf[x]; d1 += q[x + 1] * kf[x + 1]; }
;                 float d = d0 + d1;
;                 d += __shfl_xor(d, 1); d += __shfl_xor(d, 2); d += __shfl_xor(d, 4); s[i] = d; }
	v_cvt_pk_f32_fp8_e32 v[204:205], v172
	v_cvt_pk_f32_fp8_e32 v[206:207], v176
	v_pk_mul_f32 v[224:225], v[204:205], v[78:79]
	v_pk_mul_f32 v[226:227], v[206:207], v[78:79]
	v_cvt_pk_f32_fp8_sdwa v[208:209], v172 src0_sel:WORD_1
	v_cvt_pk_f32_fp8_sdwa v[210:211], v176 src0_sel:WORD_1
	v_pk_fma_f32 v[224:225], v[208:209], v[80:81], v[224:225]
	v_pk_fma_f32 v[226:227], v[210:211], v[80:81], v[226:227]
	v_cvt_pk_f32_fp8_e32 v[212:213], v173
	v_cvt_pk_f32_fp8_e32 v[214:215], v177
	v_pk_fma_f32 v[224:225], v[212:213], v[82:83], v[224:225]
	v_pk_fma_f32 v[226:227], v[214:215], v[82:83], v[226:227]
	v_cvt_pk_f32_fp8_sdwa v[216:217], v173 src0_sel:WORD_1
	v_cvt_pk_f32_fp8_sdwa v[218:219], v177 src0_sel:WORD_1
	v_pk_fma_f32 v[224:225], v[216:217], v[84:85], v[224:225]
	v_pk_fma_f32 v[226:227], v[218:219], v[84:85], v[226:227]
	v_cvt_pk_f32_fp8_e32 v[204:205], v174
	v_cvt_pk_f32_fp8_e32 v[206:207], v178
	v_pk_fma_f32 v[224:225], v[204:205], v[86:87], v[224:225]
	v_pk_fma_f32 v[226:227], v[206:207], v[86:87], v[226:227]
	v_cvt_pk_f32_fp8_sdwa v[208:209], v174 src0_sel:WORD_1
	v_cvt_pk_f32_fp8_sdwa v[210:211], v178 src0_sel:WORD_1
	v_pk_fma_f32 v[224:225], v[208:209], v[88:89], v[224:225]
	v_pk_fma_f32 v[226:227], v[210:211], v[88:89], v[226:227]
	v_cvt_pk_f32_fp8_e32 v[212:213], v175
	v_cvt_pk_f32_fp8_e32 v[214:215], v179
	v_pk_fma_f32 v[224:225], v[212:213], v[90:91], v[224:225]
	v_pk_fma_f32 v[226:227], v[214:215], v[90:91], v[226:227]
	v_cvt_pk_f32_fp8_sdwa v[216:217], v175 src0_sel:WORD_1
	v_cvt_pk_f32_fp8_sdwa v[218:219], v179 src0_sel:WORD_1
	v_pk_fma_f32 v[224:225], v[216:217], v[92:93], v[224:225]
	v_pk_fma_f32 v[226:227], v[218:219], v[92:93], v[226:227]
	v_add_f32_e32 v118, v220, v221
	v_add_f32_e32 v119, v222, v223
	v_add_f32_e32 v120, v224, v225
	v_add_f32_e32 v121, v226, v227
	v_add_f32_dpp v118, v118, v118 quad_perm:[1,0,3,2] row_mask:0xf bank_mask:0xf
	v_add_f32_dpp v119, v119, v119 quad_perm:[1,0,3,2] row_mask:0xf bank_mask:0xf
	v_add_f32_dpp v120, v120, v120 quad_perm:[1,0,3,2] row_mask:0xf bank_mask:0xf
	v_add_f32_dpp v121, v121, v121 quad_perm:[1,0,3,2] row_mask:0xf bank_mask:0xf
	v_add_f32_dpp v118, v118, v118 quad_perm:[2,3,0,1] row_mask:0xf bank_mask:0xf
	v_add_f32_dpp v119, v119, v119 quad_perm:[2,3,0,1] row_mask:0xf bank_mask:0xf
	v_add_f32_dpp v120, v120, v120 quad_perm:[2,3,0,1] row_mask:0xf bank_mask:0xf
	v_add_f32_dpp v121, v121, v121 quad_perm:[2,3,0,1] row_mask:0xf bank_mask:0xf
	v_add_f32_dpp v118, v118, v118 row_half_mirror row_mask:0xf bank_mask:0xf
	v_add_f32_dpp v119, v119, v119 row_half_mirror row_mask:0xf bank_mask:0xf
	v_add_f32_dpp v120, v120, v120 row_half_mirror row_mask:0xf bank_mask:0xf
	v_add_f32_dpp v121, v121, v121 row_half_mirror row_mask:0xf bank_mask:0xf
	s_waitcnt vmcnt(18)
	v_cvt_pk_f32_fp8_e32 v[204:205], v180
	v_cvt_pk_f32_fp8_e32 v[206:207], v184
	v_pk_mul_f32 v[220:221], v[204:205], v[78:79]
	v_pk_mul_f32 v[222:223], v[206:207], v[78:79]
	v_cvt_pk_f32_fp8_sdwa v[208:209], v180 src0_sel:WORD_1
	v_cvt_pk_f32_fp8_sdwa v[210:211], v184 src0_sel:WORD_1
	v_pk_fma_f32 v[220:221], v[208:209], v[80:81], v[220:221]
	v_pk_fma_f32 v[222:223], v[210:211], v[80:81], v[222:223]
	v_cvt_pk_f32_fp8_e32 v[212:213], v181
	v_cvt_pk_f32_fp8_e32 v[214:215], v185
	v_pk_fma_f32 v[220:221], v[212:213], v[82:83], v[220:221]
	v_pk_fma_f32 v[222:223], v[214:215], v[82:83], v[222:223]
	v_cvt_pk_f32_fp8_sdwa v[216:217], v181 src0_sel:WORD_1
	v_cvt_pk_f32_fp8_sdwa v[218:219], v185 src0_sel:WORD_1
	v_pk_fma_f32 v[220:221], v[216:217], v[84:85], v[220:221]
	v_pk_fma_f32 v[222:223], v[218:219], v[84:85], v[222:223]
	v_cvt_pk_f32_fp8_e32 v[204:205], v182
	v_cvt_pk_f32_fp8_e32 v[206:207], v186
	v_pk_fma_f32 v[220:221], v[204:205], v[86:87], v[220:221]
	v_pk_fma_f32 v[222:223], v[206:207], v[86:87], v[222:223]
	v_cvt_pk_f32_fp8_sdwa v[208:209], v182 src0_sel:WORD_1
	v_cvt_pk_f32_fp8_sdwa v[210:211], v186 src0_sel:WORD_1
	v_pk_fma_f32 v[220:221], v[208:209], v[88:89], v[220:221]
	v_pk_fma_f32 v[222:223], v[210:211], v[88:89], v[222:223]
	v_cvt_pk_f32_fp8_e32 v[212:213], v183
	v_cvt_pk_f32_fp8_e32 v[214:215], v187
	v_pk_fma_f32 v[220:221], v[212:213], v[90:91], v[220:221]
	v_pk_fma_f32 v[222:223], v[214:215], v[90:91], v[222:223]
	v_cvt_pk_f32_fp8_sdwa v[216:217], v183 src0_sel:WORD_1
	v_cvt_pk_f32_fp8_sdwa v[218:219], v187 src0_sel:WORD_1
	v_pk_fma_f32 v[220:221], v[216:217], v[92:93], v[220:221]
	v_pk_fma_f32 v[222:223], v[218:219], v[92:93], v[222:223]
	s_waitcnt vmcnt(16)
; __device__ __forceinline__ void attn_phase(const Args& a, unsigned char* lds, int lane, int wave) {
;     ...
;             float s[8];
; #pragma unroll
;             for (int i = 0; i < 8; ++i) { float kf[16]; unpack16_fp8(kk[i], kf); float d0 = 0.f, d1 = 0.f;
; #pragma unroll
;                 for (int x = 0; x < 16; x += 2) { d0 += q[x] * kf[x]; d1 += q[x + 1] * kf[x + 1]; }
;                 float d = d0 + d1;
;                 d += __shfl_xor(d, 1); d += __shfl_xor(d, 2); d += __shfl_xor(d, 4); s[i] = d; }
;             const float mn = fmaxf(fmaxf(fmaxf(mx, fmaxf(s[0], s[1])), fmaxf(s[2], s[3])), fmaxf(fmaxf(s[4], s[5]), fmaxf(s[6], s[7])));
;             const float al = __builtin_amdgcn_exp2f(mx - mn);
;             float p[8];
; #pragma unroll
;             for (int i = 0; i < 8; ++i) p[i] = __builtin_amdgcn_exp2f(s[i] - mn);
;             l = l * al + ((p[0] + p[1]) + (p[2] + p[3])) + ((p[4] + p[5]) + (p[6] + p[7]));
; #pragma unroll
;             for (int d = 0; d < 16; ++d) o[d] *= al;
; #pragma unroll
;             for (int i = 0; i < 8; ++i) { float vf[16]; unpack16_fp8(vv[i], vf);
; #pragma unroll
;                 for (int d = 0; d < 16; ++d) o[d] += p[i] * vf[d]; }
	v_cvt_pk_f32_fp8_e32 v[204:205], v188
	v_cvt_pk_f32_fp8_e32 v[206:207], v192
	v_pk_mul_f32 v[224:225], v[204:205], v[78:79]
	v_pk_mul_f32 v[226:227], v[206:207], v[78:79]
	v_cvt_pk_f32_fp8_sdwa v[208:209], v188 src0_sel:WORD_1
	v_cvt_pk_f32_fp8_sdwa v[210:211], v192 src0_sel:WORD_1
	v_pk_fma_f32 v[224:225], v[208:209], v[80:81], v[224:225]
	v_pk_fma_f32 v[226:227], v[210:211], v[80:81], v[226:227]
	v_cvt_pk_f32_fp8_e32 v[212:213], v189
	v_cvt_pk_f32_fp8_e32 v[214:215], v193
	v_pk_fma_f32 v[224:225], v[212:213], v[82:83], v[224:225]
	v_pk_fma_f32 v[226:227], v[214:215], v[82:83], v[226:227]
	v_cvt_pk_f32_fp8_sdwa v[216:217], v189 src0_sel:WORD_1
	v_cvt_pk_f32_fp8_sdwa v[218:219], v193 src0_sel:WORD_1
	v_pk_fma_f32 v[224:225], v[216:217], v[84:85], v[224:225]
	v_pk_fma_f32 v[226:227], v[218:219], v[84:85], v[226:227]
	v_cvt_pk_f32_fp8_e32 v[204:205], v190
	v_cvt_pk_f32_fp8_e32 v[206:207], v194
	v_pk_fma_f32 v[224:225], v[204:205], v[86:87], v[224:225]
	v_pk_fma_f32 v[226:227], v[206:207], v[86:87], v[226:227]
	v_cvt_pk_f32_fp8_sdwa v[208:209], v190 src0_sel:WORD_1
	v_cvt_pk_f32_fp8_sdwa v[210:211], v194 src0_sel:WORD_1
	v_pk_fma_f32 v[224:225], v[208:209], v[88:89], v[224:225]
	v_pk_fma_f32 v[226:227], v[210:211], v[88:89], v[226:227]
	v_cvt_pk_f32_fp8_e32 v[212:213], v191
	v_cvt_pk_f32_fp8_e32 v[214:215], v195
	v_pk_fma_f32 v[224:225], v[212:213], v[90:91], v[224:225]
	v_pk_fma_f32 v[226:227], v[214:215], v[90:91], v[226:227]
	v_cvt_pk_f32_fp8_sdwa v[216:217], v191 src0_sel:WORD_1
	v_cvt_pk_f32_fp8_sdwa v[218:219], v195 src0_sel:WORD_1
	v_pk_fma_f32 v[224:225], v[216:217], v[92:93], v[224:225]
	v_pk_fma_f32 v[226:227], v[218:219], v[92:93], v[226:227]
	v_add_f32_e32 v122, v220, v221
	v_add_f32_e32 v123, v222, v223
	v_add_f32_e32 v124, v224, v225
	v_add_f32_e32 v125, v226, v227
	v_add_f32_dpp v122, v122, v122 quad_perm:[1,0,3,2] row_mask:0xf bank_mask:0xf
	v_add_f32_dpp v123, v123, v123 quad_perm:[1,0,3,2] row_mask:0xf bank_mask:0xf
	v_add_f32_dpp v124, v124, v124 quad_perm:[1,0,3,2] row_mask:0xf bank_mask:0xf
	v_add_f32_dpp v125, v125, v125 quad_perm:[1,0,3,2] row_mask:0xf bank_mask:0xf
	v_add_f32_dpp v122, v122, v122 quad_perm:[2,3,0,1] row_mask:0xf bank_mask:0xf
	v_add_f32_dpp v123, v123, v123 quad_perm:[2,3,0,1] row_mask:0xf bank_mask:0xf
	v_add_f32_dpp v124, v124, v124 quad_perm:[2,3,0,1] row_mask:0xf bank_mask:0xf
	v_add_f32_dpp v125, v125, v125 quad_perm:[2,3,0,1] row_mask:0xf bank_mask:0xf
	v_add_f32_dpp v122, v122, v122 row_half_mirror row_mask:0xf bank_mask:0xf
	v_add_f32_dpp v123, v123, v123 row_half_mirror row_mask:0xf bank_mask:0xf
	v_add_f32_dpp v124, v124, v124 row_half_mirror row_mask:0xf bank_mask:0xf
	v_add_f32_dpp v125, v125, v125 row_half_mirror row_mask:0xf bank_mask:0xf
	v_max3_f32 v228, v110, v111, v112
	v_max3_f32 v229, v113, v114, v115
	v_max3_f32 v230, v116, v117, v118
	v_max3_f32 v231, v119, v120, v121
	v_max3_f32 v232, v122, v123, v124
	v_max3_f32 v233, v125, v109, v228
	v_max3_f32 v234, v229, v230, v231
	v_max3_f32 v235, v232, v233, v234
	v_sub_f32_e32 v236, v109, v235
	v_sub_f32_e32 v110, v110, v235
	v_sub_f32_e32 v111, v111, v235
	v_sub_f32_e32 v112, v112, v235
	v_sub_f32_e32 v113, v113, v235
	v_sub_f32_e32 v114, v114, v235
	v_sub_f32_e32 v115, v115, v235
	v_sub_f32_e32 v116, v116, v235
	v_sub_f32_e32 v117, v117, v235
	v_sub_f32_e32 v118, v118, v235
	v_sub_f32_e32 v119, v119, v235
	v_sub_f32_e32 v120, v120, v235
	v_sub_f32_e32 v121, v121, v235
	v_sub_f32_e32 v122, v122, v235
	v_sub_f32_e32 v123, v123, v235
	v_sub_f32_e32 v124, v124, v235
	v_sub_f32_e32 v125, v125, v235
	v_exp_f32_e32 v244, v236
	v_exp_f32_e32 v110, v110
	v_exp_f32_e32 v111, v111
	v_exp_f32_e32 v112, v112
	v_exp_f32_e32 v113, v113
	v_exp_f32_e32 v114, v114
	v_exp_f32_e32 v115, v115
	v_exp_f32_e32 v116, v116
	v_exp_f32_e32 v117, v117
	v_exp_f32_e32 v118, v118
	v_exp_f32_e32 v119, v119
	v_exp_f32_e32 v120, v120
	v_exp_f32_e32 v121, v121
	v_exp_f32_e32 v122, v122
	v_exp_f32_e32 v123, v123
	v_exp_f32_e32 v124, v124
	v_exp_f32_e32 v125, v125
	v_mov_b32_e32 v109, v235
	v_pk_mul_f32 v[62:63], v[62:63], v[244:245] op_sel_hi:[1,0]
	v_pk_mul_f32 v[64:65], v[64:65], v[244:245] op_sel_hi:[1,0]
	v_pk_mul_f32 v[66:67], v[66:67], v[244:245] op_sel_hi:[1,0]
	v_pk_mul_f32 v[68:69], v[68:69], v[244:245] op_sel_hi:[1,0]
	v_pk_mul_f32 v[70:71], v[70:71], v[244:245] op_sel_hi:[1,0]
	v_pk_mul_f32 v[72:73], v[72:73], v[244:245] op_sel_hi:[1,0]
	v_pk_mul_f32 v[74:75], v[74:75], v[244:245] op_sel_hi:[1,0]
	v_pk_mul_f32 v[76:77], v[76:77], v[244:245] op_sel_hi:[1,0]
	v_add_f32_e32 v228, v110, v111
	v_add_f32_e32 v229, v112, v113
	v_add_f32_e32 v230, v114, v115
	v_add_f32_e32 v231, v116, v117
	v_add_f32_e32 v232, v118, v119
	v_add_f32_e32 v233, v120, v121
	v_add_f32_e32 v234, v122, v123
	v_add_f32_e32 v235, v124, v125
	v_add_f32_e32 v228, v228, v229
	v_add_f32_e32 v230, v230, v231
	v_add_f32_e32 v232, v232, v233
	v_add_f32_e32 v234, v234, v235
	v_add_f32_e32 v228, v228, v230
	v_add_f32_e32 v232, v232, v234
	v_add_f32_e32 v228, v228, v232
	v_fma_f32 v108, v108, v244, v228
	s_waitcnt vmcnt(15)
	v_cvt_pk_f32_fp8_e32 v[204:205], v0
	v_cvt_pk_f32_fp8_sdwa v[206:207], v0 src0_sel:WORD_1
	v_pk_fma_f32 v[62:63], v[204:205], v[110:111], v[62:63] op_sel_hi:[1,0,1]
	v_pk_fma_f32 v[64:65], v[206:207], v[110:111], v[64:65] op_sel_hi:[1,0,1]
	v_cvt_pk_f32_fp8_e32 v[208:209], v1
	v_cvt_pk_f32_fp8_sdwa v[210:211], v1 src0_sel:WORD_1
	v_pk_fma_f32 v[66:67], v[208:209], v[110:111], v[66:67] op_sel_hi:[1,0,1]
	v_pk_fma_f32 v[68:69], v[210:211], v[110:111], v[68:69] op_sel_hi:[1,0,1]
	v_cvt_pk_f32_fp8_e32 v[212:213], v2
	v_cvt_pk_f32_fp8_sdwa v[214:215], v2 src0_sel:WORD_1
	v_pk_fma_f32 v[70:71], v[212:213], v[110:111], v[70:71] op_sel_hi:[1,0,1]
	v_pk_fma_f32 v[72:73], v[214:215], v[110:111], v[72:73] op_sel_hi:[1,0,1]
	v_cvt_pk_f32_fp8_e32 v[216:217], v3
	v_cvt_pk_f32_fp8_sdwa v[218:219], v3 src0_sel:WORD_1
	v_pk_fma_f32 v[74:75], v[216:217], v[110:111], v[74:75] op_sel_hi:[1,0,1]
	v_pk_fma_f32 v[76:77], v[218:219], v[110:111], v[76:77] op_sel_hi:[1,0,1]
	s_waitcnt vmcnt(14)
; __device__ __forceinline__ void attn_phase(const Args& a, unsigned char* lds, int lane, int wave) {
;     ...
; #pragma unroll
;             for (int i = 0; i < 8; ++i) { float vf[16]; unpack16_fp8(vv[i], vf);
; #pragma unroll
;                 for (int d = 0; d < 16; ++d) o[d] += p[i] * vf[d]; }
	v_cvt_pk_f32_fp8_e32 v[204:205], v4
	v_cvt_pk_f32_fp8_sdwa v[206:207], v4 src0_sel:WORD_1
	v_pk_fma_f32 v[62:63], v[204:205], v[110:111], v[62:63] op_sel:[0,1,0] op_sel_hi:[1,1,1]
	v_pk_fma_f32 v[64:65], v[206:207], v[110:111], v[64:65] op_sel:[0,1,0] op_sel_hi:[1,1,1]
	v_cvt_pk_f32_fp8_e32 v[208:209], v5
	v_cvt_pk_f32_fp8_sdwa v[210:211], v5 src0_sel:WORD_1
	v_pk_fma_f32 v[66:67], v[208:209], v[110:111], v[66:67] op_sel:[0,1,0] op_sel_hi:[1,1,1]
	v_pk_fma_f32 v[68:69], v[210:211], v[110:111], v[68:69] op_sel:[0,1,0] op_sel_hi:[1,1,1]
	v_cvt_pk_f32_fp8_e32 v[212:213], v6
	v_cvt_pk_f32_fp8_sdwa v[214:215], v6 src0_sel:WORD_1
	v_pk_fma_f32 v[70:71], v[212:213], v[110:111], v[70:71] op_sel:[0,1,0] op_sel_hi:[1,1,1]
	v_pk_fma_f32 v[72:73], v[214:215], v[110:111], v[72:73] op_sel:[0,1,0] op_sel_hi:[1,1,1]
	v_cvt_pk_f32_fp8_e32 v[216:217], v7
	v_cvt_pk_f32_fp8_sdwa v[218:219], v7 src0_sel:WORD_1
	v_pk_fma_f32 v[74:75], v[216:217], v[110:111], v[74:75] op_sel:[0,1,0] op_sel_hi:[1,1,1]
	v_pk_fma_f32 v[76:77], v[218:219], v[110:111], v[76:77] op_sel:[0,1,0] op_sel_hi:[1,1,1]
	s_waitcnt vmcnt(13)
	v_cvt_pk_f32_fp8_e32 v[204:205], v8
	v_cvt_pk_f32_fp8_sdwa v[206:207], v8 src0_sel:WORD_1
	v_pk_fma_f32 v[62:63], v[204:205], v[112:113], v[62:63] op_sel_hi:[1,0,1]
	v_pk_fma_f32 v[64:65], v[206:207], v[112:113], v[64:65] op_sel_hi:[1,0,1]
	v_cvt_pk_f32_fp8_e32 v[208:209], v9
	v_cvt_pk_f32_fp8_sdwa v[210:211], v9 src0_sel:WORD_1
	v_pk_fma_f32 v[66:67], v[208:209], v[112:113], v[66:67] op_sel_hi:[1,0,1]
	v_pk_fma_f32 v[68:69], v[210:211], v[112:113], v[68:69] op_sel_hi:[1,0,1]
	v_cvt_pk_f32_fp8_e32 v[212:213], v10
	v_cvt_pk_f32_fp8_sdwa v[214:215], v10 src0_sel:WORD_1
	v_pk_fma_f32 v[70:71], v[212:213], v[112:113], v[70:71] op_sel_hi:[1,0,1]
	v_pk_fma_f32 v[72:73], v[214:215], v[112:113], v[72:73] op_sel_hi:[1,0,1]
	v_cvt_pk_f32_fp8_e32 v[216:217], v11
	v_cvt_pk_f32_fp8_sdwa v[218:219], v11 src0_sel:WORD_1
	v_pk_fma_f32 v[74:75], v[216:217], v[112:113], v[74:75] op_sel_hi:[1,0,1]
	v_pk_fma_f32 v[76:77], v[218:219], v[112:113], v[76:77] op_sel_hi:[1,0,1]
	s_waitcnt vmcnt(12)
	v_cvt_pk_f32_fp8_e32 v[204:205], v12
	v_cvt_pk_f32_fp8_sdwa v[206:207], v12 src0_sel:WORD_1
	v_pk_fma_f32 v[62:63], v[204:205], v[112:113], v[62:63] op_sel:[0,1,0] op_sel_hi:[1,1,1]
	v_pk_fma_f32 v[64:65], v[206:207], v[112:113], v[64:65] op_sel:[0,1,0] op_sel_hi:[1,1,1]
	v_cvt_pk_f32_fp8_e32 v[208:209], v13
	v_cvt_pk_f32_fp8_sdwa v[210:211], v13 src0_sel:WORD_1
	v_pk_fma_f32 v[66:67], v[208:209], v[112:113], v[66:67] op_sel:[0,1,0] op_sel_hi:[1,1,1]
	v_pk_fma_f32 v[68:69], v[210:211], v[112:113], v[68:69] op_sel:[0,1,0] op_sel_hi:[1,1,1]
	v_cvt_pk_f32_fp8_e32 v[212:213], v14
	v_cvt_pk_f32_fp8_sdwa v[214:215], v14 src0_sel:WORD_1
	v_pk_fma_f32 v[70:71], v[212:213], v[112:113], v[70:71] op_sel:[0,1,0] op_sel_hi:[1,1,1]
	v_pk_fma_f32 v[72:73], v[214:215], v[112:113], v[72:73] op_sel:[0,1,0] op_sel_hi:[1,1,1]
	v_cvt_pk_f32_fp8_e32 v[216:217], v15
	v_cvt_pk_f32_fp8_sdwa v[218:219], v15 src0_sel:WORD_1
	v_pk_fma_f32 v[74:75], v[216:217], v[112:113], v[74:75] op_sel:[0,1,0] op_sel_hi:[1,1,1]
	v_pk_fma_f32 v[76:77], v[218:219], v[112:113], v[76:77] op_sel:[0,1,0] op_sel_hi:[1,1,1]
	s_waitcnt vmcnt(11)
	v_cvt_pk_f32_fp8_e32 v[204:205], v16
	v_cvt_pk_f32_fp8_sdwa v[206:207], v16 src0_sel:WORD_1
	v_pk_fma_f32 v[62:63], v[204:205], v[114:115], v[62:63] op_sel_hi:[1,0,1]
	v_pk_fma_f32 v[64:65], v[206:207], v[114:115], v[64:65] op_sel_hi:[1,0,1]
	v_cvt_pk_f32_fp8_e32 v[208:209], v17
	v_cvt_pk_f32_fp8_sdwa v[210:211], v17 src0_sel:WORD_1
	v_pk_fma_f32 v[66:67], v[208:209], v[114:115], v[66:67] op_sel_hi:[1,0,1]
	v_pk_fma_f32 v[68:69], v[210:211], v[114:115], v[68:69] op_sel_hi:[1,0,1]
	v_cvt_pk_f32_fp8_e32 v[212:213], v18
	v_cvt_pk_f32_fp8_sdwa v[214:215], v18 src0_sel:WORD_1
	v_pk_fma_f32 v[70:71], v[212:213], v[114:115], v[70:71] op_sel_hi:[1,0,1]
	v_pk_fma_f32 v[72:73], v[214:215], v[114:115], v[72:73] op_sel_hi:[1,0,1]
	v_cvt_pk_f32_fp8_e32 v[216:217], v19
	v_cvt_pk_f32_fp8_sdwa v[218:219], v19 src0_sel:WORD_1
	v_pk_fma_f32 v[74:75], v[216:217], v[114:115], v[74:75] op_sel_hi:[1,0,1]
	v_pk_fma_f32 v[76:77], v[218:219], v[114:115], v[76:77] op_sel_hi:[1,0,1]
	s_waitcnt vmcnt(10)
	v_cvt_pk_f32_fp8_e32 v[204:205], v20
	v_cvt_pk_f32_fp8_sdwa v[206:207], v20 src0_sel:WORD_1
	v_pk_fma_f32 v[62:63], v[204:205], v[114:115], v[62:63] op_sel:[0,1,0] op_sel_hi:[1,1,1]
	v_pk_fma_f32 v[64:65], v[206:207], v[114:115], v[64:65] op_sel:[0,1,0] op_sel_hi:[1,1,1]
	v_cvt_pk_f32_fp8_e32 v[208:209], v21
	v_cvt_pk_f32_fp8_sdwa v[210:211], v21 src0_sel:WORD_1
	v_pk_fma_f32 v[66:67], v[208:209], v[114:115], v[66:67] op_sel:[0,1,0] op_sel_hi:[1,1,1]
	v_pk_fma_f32 v[68:69], v[210:211], v[114:115], v[68:69] op_sel:[0,1,0] op_sel_hi:[1,1,1]
	v_cvt_pk_f32_fp8_e32 v[212:213], v22
	v_cvt_pk_f32_fp8_sdwa v[214:215], v22 src0_sel:WORD_1
	v_pk_fma_f32 v[70:71], v[212:213], v[114:115], v[70:71] op_sel:[0,1,0] op_sel_hi:[1,1,1]
	v_pk_fma_f32 v[72:73], v[214:215], v[114:115], v[72:73] op_sel:[0,1,0] op_sel_hi:[1,1,1]
	v_cvt_pk_f32_fp8_e32 v[216:217], v23
	v_cvt_pk_f32_fp8_sdwa v[218:219], v23 src0_sel:WORD_1
	v_pk_fma_f32 v[74:75], v[216:217], v[114:115], v[74:75] op_sel:[0,1,0] op_sel_hi:[1,1,1]
	v_pk_fma_f32 v[76:77], v[218:219], v[114:115], v[76:77] op_sel:[0,1,0] op_sel_hi:[1,1,1]
	s_waitcnt vmcnt(9)
; __device__ __forceinline__ void attn_phase(const Args& a, unsigned char* lds, int lane, int wave) {
;     ...
; #pragma unroll
;             for (int i = 0; i < 8; ++i) { float vf[16]; unpack16_fp8(vv[i], vf);
; #pragma unroll
;                 for (int d = 0; d < 16; ++d) o[d] += p[i] * vf[d]; }
	v_cvt_pk_f32_fp8_e32 v[204:205], v24
	v_cvt_pk_f32_fp8_sdwa v[206:207], v24 src0_sel:WORD_1
	v_pk_fma_f32 v[62:63], v[204:205], v[116:117], v[62:63] op_sel_hi:[1,0,1]
	v_pk_fma_f32 v[64:65], v[206:207], v[116:117], v[64:65] op_sel_hi:[1,0,1]
	v_cvt_pk_f32_fp8_e32 v[208:209], v25
	v_cvt_pk_f32_fp8_sdwa v[210:211], v25 src0_sel:WORD_1
	v_pk_fma_f32 v[66:67], v[208:209], v[116:117], v[66:67] op_sel_hi:[1,0,1]
	v_pk_fma_f32 v[68:69], v[210:211], v[116:117], v[68:69] op_sel_hi:[1,0,1]
	v_cvt_pk_f32_fp8_e32 v[212:213], v26
	v_cvt_pk_f32_fp8_sdwa v[214:215], v26 src0_sel:WORD_1
	v_pk_fma_f32 v[70:71], v[212:213], v[116:117], v[70:71] op_sel_hi:[1,0,1]
	v_pk_fma_f32 v[72:73], v[214:215], v[116:117], v[72:73] op_sel_hi:[1,0,1]
	v_cvt_pk_f32_fp8_e32 v[216:217], v27
	v_cvt_pk_f32_fp8_sdwa v[218:219], v27 src0_sel:WORD_1
	v_pk_fma_f32 v[74:75], v[216:217], v[116:117], v[74:75] op_sel_hi:[1,0,1]
	v_pk_fma_f32 v[76:77], v[218:219], v[116:117], v[76:77] op_sel_hi:[1,0,1]
	s_waitcnt vmcnt(8)
	v_cvt_pk_f32_fp8_e32 v[204:205], v28
	v_cvt_pk_f32_fp8_sdwa v[206:207], v28 src0_sel:WORD_1
	v_pk_fma_f32 v[62:63], v[204:205], v[116:117], v[62:63] op_sel:[0,1,0] op_sel_hi:[1,1,1]
	v_pk_fma_f32 v[64:65], v[206:207], v[116:117], v[64:65] op_sel:[0,1,0] op_sel_hi:[1,1,1]
	v_cvt_pk_f32_fp8_e32 v[208:209], v29
	v_cvt_pk_f32_fp8_sdwa v[210:211], v29 src0_sel:WORD_1
	v_pk_fma_f32 v[66:67], v[208:209], v[116:117], v[66:67] op_sel:[0,1,0] op_sel_hi:[1,1,1]
	v_pk_fma_f32 v[68:69], v[210:211], v[116:117], v[68:69] op_sel:[0,1,0] op_sel_hi:[1,1,1]
	v_cvt_pk_f32_fp8_e32 v[212:213], v30
	v_cvt_pk_f32_fp8_sdwa v[214:215], v30 src0_sel:WORD_1
	v_pk_fma_f32 v[70:71], v[212:213], v[116:117], v[70:71] op_sel:[0,1,0] op_sel_hi:[1,1,1]
	v_pk_fma_f32 v[72:73], v[214:215], v[116:117], v[72:73] op_sel:[0,1,0] op_sel_hi:[1,1,1]
	v_cvt_pk_f32_fp8_e32 v[216:217], v31
	v_cvt_pk_f32_fp8_sdwa v[218:219], v31 src0_sel:WORD_1
	v_pk_fma_f32 v[74:75], v[216:217], v[116:117], v[74:75] op_sel:[0,1,0] op_sel_hi:[1,1,1]
	v_pk_fma_f32 v[76:77], v[218:219], v[116:117], v[76:77] op_sel:[0,1,0] op_sel_hi:[1,1,1]
	s_waitcnt vmcnt(7)
	v_cvt_pk_f32_fp8_e32 v[204:205], v32
	v_cvt_pk_f32_fp8_sdwa v[206:207], v32 src0_sel:WORD_1
	v_pk_fma_f32 v[62:63], v[204:205], v[118:119], v[62:63] op_sel_hi:[1,0,1]
	v_pk_fma_f32 v[64:65], v[206:207], v[118:119], v[64:65] op_sel_hi:[1,0,1]
	v_cvt_pk_f32_fp8_e32 v[208:209], v33
	v_cvt_pk_f32_fp8_sdwa v[210:211], v33 src0_sel:WORD_1
	v_pk_fma_f32 v[66:67], v[208:209], v[118:119], v[66:67] op_sel_hi:[1,0,1]
	v_pk_fma_f32 v[68:69], v[210:211], v[118:119], v[68:69] op_sel_hi:[1,0,1]
	v_cvt_pk_f32_fp8_e32 v[212:213], v34
	v_cvt_pk_f32_fp8_sdwa v[214:215], v34 src0_sel:WORD_1
	v_pk_fma_f32 v[70:71], v[212:213], v[118:119], v[70:71] op_sel_hi:[1,0,1]
	v_pk_fma_f32 v[72:73], v[214:215], v[118:119], v[72:73] op_sel_hi:[1,0,1]
	v_cvt_pk_f32_fp8_e32 v[216:217], v35
	v_cvt_pk_f32_fp8_sdwa v[218:219], v35 src0_sel:WORD_1
	v_pk_fma_f32 v[74:75], v[216:217], v[118:119], v[74:75] op_sel_hi:[1,0,1]
	v_pk_fma_f32 v[76:77], v[218:219], v[118:119], v[76:77] op_sel_hi:[1,0,1]
	s_waitcnt vmcnt(6)
	v_cvt_pk_f32_fp8_e32 v[204:205], v36
	v_cvt_pk_f32_fp8_sdwa v[206:207], v36 src0_sel:WORD_1
	v_pk_fma_f32 v[62:63], v[204:205], v[118:119], v[62:63] op_sel:[0,1,0] op_sel_hi:[1,1,1]
	v_pk_fma_f32 v[64:65], v[206:207], v[118:119], v[64:65] op_sel:[0,1,0] op_sel_hi:[1,1,1]
	v_cvt_pk_f32_fp8_e32 v[208:209], v37
	v_cvt_pk_f32_fp8_sdwa v[210:211], v37 src0_sel:WORD_1
	v_pk_fma_f32 v[66:67], v[208:209], v[118:119], v[66:67] op_sel:[0,1,0] op_sel_hi:[1,1,1]
	v_pk_fma_f32 v[68:69], v[210:211], v[118:119], v[68:69] op_sel:[0,1,0] op_sel_hi:[1,1,1]
	v_cvt_pk_f32_fp8_e32 v[212:213], v38
	v_cvt_pk_f32_fp8_sdwa v[214:215], v38 src0_sel:WORD_1
	v_pk_fma_f32 v[70:71], v[212:213], v[118:119], v[70:71] op_sel:[0,1,0] op_sel_hi:[1,1,1]
	v_pk_fma_f32 v[72:73], v[214:215], v[118:119], v[72:73] op_sel:[0,1,0] op_sel_hi:[1,1,1]
	v_cvt_pk_f32_fp8_e32 v[216:217], v39
	v_cvt_pk_f32_fp8_sdwa v[218:219], v39 src0_sel:WORD_1
	v_pk_fma_f32 v[74:75], v[216:217], v[118:119], v[74:75] op_sel:[0,1,0] op_sel_hi:[1,1,1]
	v_pk_fma_f32 v[76:77], v[218:219], v[118:119], v[76:77] op_sel:[0,1,0] op_sel_hi:[1,1,1]
	s_waitcnt vmcnt(5)
	v_cvt_pk_f32_fp8_e32 v[204:205], v40
	v_cvt_pk_f32_fp8_sdwa v[206:207], v40 src0_sel:WORD_1
	v_pk_fma_f32 v[62:63], v[204:205], v[120:121], v[62:63] op_sel_hi:[1,0,1]
	v_pk_fma_f32 v[64:65], v[206:207], v[120:121], v[64:65] op_sel_hi:[1,0,1]
	v_cvt_pk_f32_fp8_e32 v[208:209], v41
	v_cvt_pk_f32_fp8_sdwa v[210:211], v41 src0_sel:WORD_1
	v_pk_fma_f32 v[66:67], v[208:209], v[120:121], v[66:67] op_sel_hi:[1,0,1]
	v_pk_fma_f32 v[68:69], v[210:211], v[120:121], v[68:69] op_sel_hi:[1,0,1]
	v_cvt_pk_f32_fp8_e32 v[212:213], v42
	v_cvt_pk_f32_fp8_sdwa v[214:215], v42 src0_sel:WORD_1
	v_pk_fma_f32 v[70:71], v[212:213], v[120:121], v[70:71] op_sel_hi:[1,0,1]
	v_pk_fma_f32 v[72:73], v[214:215], v[120:121], v[72:73] op_sel_hi:[1,0,1]
	v_cvt_pk_f32_fp8_e32 v[216:217], v43
	v_cvt_pk_f32_fp8_sdwa v[218:219], v43 src0_sel:WORD_1
	v_pk_fma_f32 v[74:75], v[216:217], v[120:121], v[74:75] op_sel_hi:[1,0,1]
	v_pk_fma_f32 v[76:77], v[218:219], v[120:121], v[76:77] op_sel_hi:[1,0,1]
	s_waitcnt vmcnt(4)
; __device__ __forceinline__ u32x4 pack8(const float* v) { u32x4 w; w.x = pk2(v[0], v[1]); w.y = pk2(v[2], v[3]); w.z = pk2(v[4], v[5]); w.w = pk2(v[6], v[7]); return w; }
; __device__ __forceinline__ void attn_phase(const Args& a, unsigned char* lds, int lane, int wave) {
;     ...
; #pragma unroll
;             for (int i = 0; i < 8; ++i) { float vf[16]; unpack16_fp8(vv[i], vf);
; #pragma unroll
;                 for (int d = 0; d < 16; ++d) o[d] += p[i] * vf[d]; }
;             mx = mn;
;         }
;         const float il = 1.f / l;
; #pragma unroll
;         for (int d = 0; d < 16; ++d) o[d] *= il;
;         *(u32x4*)qp = pack8(o); *(u32x4*)(qp + 8) = pack8(o + 8);
;     }
	v_cvt_pk_f32_fp8_e32 v[204:205], v44
	v_cvt_pk_f32_fp8_sdwa v[206:207], v44 src0_sel:WORD_1
	v_pk_fma_f32 v[62:63], v[204:205], v[120:121], v[62:63] op_sel:[0,1,0] op_sel_hi:[1,1,1]
	v_pk_fma_f32 v[64:65], v[206:207], v[120:121], v[64:65] op_sel:[0,1,0] op_sel_hi:[1,1,1]
	v_cvt_pk_f32_fp8_e32 v[208:209], v45
	v_cvt_pk_f32_fp8_sdwa v[210:211], v45 src0_sel:WORD_1
	v_pk_fma_f32 v[66:67], v[208:209], v[120:121], v[66:67] op_sel:[0,1,0] op_sel_hi:[1,1,1]
	v_pk_fma_f32 v[68:69], v[210:211], v[120:121], v[68:69] op_sel:[0,1,0] op_sel_hi:[1,1,1]
	v_cvt_pk_f32_fp8_e32 v[212:213], v46
	v_cvt_pk_f32_fp8_sdwa v[214:215], v46 src0_sel:WORD_1
	v_pk_fma_f32 v[70:71], v[212:213], v[120:121], v[70:71] op_sel:[0,1,0] op_sel_hi:[1,1,1]
	v_pk_fma_f32 v[72:73], v[214:215], v[120:121], v[72:73] op_sel:[0,1,0] op_sel_hi:[1,1,1]
	v_cvt_pk_f32_fp8_e32 v[216:217], v47
	v_cvt_pk_f32_fp8_sdwa v[218:219], v47 src0_sel:WORD_1
	v_pk_fma_f32 v[74:75], v[216:217], v[120:121], v[74:75] op_sel:[0,1,0] op_sel_hi:[1,1,1]
	v_pk_fma_f32 v[76:77], v[218:219], v[120:121], v[76:77] op_sel:[0,1,0] op_sel_hi:[1,1,1]
	s_waitcnt vmcnt(3)
	v_cvt_pk_f32_fp8_e32 v[204:205], v48
	v_cvt_pk_f32_fp8_sdwa v[206:207], v48 src0_sel:WORD_1
	v_pk_fma_f32 v[62:63], v[204:205], v[122:123], v[62:63] op_sel_hi:[1,0,1]
	v_pk_fma_f32 v[64:65], v[206:207], v[122:123], v[64:65] op_sel_hi:[1,0,1]
	v_cvt_pk_f32_fp8_e32 v[208:209], v49
	v_cvt_pk_f32_fp8_sdwa v[210:211], v49 src0_sel:WORD_1
	v_pk_fma_f32 v[66:67], v[208:209], v[122:123], v[66:67] op_sel_hi:[1,0,1]
	v_pk_fma_f32 v[68:69], v[210:211], v[122:123], v[68:69] op_sel_hi:[1,0,1]
	v_cvt_pk_f32_fp8_e32 v[212:213], v50
	v_cvt_pk_f32_fp8_sdwa v[214:215], v50 src0_sel:WORD_1
	v_pk_fma_f32 v[70:71], v[212:213], v[122:123], v[70:71] op_sel_hi:[1,0,1]
	v_pk_fma_f32 v[72:73], v[214:215], v[122:123], v[72:73] op_sel_hi:[1,0,1]
	v_cvt_pk_f32_fp8_e32 v[216:217], v51
	v_cvt_pk_f32_fp8_sdwa v[218:219], v51 src0_sel:WORD_1
	v_pk_fma_f32 v[74:75], v[216:217], v[122:123], v[74:75] op_sel_hi:[1,0,1]
	v_pk_fma_f32 v[76:77], v[218:219], v[122:123], v[76:77] op_sel_hi:[1,0,1]
	s_waitcnt vmcnt(2)
	v_cvt_pk_f32_fp8_e32 v[204:205], v52
	v_cvt_pk_f32_fp8_sdwa v[206:207], v52 src0_sel:WORD_1
	v_pk_fma_f32 v[62:63], v[204:205], v[122:123], v[62:63] op_sel:[0,1,0] op_sel_hi:[1,1,1]
	v_pk_fma_f32 v[64:65], v[206:207], v[122:123], v[64:65] op_sel:[0,1,0] op_sel_hi:[1,1,1]
	v_cvt_pk_f32_fp8_e32 v[208:209], v53
	v_cvt_pk_f32_fp8_sdwa v[210:211], v53 src0_sel:WORD_1
	v_pk_fma_f32 v[66:67], v[208:209], v[122:123], v[66:67] op_sel:[0,1,0] op_sel_hi:[1,1,1]
	v_pk_fma_f32 v[68:69], v[210:211], v[122:123], v[68:69] op_sel:[0,1,0] op_sel_hi:[1,1,1]
	v_cvt_pk_f32_fp8_e32 v[212:213], v54
	v_cvt_pk_f32_fp8_sdwa v[214:215], v54 src0_sel:WORD_1
	v_pk_fma_f32 v[70:71], v[212:213], v[122:123], v[70:71] op_sel:[0,1,0] op_sel_hi:[1,1,1]
	v_pk_fma_f32 v[72:73], v[214:215], v[122:123], v[72:73] op_sel:[0,1,0] op_sel_hi:[1,1,1]
	v_cvt_pk_f32_fp8_e32 v[216:217], v55
	v_cvt_pk_f32_fp8_sdwa v[218:219], v55 src0_sel:WORD_1
	v_pk_fma_f32 v[74:75], v[216:217], v[122:123], v[74:75] op_sel:[0,1,0] op_sel_hi:[1,1,1]
	v_pk_fma_f32 v[76:77], v[218:219], v[122:123], v[76:77] op_sel:[0,1,0] op_sel_hi:[1,1,1]
	s_waitcnt vmcnt(1)
	v_cvt_pk_f32_fp8_e32 v[204:205], v196
	v_cvt_pk_f32_fp8_sdwa v[206:207], v196 src0_sel:WORD_1
	v_pk_fma_f32 v[62:63], v[204:205], v[124:125], v[62:63] op_sel_hi:[1,0,1]
	v_pk_fma_f32 v[64:65], v[206:207], v[124:125], v[64:65] op_sel_hi:[1,0,1]
	v_cvt_pk_f32_fp8_e32 v[208:209], v197
	v_cvt_pk_f32_fp8_sdwa v[210:211], v197 src0_sel:WORD_1
	v_pk_fma_f32 v[66:67], v[208:209], v[124:125], v[66:67] op_sel_hi:[1,0,1]
	v_pk_fma_f32 v[68:69], v[210:211], v[124:125], v[68:69] op_sel_hi:[1,0,1]
	v_cvt_pk_f32_fp8_e32 v[212:213], v198
	v_cvt_pk_f32_fp8_sdwa v[214:215], v198 src0_sel:WORD_1
	v_pk_fma_f32 v[70:71], v[212:213], v[124:125], v[70:71] op_sel_hi:[1,0,1]
	v_pk_fma_f32 v[72:73], v[214:215], v[124:125], v[72:73] op_sel_hi:[1,0,1]
	v_cvt_pk_f32_fp8_e32 v[216:217], v199
	v_cvt_pk_f32_fp8_sdwa v[218:219], v199 src0_sel:WORD_1
	v_pk_fma_f32 v[74:75], v[216:217], v[124:125], v[74:75] op_sel_hi:[1,0,1]
	v_pk_fma_f32 v[76:77], v[218:219], v[124:125], v[76:77] op_sel_hi:[1,0,1]
	s_waitcnt vmcnt(0)
	v_cvt_pk_f32_fp8_e32 v[204:205], v200
	v_cvt_pk_f32_fp8_sdwa v[206:207], v200 src0_sel:WORD_1
	v_pk_fma_f32 v[62:63], v[204:205], v[124:125], v[62:63] op_sel:[0,1,0] op_sel_hi:[1,1,1]
	v_pk_fma_f32 v[64:65], v[206:207], v[124:125], v[64:65] op_sel:[0,1,0] op_sel_hi:[1,1,1]
	v_cvt_pk_f32_fp8_e32 v[208:209], v201
	v_cvt_pk_f32_fp8_sdwa v[210:211], v201 src0_sel:WORD_1
	v_pk_fma_f32 v[66:67], v[208:209], v[124:125], v[66:67] op_sel:[0,1,0] op_sel_hi:[1,1,1]
	v_pk_fma_f32 v[68:69], v[210:211], v[124:125], v[68:69] op_sel:[0,1,0] op_sel_hi:[1,1,1]
	v_cvt_pk_f32_fp8_e32 v[212:213], v202
	v_cvt_pk_f32_fp8_sdwa v[214:215], v202 src0_sel:WORD_1
	v_pk_fma_f32 v[70:71], v[212:213], v[124:125], v[70:71] op_sel:[0,1,0] op_sel_hi:[1,1,1]
	v_pk_fma_f32 v[72:73], v[214:215], v[124:125], v[72:73] op_sel:[0,1,0] op_sel_hi:[1,1,1]
	v_cvt_pk_f32_fp8_e32 v[216:217], v203
	v_cvt_pk_f32_fp8_sdwa v[218:219], v203 src0_sel:WORD_1
	v_pk_fma_f32 v[74:75], v[216:217], v[124:125], v[74:75] op_sel:[0,1,0] op_sel_hi:[1,1,1]
	v_pk_fma_f32 v[76:77], v[218:219], v[124:125], v[76:77] op_sel:[0,1,0] op_sel_hi:[1,1,1]
	v_div_scale_f32 v0, s[0:1], v108, v108, 1.0
	v_rcp_f32_e32 v1, v0
	v_div_scale_f32 v2, vcc, 1.0, v108, 1.0
	s_add_i32 s2, s2, s28
	v_fma_f32 v3, -v0, v1, 1.0
	v_fmac_f32_e32 v1, v3, v1
	v_mul_f32_e32 v3, v2, v1
	v_fma_f32 v4, -v0, v3, v2
	v_fmac_f32_e32 v3, v4, v1
	v_fma_f32 v0, -v0, v3, v2
	v_div_fmas_f32 v0, v0, v1, v3
	v_div_fixup_f32 v0, v0, v108, 1.0
	v_pk_mul_f32 v[62:63], v[62:63], v[0:1] op_sel_hi:[1,0]
	v_pk_mul_f32 v[64:65], v[64:65], v[0:1] op_sel_hi:[1,0]
	v_pk_mul_f32 v[66:67], v[66:67], v[0:1] op_sel_hi:[1,0]
	v_pk_mul_f32 v[68:69], v[68:69], v[0:1] op_sel_hi:[1,0]
	v_pk_mul_f32 v[70:71], v[70:71], v[0:1] op_sel_hi:[1,0]
	v_pk_mul_f32 v[72:73], v[72:73], v[0:1] op_sel_hi:[1,0]
	v_pk_mul_f32 v[74:75], v[74:75], v[0:1] op_sel_hi:[1,0]
	v_pk_mul_f32 v[76:77], v[76:77], v[0:1] op_sel_hi:[1,0]
	v_cvt_pk_bf16_f32 v4, v62, v63
	v_cvt_pk_bf16_f32 v5, v64, v65
	v_cvt_pk_bf16_f32 v6, v66, v67
	v_cvt_pk_bf16_f32 v7, v68, v69
	v_cvt_pk_bf16_f32 v8, v70, v71
	v_cvt_pk_bf16_f32 v9, v72, v73
	v_cvt_pk_bf16_f32 v10, v74, v75
	v_cvt_pk_bf16_f32 v11, v76, v77
	global_store_dwordx4 v[60:61], v[4:7], off
	global_store_dwordx4 v[60:61], v[8:11], off offset:16
	s_cmpk_gt_i32 s2, 0x41ff
	s_cbranch_scc0 .Lat_q

;     __device__ __forceinline__ void operator()(const f32x4 (&acc)[2][2][4][2], const pg8::Unit& u, int wr, int wc, int fr, int fq) const {
;     ...
;                 const int row = u.pm * 256 + ai * 128 + wr * 64 + m * 16 + fr;
;                 const int b = row < TP ? 0 : 1 + ((row - TP) >> 6);
;                 const float* sp = (row < TP ? srcP + (size_t)row * DM : srcS + (size_t)(row - TP) * DM) + col0;
;                 const float* gp = gate + (size_t)b * MODW + col0; float* dp = dst + (size_t)row * DM + col0;
; #pragma unroll
;                 for (int bj = 0; bj < 2; ++bj)
; #pragma unroll
;                     for (int n = 0; n < 2; ++n) { const f32x4 x = *(const f32x4*)(sp + bj * 128 + 4 * n), gg = *(const f32x4*)(gp + bj * 128 + 4 * n);
;                         *(f32x4*)(dp + bj * 128 + 4 * n) = x + gg * acc[ai][bj][m][n]; }
.LBB0_2005:
	v_lshl_add_u32 v152, s50, 8, v129
	v_cmp_gt_i32_e32 vcc, s34, v152
	v_cmp_lt_i32_e64 s[4:5], s48, v152
	v_add_u32_e32 v140, 0xffffc000, v152
	s_and_saveexec_b64 s[20:21], s[4:5]
	s_xor_b64 s[4:5], exec, s[20:21]
	v_lshlrev_b64 v[150:151], 13, v[140:141]
	v_mov_b32_e32 v153, v141
	v_lshl_add_u64 v[156:157], s[46:47], 0, v[150:151]
	v_lshlrev_b64 v[154:155], 13, v[152:153]
	s_andn2_saveexec_b64 s[4:5], s[4:5]
	v_ashrrev_i32_e32 v153, 31, v152
	v_lshlrev_b64 v[154:155], 13, v[152:153]
	v_lshl_add_u64 v[156:157], s[44:45], 0, v[154:155]
	s_or_b64 exec, exec, s[4:5]
	v_lshl_or_b32 v150, s18, 8, v158
	v_ashrrev_i32_e32 v151, 31, v150
	v_lshrrev_b32_e32 v140, 6, v140
	v_add_u32_e32 v140, 1, v140
	v_lshlrev_b64 v[150:151], 2, v[150:151]
	v_cndmask_b32_e64 v140, v140, 0, vcc
	v_lshl_add_u64 v[170:171], v[156:157], 0, v[150:151]
	v_mov_b64_e32 v[156:157], s[6:7]
	v_mad_u64_u32 v[156:157], s[4:5], v140, s43, v[156:157]
	v_lshl_add_u64 v[172:173], v[156:157], 0, v[150:151]
	global_load_dwordx4 v[176:179], v[170:171], off
	global_load_dwordx4 v[180:183], v[172:173], off
	global_load_dwordx4 v[184:187], v[170:171], off offset:16
	global_load_dwordx4 v[188:191], v[172:173], off offset:16
	global_load_dwordx4 v[192:195], v[170:171], off offset:512
	global_load_dwordx4 v[196:199], v[172:173], off offset:512
	global_load_dwordx4 v[200:203], v[170:171], off offset:528
	global_load_dwordx4 v[204:207], v[172:173], off offset:528
	v_lshl_add_u64 v[154:155], s[60:61], 0, v[154:155]
	v_lshl_add_u64 v[174:175], v[154:155], 0, v[150:151]
	v_add_u32_e32 v140, 0xffffc010, v152
	s_waitcnt vmcnt(0)
	v_pk_fma_f32 v[126:127], v[126:127], v[182:183], v[178:179]
	v_pk_fma_f32 v[124:125], v[124:125], v[180:181], v[176:177]
	global_store_dwordx4 v[174:175], v[124:127], off
	s_nop 1
	s_nop 0
	v_pk_fma_f32 v[122:123], v[122:123], v[190:191], v[186:187]
	v_pk_fma_f32 v[120:121], v[120:121], v[188:189], v[184:185]
	global_store_dwordx4 v[174:175], v[120:123], off offset:16
	s_nop 1
	s_nop 0
	v_pk_fma_f32 v[118:119], v[118:119], v[198:199], v[194:195]
	v_pk_fma_f32 v[116:117], v[116:117], v[196:197], v[192:193]
	global_store_dwordx4 v[174:175], v[116:119], off offset:512
	s_nop 1
	v_or_b32_e32 v116, 16, v152
	v_cmp_gt_i32_e32 vcc, s34, v116
	v_cmp_lt_i32_e64 s[4:5], s48, v116
	s_nop 0
	v_pk_fma_f32 v[114:115], v[114:115], v[206:207], v[202:203]
	v_pk_fma_f32 v[112:113], v[112:113], v[204:205], v[200:201]
	global_store_dwordx4 v[174:175], v[112:115], off offset:528
	s_and_saveexec_b64 s[20:21], s[4:5]
	s_xor_b64 s[4:5], exec, s[20:21]
	v_lshlrev_b64 v[112:113], 13, v[140:141]
	v_mov_b32_e32 v117, v141
	v_lshl_add_u64 v[114:115], s[46:47], 0, v[112:113]
	v_lshlrev_b64 v[112:113], 13, v[116:117]
	s_andn2_saveexec_b64 s[4:5], s[4:5]
	v_ashrrev_i32_e32 v117, 31, v116
	v_lshlrev_b64 v[112:113], 13, v[116:117]
	v_lshl_add_u64 v[114:115], s[44:45], 0, v[112:113]
	s_or_b64 exec, exec, s[4:5]
	v_lshrrev_b32_e32 v116, 6, v140
	v_add_u32_e32 v116, 1, v116
	v_cndmask_b32_e64 v116, v116, 0, vcc
	v_lshl_add_u64 v[122:123], v[114:115], 0, v[150:151]
	v_mov_b64_e32 v[114:115], s[6:7]
	v_mad_u64_u32 v[114:115], s[4:5], v116, s43, v[114:115]
	v_lshl_add_u64 v[124:125], v[114:115], 0, v[150:151]
	global_load_dwordx4 v[176:179], v[122:123], off
	global_load_dwordx4 v[180:183], v[124:125], off
	global_load_dwordx4 v[184:187], v[122:123], off offset:16
	global_load_dwordx4 v[188:191], v[124:125], off offset:16
	global_load_dwordx4 v[192:195], v[122:123], off offset:512
	global_load_dwordx4 v[196:199], v[124:125], off offset:512
	global_load_dwordx4 v[200:203], v[122:123], off offset:528
	global_load_dwordx4 v[204:207], v[124:125], off offset:528
	v_lshl_add_u64 v[112:113], s[60:61], 0, v[112:113]
	v_lshl_add_u64 v[126:127], v[112:113], 0, v[150:151]
	v_add_u32_e32 v140, 0xffffc020, v152
	s_waitcnt vmcnt(0)
	v_pk_fma_f32 v[110:111], v[110:111], v[182:183], v[178:179]
	v_pk_fma_f32 v[108:109], v[108:109], v[180:181], v[176:177]
	global_store_dwordx4 v[126:127], v[108:111], off
	s_nop 1
	s_nop 0
	v_pk_fma_f32 v[106:107], v[106:107], v[190:191], v[186:187]
	v_pk_fma_f32 v[104:105], v[104:105], v[188:189], v[184:185]
	global_store_dwordx4 v[126:127], v[104:107], off offset:16
	s_nop 1
	s_nop 0
	v_pk_fma_f32 v[102:103], v[102:103], v[198:199], v[194:195]
	v_pk_fma_f32 v[100:101], v[100:101], v[196:197], v[192:193]
	global_store_dwordx4 v[126:127], v[100:103], off offset:512
	s_nop 1
	v_or_b32_e32 v100, 32, v152
	v_cmp_gt_i32_e32 vcc, s34, v100
	v_cmp_lt_i32_e64 s[4:5], s48, v100
	s_nop 0
	v_pk_fma_f32 v[98:99], v[98:99], v[206:207], v[202:203]
	v_pk_fma_f32 v[96:97], v[96:97], v[204:205], v[200:201]
	global_store_dwordx4 v[126:127], v[96:99], off offset:528
	s_and_saveexec_b64 s[20:21], s[4:5]
	s_xor_b64 s[4:5], exec, s[20:21]
	v_lshlrev_b64 v[96:97], 13, v[140:141]
	v_mov_b32_e32 v101, v141
	v_lshl_add_u64 v[98:99], s[46:47], 0, v[96:97]
	v_lshlrev_b64 v[96:97], 13, v[100:101]
	s_andn2_saveexec_b64 s[4:5], s[4:5]
	v_ashrrev_i32_e32 v101, 31, v100
	v_lshlrev_b64 v[96:97], 13, v[100:101]
	v_lshl_add_u64 v[98:99], s[44:45], 0, v[96:97]
	s_or_b64 exec, exec, s[4:5]
	v_lshrrev_b32_e32 v100, 6, v140
	v_add_u32_e32 v100, 1, v100
	v_cndmask_b32_e64 v100, v100, 0, vcc
	v_lshl_add_u64 v[106:107], v[98:99], 0, v[150:151]
	v_mov_b64_e32 v[98:99], s[6:7]
	v_mad_u64_u32 v[98:99], s[4:5], v100, s43, v[98:99]
	v_lshl_add_u64 v[108:109], v[98:99], 0, v[150:151]
	global_load_dwordx4 v[176:179], v[106:107], off
	global_load_dwordx4 v[180:183], v[108:109], off
	global_load_dwordx4 v[184:187], v[106:107], off offset:16
	global_load_dwordx4 v[188:191], v[108:109], off offset:16
	global_load_dwordx4 v[192:195], v[106:107], off offset:512
	global_load_dwordx4 v[196:199], v[108:109], off offset:512
	global_load_dwordx4 v[200:203], v[106:107], off offset:528
	global_load_dwordx4 v[204:207], v[108:109], off offset:528
	v_lshl_add_u64 v[96:97], s[60:61], 0, v[96:97]
	v_lshl_add_u64 v[110:111], v[96:97], 0, v[150:151]
	v_add_u32_e32 v140, 0xffffc030, v152
	s_waitcnt vmcnt(0)
;     __device__ __forceinline__ void operator()(const f32x4 (&acc)[2][2][4][2], const pg8::Unit& u, int wr, int wc, int fr, int fq) const {
;     ...
;             for (int m = 0; m < 4; ++m) {
;                 const int row = u.pm * 256 + ai * 128 + wr * 64 + m * 16 + fr;
;                 const int b = row < TP ? 0 : 1 + ((row - TP) >> 6);
;                 const float* sp = (row < TP ? srcP + (size_t)row * DM : srcS + (size_t)(row - TP) * DM) + col0;
;                 const float* gp = gate + (size_t)b * MODW + col0; float* dp = dst + (size_t)row * DM + col0;
; #pragma unroll
;                 for (int bj = 0; bj < 2; ++bj)
; #pragma unroll
;                     for (int n = 0; n < 2; ++n) { const f32x4 x = *(const f32x4*)(sp + bj * 128 + 4 * n), gg = *(const f32x4*)(gp + bj * 128 + 4 * n);
;                         *(f32x4*)(dp + bj * 128 + 4 * n) = x + gg * acc[ai][bj][m][n]; }
	v_pk_fma_f32 v[94:95], v[94:95], v[182:183], v[178:179]
	v_pk_fma_f32 v[92:93], v[92:93], v[180:181], v[176:177]
	global_store_dwordx4 v[110:111], v[92:95], off
	s_nop 1
	s_nop 0
	v_pk_fma_f32 v[90:91], v[90:91], v[190:191], v[186:187]
	v_pk_fma_f32 v[88:89], v[88:89], v[188:189], v[184:185]
	global_store_dwordx4 v[110:111], v[88:91], off offset:16
	s_nop 1
	s_nop 0
	v_pk_fma_f32 v[86:87], v[86:87], v[198:199], v[194:195]
	v_pk_fma_f32 v[84:85], v[84:85], v[196:197], v[192:193]
	global_store_dwordx4 v[110:111], v[84:87], off offset:512
	s_nop 1
	v_or_b32_e32 v84, 48, v152
	v_cmp_gt_i32_e32 vcc, s34, v84
	v_cmp_lt_i32_e64 s[4:5], s48, v84
	s_nop 0
	v_pk_fma_f32 v[82:83], v[82:83], v[206:207], v[202:203]
	v_pk_fma_f32 v[80:81], v[80:81], v[204:205], v[200:201]
	global_store_dwordx4 v[110:111], v[80:83], off offset:528
	s_and_saveexec_b64 s[20:21], s[4:5]
	s_xor_b64 s[4:5], exec, s[20:21]
	v_lshlrev_b64 v[80:81], 13, v[140:141]
	v_mov_b32_e32 v85, v141
	v_lshl_add_u64 v[82:83], s[46:47], 0, v[80:81]
	v_lshlrev_b64 v[80:81], 13, v[84:85]
	s_andn2_saveexec_b64 s[4:5], s[4:5]
	v_ashrrev_i32_e32 v85, 31, v84
	v_lshlrev_b64 v[80:81], 13, v[84:85]
	v_lshl_add_u64 v[82:83], s[44:45], 0, v[80:81]
	s_or_b64 exec, exec, s[4:5]
	v_lshrrev_b32_e32 v84, 6, v140
	v_add_u32_e32 v84, 1, v84
	v_cndmask_b32_e64 v84, v84, 0, vcc
	v_lshl_add_u64 v[90:91], v[82:83], 0, v[150:151]
	v_mov_b64_e32 v[82:83], s[6:7]
	v_mad_u64_u32 v[82:83], s[4:5], v84, s43, v[82:83]
	v_lshl_add_u64 v[92:93], v[82:83], 0, v[150:151]
	global_load_dwordx4 v[176:179], v[90:91], off
	global_load_dwordx4 v[180:183], v[92:93], off
	global_load_dwordx4 v[184:187], v[90:91], off offset:16
	global_load_dwordx4 v[188:191], v[92:93], off offset:16
	global_load_dwordx4 v[192:195], v[90:91], off offset:512
	global_load_dwordx4 v[196:199], v[92:93], off offset:512
	global_load_dwordx4 v[200:203], v[90:91], off offset:528
	global_load_dwordx4 v[204:207], v[92:93], off offset:528
	v_lshl_add_u64 v[80:81], s[60:61], 0, v[80:81]
	v_lshl_add_u64 v[94:95], v[80:81], 0, v[150:151]
	v_add_u32_e32 v140, 0xffffc080, v152
	s_waitcnt vmcnt(0)
	v_pk_fma_f32 v[78:79], v[78:79], v[182:183], v[178:179]
	v_pk_fma_f32 v[76:77], v[76:77], v[180:181], v[176:177]
	global_store_dwordx4 v[94:95], v[76:79], off
	s_nop 1
	s_nop 0
	v_pk_fma_f32 v[74:75], v[74:75], v[190:191], v[186:187]
	v_pk_fma_f32 v[72:73], v[72:73], v[188:189], v[184:185]
	global_store_dwordx4 v[94:95], v[72:75], off offset:16
	s_nop 1
	s_nop 0
	v_pk_fma_f32 v[70:71], v[70:71], v[198:199], v[194:195]
	v_pk_fma_f32 v[68:69], v[68:69], v[196:197], v[192:193]
	global_store_dwordx4 v[94:95], v[68:71], off offset:512
	s_nop 1
	v_add_u32_e32 v68, 0x80, v152
	v_cmp_gt_i32_e32 vcc, s34, v68
	v_cmp_lt_i32_e64 s[4:5], s48, v68
	s_nop 0
	v_pk_fma_f32 v[66:67], v[66:67], v[206:207], v[202:203]
	v_pk_fma_f32 v[64:65], v[64:65], v[204:205], v[200:201]
	global_store_dwordx4 v[94:95], v[64:67], off offset:528
	s_and_saveexec_b64 s[20:21], s[4:5]
	s_xor_b64 s[4:5], exec, s[20:21]
	v_lshlrev_b64 v[64:65], 13, v[140:141]
	v_mov_b32_e32 v69, v141
	v_lshl_add_u64 v[66:67], s[46:47], 0, v[64:65]
	v_lshlrev_b64 v[64:65], 13, v[68:69]
	s_andn2_saveexec_b64 s[4:5], s[4:5]
	v_ashrrev_i32_e32 v69, 31, v68
	v_lshlrev_b64 v[64:65], 13, v[68:69]
	v_lshl_add_u64 v[66:67], s[44:45], 0, v[64:65]
	s_or_b64 exec, exec, s[4:5]
	v_lshrrev_b32_e32 v68, 6, v140
	v_add_u32_e32 v68, 1, v68
	v_cndmask_b32_e64 v68, v68, 0, vcc
	v_lshl_add_u64 v[74:75], v[66:67], 0, v[150:151]
	v_mov_b64_e32 v[66:67], s[6:7]
	v_mad_u64_u32 v[66:67], s[4:5], v68, s43, v[66:67]
	v_lshl_add_u64 v[76:77], v[66:67], 0, v[150:151]
	global_load_dwordx4 v[176:179], v[74:75], off
	global_load_dwordx4 v[180:183], v[76:77], off
	global_load_dwordx4 v[184:187], v[74:75], off offset:16
	global_load_dwordx4 v[188:191], v[76:77], off offset:16
	global_load_dwordx4 v[192:195], v[74:75], off offset:512
	global_load_dwordx4 v[196:199], v[76:77], off offset:512
	global_load_dwordx4 v[200:203], v[74:75], off offset:528
	global_load_dwordx4 v[204:207], v[76:77], off offset:528
	v_lshl_add_u64 v[64:65], s[60:61], 0, v[64:65]
	v_lshl_add_u64 v[78:79], v[64:65], 0, v[150:151]
	v_add_u32_e32 v140, 0xffffc090, v152
	s_waitcnt vmcnt(0)
	v_pk_fma_f32 v[62:63], v[62:63], v[182:183], v[178:179]
	v_pk_fma_f32 v[60:61], v[60:61], v[180:181], v[176:177]
	global_store_dwordx4 v[78:79], v[60:63], off
	s_nop 1
	s_nop 0
	v_pk_fma_f32 v[58:59], v[58:59], v[190:191], v[186:187]
	v_pk_fma_f32 v[56:57], v[56:57], v[188:189], v[184:185]
	global_store_dwordx4 v[78:79], v[56:59], off offset:16
	s_nop 1
	s_nop 0
	v_pk_fma_f32 v[54:55], v[54:55], v[198:199], v[194:195]
	v_pk_fma_f32 v[52:53], v[52:53], v[196:197], v[192:193]
	global_store_dwordx4 v[78:79], v[52:55], off offset:512
	s_nop 1
	v_add_u32_e32 v52, 0x90, v152
	v_cmp_gt_i32_e32 vcc, s34, v52
	v_cmp_lt_i32_e64 s[4:5], s48, v52
	s_nop 0
	v_pk_fma_f32 v[50:51], v[50:51], v[206:207], v[202:203]
	v_pk_fma_f32 v[48:49], v[48:49], v[204:205], v[200:201]
	global_store_dwordx4 v[78:79], v[48:51], off offset:528
	s_and_saveexec_b64 s[20:21], s[4:5]
	s_xor_b64 s[4:5], exec, s[20:21]
	v_lshlrev_b64 v[48:49], 13, v[140:141]
	v_mov_b32_e32 v53, v141
	v_lshl_add_u64 v[50:51], s[46:47], 0, v[48:49]
	v_lshlrev_b64 v[48:49], 13, v[52:53]
	s_andn2_saveexec_b64 s[4:5], s[4:5]
	v_ashrrev_i32_e32 v53, 31, v52
	v_lshlrev_b64 v[48:49], 13, v[52:53]
	v_lshl_add_u64 v[50:51], s[44:45], 0, v[48:49]
	s_or_b64 exec, exec, s[4:5]
	v_lshrrev_b32_e32 v52, 6, v140
	v_add_u32_e32 v52, 1, v52
	v_cndmask_b32_e64 v52, v52, 0, vcc
	v_lshl_add_u64 v[58:59], v[50:51], 0, v[150:151]
	v_mov_b64_e32 v[50:51], s[6:7]
	v_mad_u64_u32 v[50:51], s[4:5], v52, s43, v[50:51]
	v_lshl_add_u64 v[60:61], v[50:51], 0, v[150:151]
	global_load_dwordx4 v[176:179], v[58:59], off
	global_load_dwordx4 v[180:183], v[60:61], off
	global_load_dwordx4 v[184:187], v[58:59], off offset:16
	global_load_dwordx4 v[188:191], v[60:61], off offset:16
	global_load_dwordx4 v[192:195], v[58:59], off offset:512
	global_load_dwordx4 v[196:199], v[60:61], off offset:512
	global_load_dwordx4 v[200:203], v[58:59], off offset:528
	global_load_dwordx4 v[204:207], v[60:61], off offset:528
	v_lshl_add_u64 v[48:49], s[60:61], 0, v[48:49]
	v_lshl_add_u64 v[62:63], v[48:49], 0, v[150:151]
	v_add_u32_e32 v140, 0xffffc0a0, v152
	s_waitcnt vmcnt(0)
;     __device__ __forceinline__ void operator()(const f32x4 (&acc)[2][2][4][2], const pg8::Unit& u, int wr, int wc, int fr, int fq) const {
;     ...
;             for (int m = 0; m < 4; ++m) {
;                 const int row = u.pm * 256 + ai * 128 + wr * 64 + m * 16 + fr;
;                 const int b = row < TP ? 0 : 1 + ((row - TP) >> 6);
;                 const float* sp = (row < TP ? srcP + (size_t)row * DM : srcS + (size_t)(row - TP) * DM) + col0;
;                 const float* gp = gate + (size_t)b * MODW + col0; float* dp = dst + (size_t)row * DM + col0;
; #pragma unroll
;                 for (int bj = 0; bj < 2; ++bj)
; #pragma unroll
;                     for (int n = 0; n < 2; ++n) { const f32x4 x = *(const f32x4*)(sp + bj * 128 + 4 * n), gg = *(const f32x4*)(gp + bj * 128 + 4 * n);
;                         *(f32x4*)(dp + bj * 128 + 4 * n) = x + gg * acc[ai][bj][m][n]; }
	v_pk_fma_f32 v[46:47], v[46:47], v[182:183], v[178:179]
	v_pk_fma_f32 v[44:45], v[44:45], v[180:181], v[176:177]
	global_store_dwordx4 v[62:63], v[44:47], off
	s_nop 1
	s_nop 0
	v_pk_fma_f32 v[42:43], v[42:43], v[190:191], v[186:187]
	v_pk_fma_f32 v[40:41], v[40:41], v[188:189], v[184:185]
	global_store_dwordx4 v[62:63], v[40:43], off offset:16
	s_nop 1
	s_nop 0
	v_pk_fma_f32 v[38:39], v[38:39], v[198:199], v[194:195]
	v_pk_fma_f32 v[36:37], v[36:37], v[196:197], v[192:193]
	global_store_dwordx4 v[62:63], v[36:39], off offset:512
	s_nop 1
	v_add_u32_e32 v36, 0xa0, v152
	v_cmp_gt_i32_e32 vcc, s34, v36
	v_cmp_lt_i32_e64 s[4:5], s48, v36
	s_nop 0
	v_pk_fma_f32 v[34:35], v[34:35], v[206:207], v[202:203]
	v_pk_fma_f32 v[32:33], v[32:33], v[204:205], v[200:201]
	global_store_dwordx4 v[62:63], v[32:35], off offset:528
	s_and_saveexec_b64 s[20:21], s[4:5]
	s_xor_b64 s[4:5], exec, s[20:21]
	v_lshlrev_b64 v[32:33], 13, v[140:141]
	v_mov_b32_e32 v37, v141
	v_lshl_add_u64 v[34:35], s[46:47], 0, v[32:33]
	v_lshlrev_b64 v[32:33], 13, v[36:37]
	s_andn2_saveexec_b64 s[4:5], s[4:5]
	v_ashrrev_i32_e32 v37, 31, v36
	v_lshlrev_b64 v[32:33], 13, v[36:37]
	v_lshl_add_u64 v[34:35], s[44:45], 0, v[32:33]
	s_or_b64 exec, exec, s[4:5]
	v_lshrrev_b32_e32 v36, 6, v140
	v_add_u32_e32 v36, 1, v36
	v_cndmask_b32_e64 v36, v36, 0, vcc
	v_lshl_add_u64 v[42:43], v[34:35], 0, v[150:151]
	v_mov_b64_e32 v[34:35], s[6:7]
	v_mad_u64_u32 v[34:35], s[4:5], v36, s43, v[34:35]
	v_lshl_add_u64 v[44:45], v[34:35], 0, v[150:151]
	global_load_dwordx4 v[176:179], v[42:43], off
	global_load_dwordx4 v[180:183], v[44:45], off
	global_load_dwordx4 v[184:187], v[42:43], off offset:16
	global_load_dwordx4 v[188:191], v[44:45], off offset:16
	global_load_dwordx4 v[192:195], v[42:43], off offset:512
	global_load_dwordx4 v[196:199], v[44:45], off offset:512
	global_load_dwordx4 v[200:203], v[42:43], off offset:528
	global_load_dwordx4 v[204:207], v[44:45], off offset:528
	v_lshl_add_u64 v[32:33], s[60:61], 0, v[32:33]
	v_lshl_add_u64 v[46:47], v[32:33], 0, v[150:151]
	s_waitcnt vmcnt(0)
	v_pk_fma_f32 v[30:31], v[30:31], v[182:183], v[178:179]
	v_pk_fma_f32 v[28:29], v[28:29], v[180:181], v[176:177]
	global_store_dwordx4 v[46:47], v[28:31], off
	s_nop 1
	s_nop 0
	v_pk_fma_f32 v[26:27], v[26:27], v[190:191], v[186:187]
	v_pk_fma_f32 v[24:25], v[24:25], v[188:189], v[184:185]
	global_store_dwordx4 v[46:47], v[24:27], off offset:16
	s_nop 1
	s_nop 0
	v_pk_fma_f32 v[22:23], v[22:23], v[198:199], v[194:195]
	v_pk_fma_f32 v[20:21], v[20:21], v[196:197], v[192:193]
	global_store_dwordx4 v[46:47], v[20:23], off offset:512
	s_nop 1
	v_add_u32_e32 v20, 0xb0, v152
	v_cmp_lt_i32_e32 vcc, s48, v20
	s_nop 0
	v_pk_fma_f32 v[18:19], v[18:19], v[206:207], v[202:203]
	v_pk_fma_f32 v[16:17], v[16:17], v[204:205], v[200:201]
	global_store_dwordx4 v[46:47], v[16:19], off offset:528
	s_and_saveexec_b64 s[4:5], vcc
	s_xor_b64 s[4:5], exec, s[4:5]
	v_add_u32_e32 v140, 0xffffc0b0, v152
	v_lshrrev_b32_e32 v16, 6, v140
	v_add_u32_e32 v22, 1, v16
	v_lshlrev_b64 v[16:17], 13, v[140:141]
	v_mov_b32_e32 v21, v141
	v_lshl_add_u64 v[18:19], s[46:47], 0, v[16:17]
	v_lshlrev_b64 v[16:17], 13, v[20:21]
	v_mad_u64_u32 v[22:23], s[20:21], v22, s43, 0
	s_andn2_saveexec_b64 s[4:5], s[4:5]
	v_ashrrev_i32_e32 v21, 31, v20
	v_lshlrev_b64 v[16:17], 13, v[20:21]
	v_lshl_add_u64 v[18:19], s[44:45], 0, v[16:17]
	v_mov_b64_e32 v[22:23], 0
	s_or_b64 exec, exec, s[4:5]
	v_lshl_add_u64 v[26:27], v[18:19], 0, v[150:151]
	v_lshl_add_u64 v[18:19], s[6:7], 0, v[22:23]
	v_lshl_add_u64 v[28:29], v[18:19], 0, v[150:151]
	global_load_dwordx4 v[176:179], v[26:27], off
	global_load_dwordx4 v[180:183], v[28:29], off
	global_load_dwordx4 v[184:187], v[26:27], off offset:16
	global_load_dwordx4 v[188:191], v[28:29], off offset:16
	global_load_dwordx4 v[192:195], v[26:27], off offset:512
	global_load_dwordx4 v[196:199], v[28:29], off offset:512
	global_load_dwordx4 v[200:203], v[26:27], off offset:528
	global_load_dwordx4 v[204:207], v[28:29], off offset:528
	v_lshl_add_u64 v[16:17], s[60:61], 0, v[16:17]
	v_lshl_add_u64 v[30:31], v[16:17], 0, v[150:151]
	s_and_b64 vcc, exec, s[0:1]
	s_mov_b64 s[0:1], -1
	s_waitcnt vmcnt(0)
	v_pk_fma_f32 v[14:15], v[14:15], v[182:183], v[178:179]
	v_pk_fma_f32 v[12:13], v[12:13], v[180:181], v[176:177]
	global_store_dwordx4 v[30:31], v[12:15], off
	s_nop 1
	s_nop 0
	v_pk_fma_f32 v[10:11], v[10:11], v[190:191], v[186:187]
	v_pk_fma_f32 v[8:9], v[8:9], v[188:189], v[184:185]
	global_store_dwordx4 v[30:31], v[8:11], off offset:16
	s_nop 1
	s_nop 0
	v_pk_fma_f32 v[6:7], v[6:7], v[198:199], v[194:195]
	v_pk_fma_f32 v[4:5], v[4:5], v[196:197], v[192:193]
	global_store_dwordx4 v[30:31], v[4:7], off offset:512
	s_nop 1
	s_nop 0
	v_pk_fma_f32 v[2:3], v[2:3], v[206:207], v[202:203]
	v_pk_fma_f32 v[0:1], v[0:1], v[204:205], v[200:201]
	global_store_dwordx4 v[30:31], v[0:3], off offset:528
	s_cbranch_vccnz .LBB0_1996
	s_andn2_b64 vcc, exec, s[2:3]
	s_cbranch_vccnz .LBB0_1995
	s_barrier
	s_branch .LBB0_1995

;     __device__ __forceinline__ void operator()(const f32x4 (&acc)[2][2][4][2], const pg8::Unit& u, int wr, int wc, int fr, int fq) const {
;         const int col0 = u.pn * 256 + wc * 32 + 8 * fq;
; #pragma unroll
;         for (int ai = 0; ai < 2; ++ai)
; #pragma unroll
;             for (int m = 0; m < 4; ++m) {
;                 const int row = u.pm * 256 + ai * 128 + wr * 64 + m * 16 + fr;
;                 const int b = row < TP ? 0 : 1 + ((row - TP) >> 6);
;                 const float* sp = (row < TP ? srcP + (size_t)row * DM : srcS + (size_t)(row - TP) * DM) + col0;
;                 const float* gp = gate + (size_t)b * MODW + col0; float* dp = dst + (size_t)row * DM + col0;
; #pragma unroll
;                 for (int bj = 0; bj < 2; ++bj)
; #pragma unroll
;                     for (int n = 0; n < 2; ++n) { const f32x4 x = *(const f32x4*)(sp + bj * 128 + 4 * n), gg = *(const f32x4*)(gp + bj * 128 + 4 * n);
;                         *(f32x4*)(dp + bj * 128 + 4 * n) = x + gg * acc[ai][bj][m][n]; }
.LBB0_2367:
	v_lshl_add_u32 v148, s46, 8, v154
	v_cmp_gt_i32_e32 vcc, s33, v148
	v_cmp_lt_i32_e64 s[4:5], s42, v148
	v_add_u32_e32 v128, 0xffffc000, v148
	s_and_saveexec_b64 s[18:19], s[4:5]
	s_xor_b64 s[4:5], exec, s[18:19]
	v_lshlrev_b64 v[146:147], 13, v[128:129]
	v_mov_b32_e32 v149, v129
	v_lshl_add_u64 v[152:153], s[6:7], 0, v[146:147]
	v_lshlrev_b64 v[150:151], 13, v[148:149]
	s_andn2_saveexec_b64 s[4:5], s[4:5]
	v_ashrrev_i32_e32 v149, 31, v148
	v_lshlrev_b64 v[150:151], 13, v[148:149]
	v_lshl_add_u64 v[152:153], s[60:61], 0, v[150:151]
	s_or_b64 exec, exec, s[4:5]
	v_lshl_or_b32 v146, s45, 8, v156
	v_ashrrev_i32_e32 v147, 31, v146
	v_lshrrev_b32_e32 v128, 6, v128
	v_add_u32_e32 v128, 1, v128
	v_lshlrev_b64 v[146:147], 2, v[146:147]
	v_cndmask_b32_e64 v128, v128, 0, vcc
	v_lshl_add_u64 v[168:169], v[152:153], 0, v[146:147]
	v_mov_b64_e32 v[152:153], s[8:9]
	v_mad_u64_u32 v[152:153], s[4:5], v128, s41, v[152:153]
	v_lshl_add_u64 v[170:171], v[152:153], 0, v[146:147]
	global_load_dwordx4 v[176:179], v[168:169], off
	global_load_dwordx4 v[180:183], v[170:171], off
	global_load_dwordx4 v[184:187], v[168:169], off offset:16
	global_load_dwordx4 v[188:191], v[170:171], off offset:16
	global_load_dwordx4 v[192:195], v[168:169], off offset:512
	global_load_dwordx4 v[196:199], v[170:171], off offset:512
	global_load_dwordx4 v[200:203], v[168:169], off offset:528
	global_load_dwordx4 v[204:207], v[170:171], off offset:528
	v_lshl_add_u64 v[150:151], s[60:61], 0, v[150:151]
	v_lshl_add_u64 v[172:173], v[150:151], 0, v[146:147]
	v_add_u32_e32 v128, 0xffffc010, v148
	s_waitcnt vmcnt(0)
	v_pk_fma_f32 v[126:127], v[126:127], v[182:183], v[178:179]
	v_pk_fma_f32 v[124:125], v[124:125], v[180:181], v[176:177]
	global_store_dwordx4 v[172:173], v[124:127], off
	s_nop 1
	s_nop 0
	v_pk_fma_f32 v[122:123], v[122:123], v[190:191], v[186:187]
	v_pk_fma_f32 v[120:121], v[120:121], v[188:189], v[184:185]
	global_store_dwordx4 v[172:173], v[120:123], off offset:16
	s_nop 1
	s_nop 0
	v_pk_fma_f32 v[118:119], v[118:119], v[198:199], v[194:195]
	v_pk_fma_f32 v[116:117], v[116:117], v[196:197], v[192:193]
	global_store_dwordx4 v[172:173], v[116:119], off offset:512
	s_nop 1
	v_or_b32_e32 v116, 16, v148
	v_cmp_gt_i32_e32 vcc, s33, v116
	v_cmp_lt_i32_e64 s[4:5], s42, v116
	s_nop 0
	v_pk_fma_f32 v[114:115], v[114:115], v[206:207], v[202:203]
	v_pk_fma_f32 v[112:113], v[112:113], v[204:205], v[200:201]
	global_store_dwordx4 v[172:173], v[112:115], off offset:528
	s_and_saveexec_b64 s[18:19], s[4:5]
	s_xor_b64 s[4:5], exec, s[18:19]
	v_lshlrev_b64 v[112:113], 13, v[128:129]
	v_mov_b32_e32 v117, v129
	v_lshl_add_u64 v[114:115], s[6:7], 0, v[112:113]
	v_lshlrev_b64 v[112:113], 13, v[116:117]
	s_andn2_saveexec_b64 s[4:5], s[4:5]
	v_ashrrev_i32_e32 v117, 31, v116
	v_lshlrev_b64 v[112:113], 13, v[116:117]
	v_lshl_add_u64 v[114:115], s[60:61], 0, v[112:113]
	s_or_b64 exec, exec, s[4:5]
	v_lshrrev_b32_e32 v116, 6, v128
	v_add_u32_e32 v116, 1, v116
	v_cndmask_b32_e64 v116, v116, 0, vcc
	v_lshl_add_u64 v[122:123], v[114:115], 0, v[146:147]
	v_mov_b64_e32 v[114:115], s[8:9]
	v_mad_u64_u32 v[114:115], s[4:5], v116, s41, v[114:115]
	v_lshl_add_u64 v[124:125], v[114:115], 0, v[146:147]
	global_load_dwordx4 v[176:179], v[122:123], off
	global_load_dwordx4 v[180:183], v[124:125], off
	global_load_dwordx4 v[184:187], v[122:123], off offset:16
	global_load_dwordx4 v[188:191], v[124:125], off offset:16
	global_load_dwordx4 v[192:195], v[122:123], off offset:512
	global_load_dwordx4 v[196:199], v[124:125], off offset:512
	global_load_dwordx4 v[200:203], v[122:123], off offset:528
	global_load_dwordx4 v[204:207], v[124:125], off offset:528
	v_lshl_add_u64 v[112:113], s[60:61], 0, v[112:113]
	v_lshl_add_u64 v[126:127], v[112:113], 0, v[146:147]
	v_add_u32_e32 v128, 0xffffc020, v148
	s_waitcnt vmcnt(0)
	v_pk_fma_f32 v[110:111], v[110:111], v[182:183], v[178:179]
	v_pk_fma_f32 v[108:109], v[108:109], v[180:181], v[176:177]
	global_store_dwordx4 v[126:127], v[108:111], off
	s_nop 1
	s_nop 0
	v_pk_fma_f32 v[106:107], v[106:107], v[190:191], v[186:187]
	v_pk_fma_f32 v[104:105], v[104:105], v[188:189], v[184:185]
	global_store_dwordx4 v[126:127], v[104:107], off offset:16
	s_nop 1
	s_nop 0
	v_pk_fma_f32 v[102:103], v[102:103], v[198:199], v[194:195]
	v_pk_fma_f32 v[100:101], v[100:101], v[196:197], v[192:193]
	global_store_dwordx4 v[126:127], v[100:103], off offset:512
	s_nop 1
	v_or_b32_e32 v100, 32, v148
	v_cmp_gt_i32_e32 vcc, s33, v100
	v_cmp_lt_i32_e64 s[4:5], s42, v100
	s_nop 0
	v_pk_fma_f32 v[98:99], v[98:99], v[206:207], v[202:203]
	v_pk_fma_f32 v[96:97], v[96:97], v[204:205], v[200:201]
	global_store_dwordx4 v[126:127], v[96:99], off offset:528
	s_and_saveexec_b64 s[18:19], s[4:5]
	s_xor_b64 s[4:5], exec, s[18:19]
	v_lshlrev_b64 v[96:97], 13, v[128:129]
	v_mov_b32_e32 v101, v129
	v_lshl_add_u64 v[98:99], s[6:7], 0, v[96:97]
	v_lshlrev_b64 v[96:97], 13, v[100:101]
	s_andn2_saveexec_b64 s[4:5], s[4:5]
	v_ashrrev_i32_e32 v101, 31, v100
	v_lshlrev_b64 v[96:97], 13, v[100:101]
	v_lshl_add_u64 v[98:99], s[60:61], 0, v[96:97]
	s_or_b64 exec, exec, s[4:5]
	v_lshrrev_b32_e32 v100, 6, v128
	v_add_u32_e32 v100, 1, v100
	v_cndmask_b32_e64 v100, v100, 0, vcc
	v_lshl_add_u64 v[106:107], v[98:99], 0, v[146:147]
	v_mov_b64_e32 v[98:99], s[8:9]
	v_mad_u64_u32 v[98:99], s[4:5], v100, s41, v[98:99]
	v_lshl_add_u64 v[108:109], v[98:99], 0, v[146:147]
	global_load_dwordx4 v[176:179], v[106:107], off
	global_load_dwordx4 v[180:183], v[108:109], off
	global_load_dwordx4 v[184:187], v[106:107], off offset:16
	global_load_dwordx4 v[188:191], v[108:109], off offset:16
	global_load_dwordx4 v[192:195], v[106:107], off offset:512
	global_load_dwordx4 v[196:199], v[108:109], off offset:512
	global_load_dwordx4 v[200:203], v[106:107], off offset:528
	global_load_dwordx4 v[204:207], v[108:109], off offset:528
	v_lshl_add_u64 v[96:97], s[60:61], 0, v[96:97]
	v_lshl_add_u64 v[110:111], v[96:97], 0, v[146:147]
	v_add_u32_e32 v128, 0xffffc030, v148
	s_waitcnt vmcnt(0)
;     __device__ __forceinline__ void operator()(const f32x4 (&acc)[2][2][4][2], const pg8::Unit& u, int wr, int wc, int fr, int fq) const {
;     ...
;             for (int m = 0; m < 4; ++m) {
;                 const int row = u.pm * 256 + ai * 128 + wr * 64 + m * 16 + fr;
;                 const int b = row < TP ? 0 : 1 + ((row - TP) >> 6);
;                 const float* sp = (row < TP ? srcP + (size_t)row * DM : srcS + (size_t)(row - TP) * DM) + col0;
;                 const float* gp = gate + (size_t)b * MODW + col0; float* dp = dst + (size_t)row * DM + col0;
; #pragma unroll
;                 for (int bj = 0; bj < 2; ++bj)
; #pragma unroll
;                     for (int n = 0; n < 2; ++n) { const f32x4 x = *(const f32x4*)(sp + bj * 128 + 4 * n), gg = *(const f32x4*)(gp + bj * 128 + 4 * n);
;                         *(f32x4*)(dp + bj * 128 + 4 * n) = x + gg * acc[ai][bj][m][n]; }
	v_pk_fma_f32 v[94:95], v[94:95], v[182:183], v[178:179]
	v_pk_fma_f32 v[92:93], v[92:93], v[180:181], v[176:177]
	global_store_dwordx4 v[110:111], v[92:95], off
	s_nop 1
	s_nop 0
	v_pk_fma_f32 v[90:91], v[90:91], v[190:191], v[186:187]
	v_pk_fma_f32 v[88:89], v[88:89], v[188:189], v[184:185]
	global_store_dwordx4 v[110:111], v[88:91], off offset:16
	s_nop 1
	s_nop 0
	v_pk_fma_f32 v[86:87], v[86:87], v[198:199], v[194:195]
	v_pk_fma_f32 v[84:85], v[84:85], v[196:197], v[192:193]
	global_store_dwordx4 v[110:111], v[84:87], off offset:512
	s_nop 1
	v_or_b32_e32 v84, 48, v148
	v_cmp_gt_i32_e32 vcc, s33, v84
	v_cmp_lt_i32_e64 s[4:5], s42, v84
	s_nop 0
	v_pk_fma_f32 v[82:83], v[82:83], v[206:207], v[202:203]
	v_pk_fma_f32 v[80:81], v[80:81], v[204:205], v[200:201]
	global_store_dwordx4 v[110:111], v[80:83], off offset:528
	s_and_saveexec_b64 s[18:19], s[4:5]
	s_xor_b64 s[4:5], exec, s[18:19]
	v_lshlrev_b64 v[80:81], 13, v[128:129]
	v_mov_b32_e32 v85, v129
	v_lshl_add_u64 v[82:83], s[6:7], 0, v[80:81]
	v_lshlrev_b64 v[80:81], 13, v[84:85]
	s_andn2_saveexec_b64 s[4:5], s[4:5]
	v_ashrrev_i32_e32 v85, 31, v84
	v_lshlrev_b64 v[80:81], 13, v[84:85]
	v_lshl_add_u64 v[82:83], s[60:61], 0, v[80:81]
	s_or_b64 exec, exec, s[4:5]
	v_lshrrev_b32_e32 v84, 6, v128
	v_add_u32_e32 v84, 1, v84
	v_cndmask_b32_e64 v84, v84, 0, vcc
	v_lshl_add_u64 v[90:91], v[82:83], 0, v[146:147]
	v_mov_b64_e32 v[82:83], s[8:9]
	v_mad_u64_u32 v[82:83], s[4:5], v84, s41, v[82:83]
	v_lshl_add_u64 v[92:93], v[82:83], 0, v[146:147]
	global_load_dwordx4 v[176:179], v[90:91], off
	global_load_dwordx4 v[180:183], v[92:93], off
	global_load_dwordx4 v[184:187], v[90:91], off offset:16
	global_load_dwordx4 v[188:191], v[92:93], off offset:16
	global_load_dwordx4 v[192:195], v[90:91], off offset:512
	global_load_dwordx4 v[196:199], v[92:93], off offset:512
	global_load_dwordx4 v[200:203], v[90:91], off offset:528
	global_load_dwordx4 v[204:207], v[92:93], off offset:528
	v_lshl_add_u64 v[80:81], s[60:61], 0, v[80:81]
	v_lshl_add_u64 v[94:95], v[80:81], 0, v[146:147]
	v_add_u32_e32 v128, 0xffffc080, v148
	s_waitcnt vmcnt(0)
	v_pk_fma_f32 v[78:79], v[78:79], v[182:183], v[178:179]
	v_pk_fma_f32 v[76:77], v[76:77], v[180:181], v[176:177]
	global_store_dwordx4 v[94:95], v[76:79], off
	s_nop 1
	s_nop 0
	v_pk_fma_f32 v[74:75], v[74:75], v[190:191], v[186:187]
	v_pk_fma_f32 v[72:73], v[72:73], v[188:189], v[184:185]
	global_store_dwordx4 v[94:95], v[72:75], off offset:16
	s_nop 1
	s_nop 0
	v_pk_fma_f32 v[70:71], v[70:71], v[198:199], v[194:195]
	v_pk_fma_f32 v[68:69], v[68:69], v[196:197], v[192:193]
	global_store_dwordx4 v[94:95], v[68:71], off offset:512
	s_nop 1
	v_add_u32_e32 v68, 0x80, v148
	v_cmp_gt_i32_e32 vcc, s33, v68
	v_cmp_lt_i32_e64 s[4:5], s42, v68
	s_nop 0
	v_pk_fma_f32 v[66:67], v[66:67], v[206:207], v[202:203]
	v_pk_fma_f32 v[64:65], v[64:65], v[204:205], v[200:201]
	global_store_dwordx4 v[94:95], v[64:67], off offset:528
	s_and_saveexec_b64 s[18:19], s[4:5]
	s_xor_b64 s[4:5], exec, s[18:19]
	v_lshlrev_b64 v[64:65], 13, v[128:129]
	v_mov_b32_e32 v69, v129
	v_lshl_add_u64 v[66:67], s[6:7], 0, v[64:65]
	v_lshlrev_b64 v[64:65], 13, v[68:69]
	s_andn2_saveexec_b64 s[4:5], s[4:5]
	v_ashrrev_i32_e32 v69, 31, v68
	v_lshlrev_b64 v[64:65], 13, v[68:69]
	v_lshl_add_u64 v[66:67], s[60:61], 0, v[64:65]
	s_or_b64 exec, exec, s[4:5]
	v_lshrrev_b32_e32 v68, 6, v128
	v_add_u32_e32 v68, 1, v68
	v_cndmask_b32_e64 v68, v68, 0, vcc
	v_lshl_add_u64 v[74:75], v[66:67], 0, v[146:147]
	v_mov_b64_e32 v[66:67], s[8:9]
	v_mad_u64_u32 v[66:67], s[4:5], v68, s41, v[66:67]
	v_lshl_add_u64 v[76:77], v[66:67], 0, v[146:147]
	global_load_dwordx4 v[176:179], v[74:75], off
	global_load_dwordx4 v[180:183], v[76:77], off
	global_load_dwordx4 v[184:187], v[74:75], off offset:16
	global_load_dwordx4 v[188:191], v[76:77], off offset:16
	global_load_dwordx4 v[192:195], v[74:75], off offset:512
	global_load_dwordx4 v[196:199], v[76:77], off offset:512
	global_load_dwordx4 v[200:203], v[74:75], off offset:528
	global_load_dwordx4 v[204:207], v[76:77], off offset:528
	v_lshl_add_u64 v[64:65], s[60:61], 0, v[64:65]
	v_lshl_add_u64 v[78:79], v[64:65], 0, v[146:147]
	v_add_u32_e32 v128, 0xffffc090, v148
	s_waitcnt vmcnt(0)
	v_pk_fma_f32 v[62:63], v[62:63], v[182:183], v[178:179]
	v_pk_fma_f32 v[60:61], v[60:61], v[180:181], v[176:177]
	global_store_dwordx4 v[78:79], v[60:63], off
	s_nop 1
	s_nop 0
	v_pk_fma_f32 v[58:59], v[58:59], v[190:191], v[186:187]
	v_pk_fma_f32 v[56:57], v[56:57], v[188:189], v[184:185]
	global_store_dwordx4 v[78:79], v[56:59], off offset:16
	s_nop 1
	s_nop 0
	v_pk_fma_f32 v[54:55], v[54:55], v[198:199], v[194:195]
	v_pk_fma_f32 v[52:53], v[52:53], v[196:197], v[192:193]
	global_store_dwordx4 v[78:79], v[52:55], off offset:512
	s_nop 1
	v_add_u32_e32 v52, 0x90, v148
	v_cmp_gt_i32_e32 vcc, s33, v52
	v_cmp_lt_i32_e64 s[4:5], s42, v52
	s_nop 0
	v_pk_fma_f32 v[50:51], v[50:51], v[206:207], v[202:203]
	v_pk_fma_f32 v[48:49], v[48:49], v[204:205], v[200:201]
	global_store_dwordx4 v[78:79], v[48:51], off offset:528
	s_and_saveexec_b64 s[18:19], s[4:5]
	s_xor_b64 s[4:5], exec, s[18:19]
	v_lshlrev_b64 v[48:49], 13, v[128:129]
	v_mov_b32_e32 v53, v129
	v_lshl_add_u64 v[50:51], s[6:7], 0, v[48:49]
	v_lshlrev_b64 v[48:49], 13, v[52:53]
	s_andn2_saveexec_b64 s[4:5], s[4:5]
	v_ashrrev_i32_e32 v53, 31, v52
	v_lshlrev_b64 v[48:49], 13, v[52:53]
	v_lshl_add_u64 v[50:51], s[60:61], 0, v[48:49]
	s_or_b64 exec, exec, s[4:5]
	v_lshrrev_b32_e32 v52, 6, v128
	v_add_u32_e32 v52, 1, v52
	v_cndmask_b32_e64 v52, v52, 0, vcc
	v_lshl_add_u64 v[58:59], v[50:51], 0, v[146:147]
	v_mov_b64_e32 v[50:51], s[8:9]
	v_mad_u64_u32 v[50:51], s[4:5], v52, s41, v[50:51]
	v_lshl_add_u64 v[60:61], v[50:51], 0, v[146:147]
	global_load_dwordx4 v[176:179], v[58:59], off
	global_load_dwordx4 v[180:183], v[60:61], off
	global_load_dwordx4 v[184:187], v[58:59], off offset:16
	global_load_dwordx4 v[188:191], v[60:61], off offset:16
	global_load_dwordx4 v[192:195], v[58:59], off offset:512
	global_load_dwordx4 v[196:199], v[60:61], off offset:512
	global_load_dwordx4 v[200:203], v[58:59], off offset:528
	global_load_dwordx4 v[204:207], v[60:61], off offset:528
	v_lshl_add_u64 v[48:49], s[60:61], 0, v[48:49]
	v_lshl_add_u64 v[62:63], v[48:49], 0, v[146:147]
	v_add_u32_e32 v128, 0xffffc0a0, v148
	s_waitcnt vmcnt(0)
;     __device__ __forceinline__ void operator()(const f32x4 (&acc)[2][2][4][2], const pg8::Unit& u, int wr, int wc, int fr, int fq) const {
;     ...
;             for (int m = 0; m < 4; ++m) {
;                 const int row = u.pm * 256 + ai * 128 + wr * 64 + m * 16 + fr;
;                 const int b = row < TP ? 0 : 1 + ((row - TP) >> 6);
;                 const float* sp = (row < TP ? srcP + (size_t)row * DM : srcS + (size_t)(row - TP) * DM) + col0;
;                 const float* gp = gate + (size_t)b * MODW + col0; float* dp = dst + (size_t)row * DM + col0;
; #pragma unroll
;                 for (int bj = 0; bj < 2; ++bj)
; #pragma unroll
;                     for (int n = 0; n < 2; ++n) { const f32x4 x = *(const f32x4*)(sp + bj * 128 + 4 * n), gg = *(const f32x4*)(gp + bj * 128 + 4 * n);
;                         *(f32x4*)(dp + bj * 128 + 4 * n) = x + gg * acc[ai][bj][m][n]; }
	v_pk_fma_f32 v[46:47], v[46:47], v[182:183], v[178:179]
	v_pk_fma_f32 v[44:45], v[44:45], v[180:181], v[176:177]
	global_store_dwordx4 v[62:63], v[44:47], off
	s_nop 1
	s_nop 0
	v_pk_fma_f32 v[42:43], v[42:43], v[190:191], v[186:187]
	v_pk_fma_f32 v[40:41], v[40:41], v[188:189], v[184:185]
	global_store_dwordx4 v[62:63], v[40:43], off offset:16
	s_nop 1
	s_nop 0
	v_pk_fma_f32 v[38:39], v[38:39], v[198:199], v[194:195]
	v_pk_fma_f32 v[36:37], v[36:37], v[196:197], v[192:193]
	global_store_dwordx4 v[62:63], v[36:39], off offset:512
	s_nop 1
	v_add_u32_e32 v36, 0xa0, v148
	v_cmp_gt_i32_e32 vcc, s33, v36
	v_cmp_lt_i32_e64 s[4:5], s42, v36
	s_nop 0
	v_pk_fma_f32 v[34:35], v[34:35], v[206:207], v[202:203]
	v_pk_fma_f32 v[32:33], v[32:33], v[204:205], v[200:201]
	global_store_dwordx4 v[62:63], v[32:35], off offset:528
	s_and_saveexec_b64 s[18:19], s[4:5]
	s_xor_b64 s[4:5], exec, s[18:19]
	v_lshlrev_b64 v[32:33], 13, v[128:129]
	v_mov_b32_e32 v37, v129
	v_lshl_add_u64 v[34:35], s[6:7], 0, v[32:33]
	v_lshlrev_b64 v[32:33], 13, v[36:37]
	s_andn2_saveexec_b64 s[4:5], s[4:5]
	v_ashrrev_i32_e32 v37, 31, v36
	v_lshlrev_b64 v[32:33], 13, v[36:37]
	v_lshl_add_u64 v[34:35], s[60:61], 0, v[32:33]
	s_or_b64 exec, exec, s[4:5]
	v_lshrrev_b32_e32 v36, 6, v128
	v_add_u32_e32 v36, 1, v36
	v_cndmask_b32_e64 v36, v36, 0, vcc
	v_lshl_add_u64 v[42:43], v[34:35], 0, v[146:147]
	v_mov_b64_e32 v[34:35], s[8:9]
	v_mad_u64_u32 v[34:35], s[4:5], v36, s41, v[34:35]
	v_lshl_add_u64 v[44:45], v[34:35], 0, v[146:147]
	global_load_dwordx4 v[176:179], v[42:43], off
	global_load_dwordx4 v[180:183], v[44:45], off
	global_load_dwordx4 v[184:187], v[42:43], off offset:16
	global_load_dwordx4 v[188:191], v[44:45], off offset:16
	global_load_dwordx4 v[192:195], v[42:43], off offset:512
	global_load_dwordx4 v[196:199], v[44:45], off offset:512
	global_load_dwordx4 v[200:203], v[42:43], off offset:528
	global_load_dwordx4 v[204:207], v[44:45], off offset:528
	v_lshl_add_u64 v[32:33], s[60:61], 0, v[32:33]
	v_lshl_add_u64 v[46:47], v[32:33], 0, v[146:147]
	s_waitcnt vmcnt(0)
	v_pk_fma_f32 v[30:31], v[30:31], v[182:183], v[178:179]
	v_pk_fma_f32 v[28:29], v[28:29], v[180:181], v[176:177]
	global_store_dwordx4 v[46:47], v[28:31], off
	s_nop 1
	s_nop 0
	v_pk_fma_f32 v[26:27], v[26:27], v[190:191], v[186:187]
	v_pk_fma_f32 v[24:25], v[24:25], v[188:189], v[184:185]
	global_store_dwordx4 v[46:47], v[24:27], off offset:16
	s_nop 1
	s_nop 0
	v_pk_fma_f32 v[22:23], v[22:23], v[198:199], v[194:195]
	v_pk_fma_f32 v[20:21], v[20:21], v[196:197], v[192:193]
	global_store_dwordx4 v[46:47], v[20:23], off offset:512
	s_nop 1
	v_add_u32_e32 v20, 0xb0, v148
	v_cmp_lt_i32_e32 vcc, s42, v20
	s_nop 0
	v_pk_fma_f32 v[18:19], v[18:19], v[206:207], v[202:203]
	v_pk_fma_f32 v[16:17], v[16:17], v[204:205], v[200:201]
	global_store_dwordx4 v[46:47], v[16:19], off offset:528
	s_and_saveexec_b64 s[4:5], vcc
	s_xor_b64 s[4:5], exec, s[4:5]
	v_add_u32_e32 v128, 0xffffc0b0, v148
	v_lshrrev_b32_e32 v16, 6, v128
	v_add_u32_e32 v22, 1, v16
	v_lshlrev_b64 v[16:17], 13, v[128:129]
	v_mov_b32_e32 v21, v129
	v_lshl_add_u64 v[18:19], s[6:7], 0, v[16:17]
	v_lshlrev_b64 v[16:17], 13, v[20:21]
	v_mad_u64_u32 v[22:23], s[18:19], v22, s41, 0
	s_andn2_saveexec_b64 s[4:5], s[4:5]
	v_ashrrev_i32_e32 v21, 31, v20
	v_lshlrev_b64 v[16:17], 13, v[20:21]
	v_lshl_add_u64 v[18:19], s[60:61], 0, v[16:17]
	v_mov_b64_e32 v[22:23], 0
	s_or_b64 exec, exec, s[4:5]
	v_lshl_add_u64 v[26:27], v[18:19], 0, v[146:147]
	v_lshl_add_u64 v[18:19], s[8:9], 0, v[22:23]
	v_lshl_add_u64 v[28:29], v[18:19], 0, v[146:147]
	global_load_dwordx4 v[176:179], v[26:27], off
	global_load_dwordx4 v[180:183], v[28:29], off
	global_load_dwordx4 v[184:187], v[26:27], off offset:16
	global_load_dwordx4 v[188:191], v[28:29], off offset:16
	global_load_dwordx4 v[192:195], v[26:27], off offset:512
	global_load_dwordx4 v[196:199], v[28:29], off offset:512
	global_load_dwordx4 v[200:203], v[26:27], off offset:528
	global_load_dwordx4 v[204:207], v[28:29], off offset:528
	v_lshl_add_u64 v[16:17], s[60:61], 0, v[16:17]
	v_lshl_add_u64 v[30:31], v[16:17], 0, v[146:147]
	s_and_b64 vcc, exec, s[0:1]
	s_mov_b64 s[0:1], -1
	s_waitcnt vmcnt(0)
	v_pk_fma_f32 v[14:15], v[14:15], v[182:183], v[178:179]
	v_pk_fma_f32 v[12:13], v[12:13], v[180:181], v[176:177]
	global_store_dwordx4 v[30:31], v[12:15], off
	s_nop 1
	s_nop 0
	v_pk_fma_f32 v[10:11], v[10:11], v[190:191], v[186:187]
	v_pk_fma_f32 v[8:9], v[8:9], v[188:189], v[184:185]
	global_store_dwordx4 v[30:31], v[8:11], off offset:16
	s_nop 1
	s_nop 0
	v_pk_fma_f32 v[6:7], v[6:7], v[198:199], v[194:195]
	v_pk_fma_f32 v[4:5], v[4:5], v[196:197], v[192:193]
	global_store_dwordx4 v[30:31], v[4:7], off offset:512
	s_nop 1
	s_nop 0
	v_pk_fma_f32 v[2:3], v[2:3], v[206:207], v[202:203]
	v_pk_fma_f32 v[0:1], v[0:1], v[204:205], v[200:201]
	global_store_dwordx4 v[30:31], v[0:3], off offset:528
	s_cbranch_vccnz .LBB0_2356
	s_andn2_b64 vcc, exec, s[2:3]
	s_cbranch_vccnz .LBB0_2355
	s_barrier
	s_branch .LBB0_2355
